# fgate: 16-byte x loads (k remapped), second 4-row pass streamed in behind the first pass unpack
# baseline (speedup 1.0000x reference)
; __device__ __forceinline__ void fgate_phase(const bfr* x, const float* wf, const float* bfg, float* cl, float* ctot, LAS float* scr, int bx, int G, int tid, int lane, int wave) {
;     for (int chunk = bx; chunk < M / 64; chunk += G) {
; #pragma unroll 1
;         for (int j = 0; j < 8; j += 2) { const int row = chunk * 64 + wave * 8 + j; typedef unsigned u32x2 __attribute__((ext_vector_type(2))); const u32x2* xa = (const u32x2*)(x + (size_t)row * D) + lane; const u32x2* xb2 = xa + D / 4; f32x4 va[4], vb[4]; float r[18]; int zo = 0; asm volatile("" : "+v"(zo));
; #pragma unroll
;             for (int jj = 0; jj < 4; ++jj) { const u32x2 wa = xa[64 * jj], wb = xb2[64 * jj]; va[jj] = (f32x4){bf_lo(wa.x), bf_hi(wa.x), bf_lo(wa.y), bf_hi(wa.y)}; vb[jj] = (f32x4){bf_lo(wb.x), bf_hi(wb.x), bf_lo(wb.y), bf_hi(wb.y)}; }
;             r[16] = 0.f; r[17] = 0.f;
; #pragma unroll
;             for (int jj = 0; jj < 4; ++jj) { r[16] += (va[jj].x * va[jj].x + va[jj].y * va[jj].y) + (va[jj].z * va[jj].z + va[jj].w * va[jj].w); r[17] += (vb[jj].x * vb[jj].x + vb[jj].y * vb[jj].y) + (vb[jj].z * vb[jj].z + vb[jj].w * vb[jj].w); }
; #pragma unroll
;             for (int h = 0; h < NH; ++h) { const f32x4* wr = (const f32x4*)(wf + h * D) + lane + zo; float da = 0.f, db = 0.f;
; #pragma unroll
;                 for (int jj = 0; jj < 4; ++jj) { const f32x4 w = wr[64 * jj]; da += (va[jj].x * w.x + va[jj].y * w.y) + (va[jj].z * w.z + va[jj].w * w.w); db += (vb[jj].x * w.x + vb[jj].y * w.y) + (vb[jj].z * w.z + vb[jj].w * w.w); }
;                 r[h] = da; r[8 + h] = db; }
.LBB0_424:
	s_mov_b32 s38, s33
	s_ashr_i32 s39, s33, 31
	s_lshl_b64 s[38:39], s[38:39], 11
	s_mov_b64 s[98:99], 0x1000
	s_mov_b64 s[100:101], 0x2000
	v_lshl_add_u64 v[38:39], v[28:29], 0, s[38:39]
	v_mov_b32_e32 v160, v158
	v_mov_b32_e32 v161, 0
	v_lshl_add_u64 v[38:39], v[160:161], 3, v[38:39]
	v_lshl_add_u64 v[98:99], v[38:39], 0, s[98:99]
	global_load_dwordx4 v[112:115], v[38:39], off
	global_load_dwordx4 v[108:111], v[38:39], off offset:1024
	global_load_dwordx4 v[104:107], v[38:39], off offset:2048
	global_load_dwordx4 v[100:103], v[38:39], off offset:3072
	global_load_dwordx4 v[84:87], v[98:99], off
	global_load_dwordx4 v[80:83], v[98:99], off offset:1024
	global_load_dwordx4 v[76:79], v[98:99], off offset:2048
	global_load_dwordx4 v[72:75], v[98:99], off offset:3072
	global_load_dword v61, v[32:33], off
	v_lshrrev_b32_e32 v62, 6, v128
	v_lshlrev_b32_e32 v63, 4, v158
	v_readfirstlane_b32 s20, v30
	v_readfirstlane_b32 s21, v31
	v_readfirstlane_b32 s66, v62
	s_lshl_b32 s66, s66, 12
	s_add_u32 s20, s20, s66
	s_addc_u32 s21, s21, 0
	s_add_i32 s66, s66, 0x1000
	s_mov_b32 m0, s66
	s_nop 0
	global_load_lds_dwordx4 v63, s[20:21]
	s_add_u32 s20, s20, 0x400
	s_addc_u32 s21, s21, 0
	s_add_i32 s66, s66, 0x400
	s_mov_b32 m0, s66
	s_nop 0
	global_load_lds_dwordx4 v63, s[20:21]
	s_add_u32 s20, s20, 0x400
	s_addc_u32 s21, s21, 0
	s_add_i32 s66, s66, 0x400
	s_mov_b32 m0, s66
	s_nop 0
	global_load_lds_dwordx4 v63, s[20:21]
	s_add_u32 s20, s20, 0x400
	s_addc_u32 s21, s21, 0
	s_add_i32 s66, s66, 0x400
	s_mov_b32 m0, s66
	s_nop 0
	global_load_lds_dwordx4 v63, s[20:21]
	s_waitcnt vmcnt(0)
	s_barrier
	v_lshlrev_b32_e32 v63, 5, v158
	ds_read_b128 v[248:251], v63 offset:4096
	ds_read_b128 v[244:247], v63 offset:4112
	ds_read_b128 v[240:243], v63 offset:6144
	ds_read_b128 v[236:239], v63 offset:6160
	ds_read_b128 v[232:235], v63 offset:8192
	ds_read_b128 v[228:231], v63 offset:8208
	ds_read_b128 v[224:227], v63 offset:10240
	ds_read_b128 v[220:223], v63 offset:10256
	ds_read_b128 v[216:219], v63 offset:12288
	ds_read_b128 v[212:215], v63 offset:12304
	ds_read_b128 v[208:211], v63 offset:14336
	ds_read_b128 v[204:207], v63 offset:14352
	ds_read_b128 v[200:203], v63 offset:16384
	ds_read_b128 v[196:199], v63 offset:16400
	ds_read_b128 v[192:195], v63 offset:18432
	ds_read_b128 v[188:191], v63 offset:18448
	ds_read_b128 v[182:185], v63 offset:20480
	ds_read_b128 v[178:181], v63 offset:20496
	ds_read_b128 v[174:177], v63 offset:22528
	ds_read_b128 v[170:173], v63 offset:22544
	ds_read_b128 v[166:169], v63 offset:24576
	ds_read_b128 v[162:165], v63 offset:24592
	ds_read_b128 v[154:157], v63 offset:26624
	ds_read_b128 v[150:153], v63 offset:26640
	ds_read_b128 v[146:149], v63 offset:28672
	ds_read_b128 v[142:145], v63 offset:28688
	ds_read_b128 v[138:141], v63 offset:30720
	ds_read_b128 v[134:137], v63 offset:30736
	ds_read_b128 v[130:133], v63 offset:32768
	ds_read_b128 v[124:127], v63 offset:32784
	ds_read_b128 v[120:123], v63 offset:34816
	ds_read_b128 v[116:119], v63 offset:34832
	v_and_b32_e32 v64, 7, v158
	v_cmp_eq_u32_e64 s[6:7], 1, v64
	v_cmp_eq_u32_e64 s[8:9], 2, v64
	v_cmp_eq_u32_e64 s[10:11], 3, v64
	v_cmp_eq_u32_e64 s[12:13], 4, v64
	v_cmp_eq_u32_e64 s[14:15], 5, v64
	v_cmp_eq_u32_e64 s[16:17], 6, v64
	v_cmp_eq_u32_e64 s[18:19], 7, v64
	v_lshrrev_b32_e32 v62, 4, v158
	v_lshlrev_b32_e32 v62, 5, v62
	v_sub_u32_e32 v65, v95, v62
	s_mov_b32 s40, 0xffff0000
	s_waitcnt vmcnt(0) lgkmcnt(0)
	v_lshlrev_b32_e32 v97, 16, v112
	v_and_b32_e32 v159, s40, v112
	v_lshlrev_b32_e32 v187, 16, v113
	v_and_b32_e32 v0, s40, v113
	v_lshlrev_b32_e32 v1, 16, v114
	v_and_b32_e32 v2, s40, v114
	v_lshlrev_b32_e32 v3, 16, v115
	v_and_b32_e32 v4, s40, v115
	v_lshlrev_b32_e32 v5, 16, v108
	v_and_b32_e32 v6, s40, v108
	v_lshlrev_b32_e32 v7, 16, v109
	v_and_b32_e32 v8, s40, v109
	v_lshlrev_b32_e32 v9, 16, v110
	v_and_b32_e32 v10, s40, v110
	v_lshlrev_b32_e32 v11, 16, v111
	v_and_b32_e32 v12, s40, v111
	v_lshl_add_u64 v[38:39], v[38:39], 0, s[100:101]
	v_lshl_add_u64 v[98:99], v[98:99], 0, s[100:101]
	global_load_dwordx4 v[112:115], v[38:39], off
	global_load_dwordx4 v[108:111], v[38:39], off offset:1024
	v_mul_f32_e32 v57, v97, v97
	v_mul_f32_e32 v13, v97, v248
	v_mul_f32_e32 v14, v97, v232
	v_mul_f32_e32 v15, v97, v216
	v_mul_f32_e32 v16, v97, v200
	v_mul_f32_e32 v17, v97, v182
	v_mul_f32_e32 v18, v97, v166
	v_mul_f32_e32 v19, v97, v146
	v_mul_f32_e32 v20, v97, v130
	v_fmac_f32_e32 v57, v159, v159
	v_fmac_f32_e32 v13, v159, v249
	v_fmac_f32_e32 v14, v159, v233
	v_fmac_f32_e32 v15, v159, v217
	v_fmac_f32_e32 v16, v159, v201
	v_fmac_f32_e32 v17, v159, v183
	v_fmac_f32_e32 v18, v159, v167
	v_fmac_f32_e32 v19, v159, v147
	v_fmac_f32_e32 v20, v159, v131
	v_fmac_f32_e32 v57, v187, v187
	v_fmac_f32_e32 v13, v187, v250
	v_fmac_f32_e32 v14, v187, v234
	v_fmac_f32_e32 v15, v187, v218
	v_fmac_f32_e32 v16, v187, v202
	v_fmac_f32_e32 v17, v187, v184
	v_fmac_f32_e32 v18, v187, v168
	v_fmac_f32_e32 v19, v187, v148
	v_fmac_f32_e32 v20, v187, v132
	v_fmac_f32_e32 v57, v0, v0
	v_fmac_f32_e32 v13, v0, v251
	v_fmac_f32_e32 v14, v0, v235
	v_fmac_f32_e32 v15, v0, v219
	v_fmac_f32_e32 v16, v0, v203
	v_fmac_f32_e32 v17, v0, v185
	v_fmac_f32_e32 v18, v0, v169
	v_fmac_f32_e32 v19, v0, v149
	v_fmac_f32_e32 v20, v0, v133
	v_fmac_f32_e32 v57, v1, v1
	v_fmac_f32_e32 v13, v1, v244
	v_fmac_f32_e32 v14, v1, v228
	v_fmac_f32_e32 v15, v1, v212
	v_fmac_f32_e32 v16, v1, v196
	v_fmac_f32_e32 v17, v1, v178
	v_fmac_f32_e32 v18, v1, v162
	v_fmac_f32_e32 v19, v1, v142
	v_fmac_f32_e32 v20, v1, v124
	v_fmac_f32_e32 v57, v2, v2
	v_fmac_f32_e32 v13, v2, v245
	v_fmac_f32_e32 v14, v2, v229
	v_fmac_f32_e32 v15, v2, v213
; __device__ __forceinline__ void fgate_phase(const bfr* x, const float* wf, const float* bfg, float* cl, float* ctot, LAS float* scr, int bx, int G, int tid, int lane, int wave) {
;     ...
;         for (int j = 0; j < 8; j += 2) { const int row = chunk * 64 + wave * 8 + j; typedef unsigned u32x2 __attribute__((ext_vector_type(2))); const u32x2* xa = (const u32x2*)(x + (size_t)row * D) + lane; const u32x2* xb2 = xa + D / 4; f32x4 va[4], vb[4]; float r[18]; int zo = 0; asm volatile("" : "+v"(zo));
; #pragma unroll
;             for (int jj = 0; jj < 4; ++jj) { const u32x2 wa = xa[64 * jj], wb = xb2[64 * jj]; va[jj] = (f32x4){bf_lo(wa.x), bf_hi(wa.x), bf_lo(wa.y), bf_hi(wa.y)}; vb[jj] = (f32x4){bf_lo(wb.x), bf_hi(wb.x), bf_lo(wb.y), bf_hi(wb.y)}; }
;             r[16] = 0.f; r[17] = 0.f;
; #pragma unroll
;             for (int jj = 0; jj < 4; ++jj) { r[16] += (va[jj].x * va[jj].x + va[jj].y * va[jj].y) + (va[jj].z * va[jj].z + va[jj].w * va[jj].w); r[17] += (vb[jj].x * vb[jj].x + vb[jj].y * vb[jj].y) + (vb[jj].z * vb[jj].z + vb[jj].w * vb[jj].w); }
; #pragma unroll
;             for (int h = 0; h < NH; ++h) { const f32x4* wr = (const f32x4*)(wf + h * D) + lane + zo; float da = 0.f, db = 0.f;
; #pragma unroll
;                 for (int jj = 0; jj < 4; ++jj) { const f32x4 w = wr[64 * jj]; da += (va[jj].x * w.x + va[jj].y * w.y) + (va[jj].z * w.z + va[jj].w * w.w); db += (vb[jj].x * w.x + vb[jj].y * w.y) + (vb[jj].z * w.z + vb[jj].w * w.w); }
;                 r[h] = da; r[8 + h] = db; }
	v_fmac_f32_e32 v16, v2, v197
	v_fmac_f32_e32 v17, v2, v179
	v_fmac_f32_e32 v18, v2, v163
	v_fmac_f32_e32 v19, v2, v143
	v_fmac_f32_e32 v20, v2, v125
	v_fmac_f32_e32 v57, v3, v3
	v_fmac_f32_e32 v13, v3, v246
	v_fmac_f32_e32 v14, v3, v230
	v_fmac_f32_e32 v15, v3, v214
	v_fmac_f32_e32 v16, v3, v198
	v_fmac_f32_e32 v17, v3, v180
	v_fmac_f32_e32 v18, v3, v164
	v_fmac_f32_e32 v19, v3, v144
	v_fmac_f32_e32 v20, v3, v126
	v_fmac_f32_e32 v57, v4, v4
	v_fmac_f32_e32 v13, v4, v247
	v_fmac_f32_e32 v14, v4, v231
	v_fmac_f32_e32 v15, v4, v215
	v_fmac_f32_e32 v16, v4, v199
	v_fmac_f32_e32 v17, v4, v181
	v_fmac_f32_e32 v18, v4, v165
	v_fmac_f32_e32 v19, v4, v145
	v_fmac_f32_e32 v20, v4, v127
	v_fmac_f32_e32 v57, v5, v5
	v_fmac_f32_e32 v13, v5, v240
	v_fmac_f32_e32 v14, v5, v224
	v_fmac_f32_e32 v15, v5, v208
	v_fmac_f32_e32 v16, v5, v192
	v_fmac_f32_e32 v17, v5, v174
	v_fmac_f32_e32 v18, v5, v154
	v_fmac_f32_e32 v19, v5, v138
	v_fmac_f32_e32 v20, v5, v120
	v_fmac_f32_e32 v57, v6, v6
	v_fmac_f32_e32 v13, v6, v241
	v_fmac_f32_e32 v14, v6, v225
	v_fmac_f32_e32 v15, v6, v209
	v_fmac_f32_e32 v16, v6, v193
	v_fmac_f32_e32 v17, v6, v175
	v_fmac_f32_e32 v18, v6, v155
	v_fmac_f32_e32 v19, v6, v139
	v_fmac_f32_e32 v20, v6, v121
	v_fmac_f32_e32 v57, v7, v7
	v_fmac_f32_e32 v13, v7, v242
	v_fmac_f32_e32 v14, v7, v226
	v_fmac_f32_e32 v15, v7, v210
	v_fmac_f32_e32 v16, v7, v194
	v_fmac_f32_e32 v17, v7, v176
	v_fmac_f32_e32 v18, v7, v156
	v_fmac_f32_e32 v19, v7, v140
	v_fmac_f32_e32 v20, v7, v122
	v_fmac_f32_e32 v57, v8, v8
	v_fmac_f32_e32 v13, v8, v243
	v_fmac_f32_e32 v14, v8, v227
	v_fmac_f32_e32 v15, v8, v211
	v_fmac_f32_e32 v16, v8, v195
	v_fmac_f32_e32 v17, v8, v177
	v_fmac_f32_e32 v18, v8, v157
	v_fmac_f32_e32 v19, v8, v141
	v_fmac_f32_e32 v20, v8, v123
	v_fmac_f32_e32 v57, v9, v9
	v_fmac_f32_e32 v13, v9, v236
	v_fmac_f32_e32 v14, v9, v220
	v_fmac_f32_e32 v15, v9, v204
	v_fmac_f32_e32 v16, v9, v188
	v_fmac_f32_e32 v17, v9, v170
	v_fmac_f32_e32 v18, v9, v150
	v_fmac_f32_e32 v19, v9, v134
	v_fmac_f32_e32 v20, v9, v116
	v_fmac_f32_e32 v57, v10, v10
	v_fmac_f32_e32 v13, v10, v237
	v_fmac_f32_e32 v14, v10, v221
	v_fmac_f32_e32 v15, v10, v205
	v_fmac_f32_e32 v16, v10, v189
	v_fmac_f32_e32 v17, v10, v171
	v_fmac_f32_e32 v18, v10, v151
	v_fmac_f32_e32 v19, v10, v135
	v_fmac_f32_e32 v20, v10, v117
	v_fmac_f32_e32 v57, v11, v11
	v_fmac_f32_e32 v13, v11, v238
	v_fmac_f32_e32 v14, v11, v222
	v_fmac_f32_e32 v15, v11, v206
	v_fmac_f32_e32 v16, v11, v190
	v_fmac_f32_e32 v17, v11, v172
	v_fmac_f32_e32 v18, v11, v152
	v_fmac_f32_e32 v19, v11, v136
	v_fmac_f32_e32 v20, v11, v118
	v_fmac_f32_e32 v57, v12, v12
	v_fmac_f32_e32 v13, v12, v239
	v_fmac_f32_e32 v14, v12, v223
	v_fmac_f32_e32 v15, v12, v207
	v_fmac_f32_e32 v16, v12, v191
	v_fmac_f32_e32 v17, v12, v173
	v_fmac_f32_e32 v18, v12, v153
	v_fmac_f32_e32 v19, v12, v137
	v_fmac_f32_e32 v20, v12, v119
	v_lshlrev_b32_e32 v97, 16, v104
	v_and_b32_e32 v159, s40, v104
	v_lshlrev_b32_e32 v187, 16, v105
	v_and_b32_e32 v0, s40, v105
	v_lshlrev_b32_e32 v1, 16, v106
	v_and_b32_e32 v2, s40, v106
	v_lshlrev_b32_e32 v3, 16, v107
	v_and_b32_e32 v4, s40, v107
	v_lshlrev_b32_e32 v5, 16, v100
	v_and_b32_e32 v6, s40, v100
	v_lshlrev_b32_e32 v7, 16, v101
	v_and_b32_e32 v8, s40, v101
	v_lshlrev_b32_e32 v9, 16, v102
	v_and_b32_e32 v10, s40, v102
	v_lshlrev_b32_e32 v11, 16, v103
	v_and_b32_e32 v12, s40, v103
	global_load_dwordx4 v[104:107], v[38:39], off offset:2048
	global_load_dwordx4 v[100:103], v[38:39], off offset:3072
	v_mul_f32_e32 v58, v97, v97
	v_mul_f32_e32 v21, v97, v248
	v_mul_f32_e32 v22, v97, v232
	v_mul_f32_e32 v23, v97, v216
	v_mul_f32_e32 v24, v97, v200
	v_mul_f32_e32 v25, v97, v182
	v_mul_f32_e32 v26, v97, v166
	v_mul_f32_e32 v27, v97, v146
	v_mul_f32_e32 v40, v97, v130
	v_fmac_f32_e32 v58, v159, v159
	v_fmac_f32_e32 v21, v159, v249
	v_fmac_f32_e32 v22, v159, v233
	v_fmac_f32_e32 v23, v159, v217
	v_fmac_f32_e32 v24, v159, v201
	v_fmac_f32_e32 v25, v159, v183
	v_fmac_f32_e32 v26, v159, v167
	v_fmac_f32_e32 v27, v159, v147
	v_fmac_f32_e32 v40, v159, v131
	v_fmac_f32_e32 v58, v187, v187
	v_fmac_f32_e32 v21, v187, v250
	v_fmac_f32_e32 v22, v187, v234
	v_fmac_f32_e32 v23, v187, v218
	v_fmac_f32_e32 v24, v187, v202
	v_fmac_f32_e32 v25, v187, v184
	v_fmac_f32_e32 v26, v187, v168
	v_fmac_f32_e32 v27, v187, v148
	v_fmac_f32_e32 v40, v187, v132
	v_fmac_f32_e32 v58, v0, v0
	v_fmac_f32_e32 v21, v0, v251
	v_fmac_f32_e32 v22, v0, v235
	v_fmac_f32_e32 v23, v0, v219
	v_fmac_f32_e32 v24, v0, v203
	v_fmac_f32_e32 v25, v0, v185
	v_fmac_f32_e32 v26, v0, v169
	v_fmac_f32_e32 v27, v0, v149
	v_fmac_f32_e32 v40, v0, v133
	v_fmac_f32_e32 v58, v1, v1
	v_fmac_f32_e32 v21, v1, v244
	v_fmac_f32_e32 v22, v1, v228
	v_fmac_f32_e32 v23, v1, v212
	v_fmac_f32_e32 v24, v1, v196
	v_fmac_f32_e32 v25, v1, v178
	v_fmac_f32_e32 v26, v1, v162
	v_fmac_f32_e32 v27, v1, v142
	v_fmac_f32_e32 v40, v1, v124
	v_fmac_f32_e32 v58, v2, v2
	v_fmac_f32_e32 v21, v2, v245
	v_fmac_f32_e32 v22, v2, v229
	v_fmac_f32_e32 v23, v2, v213
	v_fmac_f32_e32 v24, v2, v197
	v_fmac_f32_e32 v25, v2, v179
	v_fmac_f32_e32 v26, v2, v163
	v_fmac_f32_e32 v27, v2, v143
	v_fmac_f32_e32 v40, v2, v125
	v_fmac_f32_e32 v58, v3, v3
	v_fmac_f32_e32 v21, v3, v246
	v_fmac_f32_e32 v22, v3, v230
	v_fmac_f32_e32 v23, v3, v214
	v_fmac_f32_e32 v24, v3, v198
	v_fmac_f32_e32 v25, v3, v180
	v_fmac_f32_e32 v26, v3, v164
	v_fmac_f32_e32 v27, v3, v144
	v_fmac_f32_e32 v40, v3, v126
	v_fmac_f32_e32 v58, v4, v4
	v_fmac_f32_e32 v21, v4, v247
	v_fmac_f32_e32 v22, v4, v231
	v_fmac_f32_e32 v23, v4, v215
	v_fmac_f32_e32 v24, v4, v199
	v_fmac_f32_e32 v25, v4, v181
	v_fmac_f32_e32 v26, v4, v165
	v_fmac_f32_e32 v27, v4, v145
; __device__ __forceinline__ void fgate_phase(const bfr* x, const float* wf, const float* bfg, float* cl, float* ctot, LAS float* scr, int bx, int G, int tid, int lane, int wave) {
;     ...
;         for (int j = 0; j < 8; j += 2) { const int row = chunk * 64 + wave * 8 + j; typedef unsigned u32x2 __attribute__((ext_vector_type(2))); const u32x2* xa = (const u32x2*)(x + (size_t)row * D) + lane; const u32x2* xb2 = xa + D / 4; f32x4 va[4], vb[4]; float r[18]; int zo = 0; asm volatile("" : "+v"(zo));
; #pragma unroll
;             for (int jj = 0; jj < 4; ++jj) { const u32x2 wa = xa[64 * jj], wb = xb2[64 * jj]; va[jj] = (f32x4){bf_lo(wa.x), bf_hi(wa.x), bf_lo(wa.y), bf_hi(wa.y)}; vb[jj] = (f32x4){bf_lo(wb.x), bf_hi(wb.x), bf_lo(wb.y), bf_hi(wb.y)}; }
;             r[16] = 0.f; r[17] = 0.f;
; #pragma unroll
;             for (int jj = 0; jj < 4; ++jj) { r[16] += (va[jj].x * va[jj].x + va[jj].y * va[jj].y) + (va[jj].z * va[jj].z + va[jj].w * va[jj].w); r[17] += (vb[jj].x * vb[jj].x + vb[jj].y * vb[jj].y) + (vb[jj].z * vb[jj].z + vb[jj].w * vb[jj].w); }
; #pragma unroll
;             for (int h = 0; h < NH; ++h) { const f32x4* wr = (const f32x4*)(wf + h * D) + lane + zo; float da = 0.f, db = 0.f;
; #pragma unroll
;                 for (int jj = 0; jj < 4; ++jj) { const f32x4 w = wr[64 * jj]; da += (va[jj].x * w.x + va[jj].y * w.y) + (va[jj].z * w.z + va[jj].w * w.w); db += (vb[jj].x * w.x + vb[jj].y * w.y) + (vb[jj].z * w.z + vb[jj].w * w.w); }
;                 r[h] = da; r[8 + h] = db; }
	v_fmac_f32_e32 v40, v4, v127
	v_fmac_f32_e32 v58, v5, v5
	v_fmac_f32_e32 v21, v5, v240
	v_fmac_f32_e32 v22, v5, v224
	v_fmac_f32_e32 v23, v5, v208
	v_fmac_f32_e32 v24, v5, v192
	v_fmac_f32_e32 v25, v5, v174
	v_fmac_f32_e32 v26, v5, v154
	v_fmac_f32_e32 v27, v5, v138
	v_fmac_f32_e32 v40, v5, v120
	v_fmac_f32_e32 v58, v6, v6
	v_fmac_f32_e32 v21, v6, v241
	v_fmac_f32_e32 v22, v6, v225
	v_fmac_f32_e32 v23, v6, v209
	v_fmac_f32_e32 v24, v6, v193
	v_fmac_f32_e32 v25, v6, v175
	v_fmac_f32_e32 v26, v6, v155
	v_fmac_f32_e32 v27, v6, v139
	v_fmac_f32_e32 v40, v6, v121
	v_fmac_f32_e32 v58, v7, v7
	v_fmac_f32_e32 v21, v7, v242
	v_fmac_f32_e32 v22, v7, v226
	v_fmac_f32_e32 v23, v7, v210
	v_fmac_f32_e32 v24, v7, v194
	v_fmac_f32_e32 v25, v7, v176
	v_fmac_f32_e32 v26, v7, v156
	v_fmac_f32_e32 v27, v7, v140
	v_fmac_f32_e32 v40, v7, v122
	v_fmac_f32_e32 v58, v8, v8
	v_fmac_f32_e32 v21, v8, v243
	v_fmac_f32_e32 v22, v8, v227
	v_fmac_f32_e32 v23, v8, v211
	v_fmac_f32_e32 v24, v8, v195
	v_fmac_f32_e32 v25, v8, v177
	v_fmac_f32_e32 v26, v8, v157
	v_fmac_f32_e32 v27, v8, v141
	v_fmac_f32_e32 v40, v8, v123
	v_fmac_f32_e32 v58, v9, v9
	v_fmac_f32_e32 v21, v9, v236
	v_fmac_f32_e32 v22, v9, v220
	v_fmac_f32_e32 v23, v9, v204
	v_fmac_f32_e32 v24, v9, v188
	v_fmac_f32_e32 v25, v9, v170
	v_fmac_f32_e32 v26, v9, v150
	v_fmac_f32_e32 v27, v9, v134
	v_fmac_f32_e32 v40, v9, v116
	v_fmac_f32_e32 v58, v10, v10
	v_fmac_f32_e32 v21, v10, v237
	v_fmac_f32_e32 v22, v10, v221
	v_fmac_f32_e32 v23, v10, v205
	v_fmac_f32_e32 v24, v10, v189
	v_fmac_f32_e32 v25, v10, v171
	v_fmac_f32_e32 v26, v10, v151
	v_fmac_f32_e32 v27, v10, v135
	v_fmac_f32_e32 v40, v10, v117
	v_fmac_f32_e32 v58, v11, v11
	v_fmac_f32_e32 v21, v11, v238
	v_fmac_f32_e32 v22, v11, v222
	v_fmac_f32_e32 v23, v11, v206
	v_fmac_f32_e32 v24, v11, v190
	v_fmac_f32_e32 v25, v11, v172
	v_fmac_f32_e32 v26, v11, v152
	v_fmac_f32_e32 v27, v11, v136
	v_fmac_f32_e32 v40, v11, v118
	v_fmac_f32_e32 v58, v12, v12
	v_fmac_f32_e32 v21, v12, v239
	v_fmac_f32_e32 v22, v12, v223
	v_fmac_f32_e32 v23, v12, v207
	v_fmac_f32_e32 v24, v12, v191
	v_fmac_f32_e32 v25, v12, v173
	v_fmac_f32_e32 v26, v12, v153
	v_fmac_f32_e32 v27, v12, v137
	v_fmac_f32_e32 v40, v12, v119
	v_lshlrev_b32_e32 v97, 16, v84
	v_and_b32_e32 v159, s40, v84
	v_lshlrev_b32_e32 v187, 16, v85
	v_and_b32_e32 v0, s40, v85
	v_lshlrev_b32_e32 v1, 16, v86
	v_and_b32_e32 v2, s40, v86
	v_lshlrev_b32_e32 v3, 16, v87
	v_and_b32_e32 v4, s40, v87
	v_lshlrev_b32_e32 v5, 16, v80
	v_and_b32_e32 v6, s40, v80
	v_lshlrev_b32_e32 v7, 16, v81
	v_and_b32_e32 v8, s40, v81
	v_lshlrev_b32_e32 v9, 16, v82
	v_and_b32_e32 v10, s40, v82
	v_lshlrev_b32_e32 v11, 16, v83
	v_and_b32_e32 v12, s40, v83
	global_load_dwordx4 v[84:87], v[98:99], off
	global_load_dwordx4 v[80:83], v[98:99], off offset:1024
	v_mul_f32_e32 v59, v97, v97
	v_mul_f32_e32 v41, v97, v248
	v_mul_f32_e32 v42, v97, v232
	v_mul_f32_e32 v43, v97, v216
	v_mul_f32_e32 v44, v97, v200
	v_mul_f32_e32 v45, v97, v182
	v_mul_f32_e32 v46, v97, v166
	v_mul_f32_e32 v47, v97, v146
	v_mul_f32_e32 v48, v97, v130
	v_fmac_f32_e32 v59, v159, v159
	v_fmac_f32_e32 v41, v159, v249
	v_fmac_f32_e32 v42, v159, v233
	v_fmac_f32_e32 v43, v159, v217
	v_fmac_f32_e32 v44, v159, v201
	v_fmac_f32_e32 v45, v159, v183
	v_fmac_f32_e32 v46, v159, v167
	v_fmac_f32_e32 v47, v159, v147
	v_fmac_f32_e32 v48, v159, v131
	v_fmac_f32_e32 v59, v187, v187
	v_fmac_f32_e32 v41, v187, v250
	v_fmac_f32_e32 v42, v187, v234
	v_fmac_f32_e32 v43, v187, v218
	v_fmac_f32_e32 v44, v187, v202
	v_fmac_f32_e32 v45, v187, v184
	v_fmac_f32_e32 v46, v187, v168
	v_fmac_f32_e32 v47, v187, v148
	v_fmac_f32_e32 v48, v187, v132
	v_fmac_f32_e32 v59, v0, v0
	v_fmac_f32_e32 v41, v0, v251
	v_fmac_f32_e32 v42, v0, v235
	v_fmac_f32_e32 v43, v0, v219
	v_fmac_f32_e32 v44, v0, v203
	v_fmac_f32_e32 v45, v0, v185
	v_fmac_f32_e32 v46, v0, v169
	v_fmac_f32_e32 v47, v0, v149
	v_fmac_f32_e32 v48, v0, v133
	v_fmac_f32_e32 v59, v1, v1
	v_fmac_f32_e32 v41, v1, v244
	v_fmac_f32_e32 v42, v1, v228
	v_fmac_f32_e32 v43, v1, v212
	v_fmac_f32_e32 v44, v1, v196
	v_fmac_f32_e32 v45, v1, v178
	v_fmac_f32_e32 v46, v1, v162
	v_fmac_f32_e32 v47, v1, v142
	v_fmac_f32_e32 v48, v1, v124
	v_fmac_f32_e32 v59, v2, v2
	v_fmac_f32_e32 v41, v2, v245
	v_fmac_f32_e32 v42, v2, v229
	v_fmac_f32_e32 v43, v2, v213
	v_fmac_f32_e32 v44, v2, v197
	v_fmac_f32_e32 v45, v2, v179
	v_fmac_f32_e32 v46, v2, v163
	v_fmac_f32_e32 v47, v2, v143
	v_fmac_f32_e32 v48, v2, v125
	v_fmac_f32_e32 v59, v3, v3
	v_fmac_f32_e32 v41, v3, v246
	v_fmac_f32_e32 v42, v3, v230
	v_fmac_f32_e32 v43, v3, v214
	v_fmac_f32_e32 v44, v3, v198
	v_fmac_f32_e32 v45, v3, v180
	v_fmac_f32_e32 v46, v3, v164
	v_fmac_f32_e32 v47, v3, v144
	v_fmac_f32_e32 v48, v3, v126
	v_fmac_f32_e32 v59, v4, v4
	v_fmac_f32_e32 v41, v4, v247
	v_fmac_f32_e32 v42, v4, v231
	v_fmac_f32_e32 v43, v4, v215
	v_fmac_f32_e32 v44, v4, v199
	v_fmac_f32_e32 v45, v4, v181
	v_fmac_f32_e32 v46, v4, v165
	v_fmac_f32_e32 v47, v4, v145
	v_fmac_f32_e32 v48, v4, v127
	v_fmac_f32_e32 v59, v5, v5
	v_fmac_f32_e32 v41, v5, v240
	v_fmac_f32_e32 v42, v5, v224
	v_fmac_f32_e32 v43, v5, v208
	v_fmac_f32_e32 v44, v5, v192
	v_fmac_f32_e32 v45, v5, v174
	v_fmac_f32_e32 v46, v5, v154
	v_fmac_f32_e32 v47, v5, v138
	v_fmac_f32_e32 v48, v5, v120
	v_fmac_f32_e32 v59, v6, v6
	v_fmac_f32_e32 v41, v6, v241
	v_fmac_f32_e32 v42, v6, v225
	v_fmac_f32_e32 v43, v6, v209
	v_fmac_f32_e32 v44, v6, v193
	v_fmac_f32_e32 v45, v6, v175
	v_fmac_f32_e32 v46, v6, v155
	v_fmac_f32_e32 v47, v6, v139
	v_fmac_f32_e32 v48, v6, v121
	v_fmac_f32_e32 v59, v7, v7
	v_fmac_f32_e32 v41, v7, v242
	v_fmac_f32_e32 v42, v7, v226
	v_fmac_f32_e32 v43, v7, v210
; __device__ __forceinline__ void fgate_phase(const bfr* x, const float* wf, const float* bfg, float* cl, float* ctot, LAS float* scr, int bx, int G, int tid, int lane, int wave) {
;     ...
;         for (int j = 0; j < 8; j += 2) { const int row = chunk * 64 + wave * 8 + j; typedef unsigned u32x2 __attribute__((ext_vector_type(2))); const u32x2* xa = (const u32x2*)(x + (size_t)row * D) + lane; const u32x2* xb2 = xa + D / 4; f32x4 va[4], vb[4]; float r[18]; int zo = 0; asm volatile("" : "+v"(zo));
; #pragma unroll
;             for (int jj = 0; jj < 4; ++jj) { const u32x2 wa = xa[64 * jj], wb = xb2[64 * jj]; va[jj] = (f32x4){bf_lo(wa.x), bf_hi(wa.x), bf_lo(wa.y), bf_hi(wa.y)}; vb[jj] = (f32x4){bf_lo(wb.x), bf_hi(wb.x), bf_lo(wb.y), bf_hi(wb.y)}; }
;             r[16] = 0.f; r[17] = 0.f;
; #pragma unroll
;             for (int jj = 0; jj < 4; ++jj) { r[16] += (va[jj].x * va[jj].x + va[jj].y * va[jj].y) + (va[jj].z * va[jj].z + va[jj].w * va[jj].w); r[17] += (vb[jj].x * vb[jj].x + vb[jj].y * vb[jj].y) + (vb[jj].z * vb[jj].z + vb[jj].w * vb[jj].w); }
; #pragma unroll
;             for (int h = 0; h < NH; ++h) { const f32x4* wr = (const f32x4*)(wf + h * D) + lane + zo; float da = 0.f, db = 0.f;
; #pragma unroll
;                 for (int jj = 0; jj < 4; ++jj) { const f32x4 w = wr[64 * jj]; da += (va[jj].x * w.x + va[jj].y * w.y) + (va[jj].z * w.z + va[jj].w * w.w); db += (vb[jj].x * w.x + vb[jj].y * w.y) + (vb[jj].z * w.z + vb[jj].w * w.w); }
;                 r[h] = da; r[8 + h] = db; }
	v_fmac_f32_e32 v44, v7, v194
	v_fmac_f32_e32 v45, v7, v176
	v_fmac_f32_e32 v46, v7, v156
	v_fmac_f32_e32 v47, v7, v140
	v_fmac_f32_e32 v48, v7, v122
	v_fmac_f32_e32 v59, v8, v8
	v_fmac_f32_e32 v41, v8, v243
	v_fmac_f32_e32 v42, v8, v227
	v_fmac_f32_e32 v43, v8, v211
	v_fmac_f32_e32 v44, v8, v195
	v_fmac_f32_e32 v45, v8, v177
	v_fmac_f32_e32 v46, v8, v157
	v_fmac_f32_e32 v47, v8, v141
	v_fmac_f32_e32 v48, v8, v123
	v_fmac_f32_e32 v59, v9, v9
	v_fmac_f32_e32 v41, v9, v236
	v_fmac_f32_e32 v42, v9, v220
	v_fmac_f32_e32 v43, v9, v204
	v_fmac_f32_e32 v44, v9, v188
	v_fmac_f32_e32 v45, v9, v170
	v_fmac_f32_e32 v46, v9, v150
	v_fmac_f32_e32 v47, v9, v134
	v_fmac_f32_e32 v48, v9, v116
	v_fmac_f32_e32 v59, v10, v10
	v_fmac_f32_e32 v41, v10, v237
	v_fmac_f32_e32 v42, v10, v221
	v_fmac_f32_e32 v43, v10, v205
	v_fmac_f32_e32 v44, v10, v189
	v_fmac_f32_e32 v45, v10, v171
	v_fmac_f32_e32 v46, v10, v151
	v_fmac_f32_e32 v47, v10, v135
	v_fmac_f32_e32 v48, v10, v117
	v_fmac_f32_e32 v59, v11, v11
	v_fmac_f32_e32 v41, v11, v238
	v_fmac_f32_e32 v42, v11, v222
	v_fmac_f32_e32 v43, v11, v206
	v_fmac_f32_e32 v44, v11, v190
	v_fmac_f32_e32 v45, v11, v172
	v_fmac_f32_e32 v46, v11, v152
	v_fmac_f32_e32 v47, v11, v136
	v_fmac_f32_e32 v48, v11, v118
	v_fmac_f32_e32 v59, v12, v12
	v_fmac_f32_e32 v41, v12, v239
	v_fmac_f32_e32 v42, v12, v223
	v_fmac_f32_e32 v43, v12, v207
	v_fmac_f32_e32 v44, v12, v191
	v_fmac_f32_e32 v45, v12, v173
	v_fmac_f32_e32 v46, v12, v153
	v_fmac_f32_e32 v47, v12, v137
	v_fmac_f32_e32 v48, v12, v119
	v_lshlrev_b32_e32 v97, 16, v76
	v_and_b32_e32 v159, s40, v76
	v_lshlrev_b32_e32 v187, 16, v77
	v_and_b32_e32 v0, s40, v77
	v_lshlrev_b32_e32 v1, 16, v78
	v_and_b32_e32 v2, s40, v78
	v_lshlrev_b32_e32 v3, 16, v79
	v_and_b32_e32 v4, s40, v79
	v_lshlrev_b32_e32 v5, 16, v72
	v_and_b32_e32 v6, s40, v72
	v_lshlrev_b32_e32 v7, 16, v73
	v_and_b32_e32 v8, s40, v73
	v_lshlrev_b32_e32 v9, 16, v74
	v_and_b32_e32 v10, s40, v74
	v_lshlrev_b32_e32 v11, 16, v75
	v_and_b32_e32 v12, s40, v75
	global_load_dwordx4 v[76:79], v[98:99], off offset:2048
	global_load_dwordx4 v[72:75], v[98:99], off offset:3072
	v_mul_f32_e32 v60, v97, v97
	v_mul_f32_e32 v49, v97, v248
	v_mul_f32_e32 v50, v97, v232
	v_mul_f32_e32 v51, v97, v216
	v_mul_f32_e32 v52, v97, v200
	v_mul_f32_e32 v53, v97, v182
	v_mul_f32_e32 v54, v97, v166
	v_mul_f32_e32 v55, v97, v146
	v_mul_f32_e32 v56, v97, v130
	v_fmac_f32_e32 v60, v159, v159
	v_fmac_f32_e32 v49, v159, v249
	v_fmac_f32_e32 v50, v159, v233
	v_fmac_f32_e32 v51, v159, v217
	v_fmac_f32_e32 v52, v159, v201
	v_fmac_f32_e32 v53, v159, v183
	v_fmac_f32_e32 v54, v159, v167
	v_fmac_f32_e32 v55, v159, v147
	v_fmac_f32_e32 v56, v159, v131
	v_fmac_f32_e32 v60, v187, v187
	v_fmac_f32_e32 v49, v187, v250
	v_fmac_f32_e32 v50, v187, v234
	v_fmac_f32_e32 v51, v187, v218
	v_fmac_f32_e32 v52, v187, v202
	v_fmac_f32_e32 v53, v187, v184
	v_fmac_f32_e32 v54, v187, v168
	v_fmac_f32_e32 v55, v187, v148
	v_fmac_f32_e32 v56, v187, v132
	v_fmac_f32_e32 v60, v0, v0
	v_fmac_f32_e32 v49, v0, v251
	v_fmac_f32_e32 v50, v0, v235
	v_fmac_f32_e32 v51, v0, v219
	v_fmac_f32_e32 v52, v0, v203
	v_fmac_f32_e32 v53, v0, v185
	v_fmac_f32_e32 v54, v0, v169
	v_fmac_f32_e32 v55, v0, v149
	v_fmac_f32_e32 v56, v0, v133
	v_fmac_f32_e32 v60, v1, v1
	v_fmac_f32_e32 v49, v1, v244
	v_fmac_f32_e32 v50, v1, v228
	v_fmac_f32_e32 v51, v1, v212
	v_fmac_f32_e32 v52, v1, v196
	v_fmac_f32_e32 v53, v1, v178
	v_fmac_f32_e32 v54, v1, v162
	v_fmac_f32_e32 v55, v1, v142
	v_fmac_f32_e32 v56, v1, v124
	v_fmac_f32_e32 v60, v2, v2
	v_fmac_f32_e32 v49, v2, v245
	v_fmac_f32_e32 v50, v2, v229
	v_fmac_f32_e32 v51, v2, v213
	v_fmac_f32_e32 v52, v2, v197
	v_fmac_f32_e32 v53, v2, v179
	v_fmac_f32_e32 v54, v2, v163
	v_fmac_f32_e32 v55, v2, v143
	v_fmac_f32_e32 v56, v2, v125
	v_fmac_f32_e32 v60, v3, v3
	v_fmac_f32_e32 v49, v3, v246
	v_fmac_f32_e32 v50, v3, v230
	v_fmac_f32_e32 v51, v3, v214
	v_fmac_f32_e32 v52, v3, v198
	v_fmac_f32_e32 v53, v3, v180
	v_fmac_f32_e32 v54, v3, v164
	v_fmac_f32_e32 v55, v3, v144
	v_fmac_f32_e32 v56, v3, v126
	v_fmac_f32_e32 v60, v4, v4
	v_fmac_f32_e32 v49, v4, v247
	v_fmac_f32_e32 v50, v4, v231
	v_fmac_f32_e32 v51, v4, v215
	v_fmac_f32_e32 v52, v4, v199
	v_fmac_f32_e32 v53, v4, v181
	v_fmac_f32_e32 v54, v4, v165
	v_fmac_f32_e32 v55, v4, v145
	v_fmac_f32_e32 v56, v4, v127
	v_fmac_f32_e32 v60, v5, v5
	v_fmac_f32_e32 v49, v5, v240
	v_fmac_f32_e32 v50, v5, v224
	v_fmac_f32_e32 v51, v5, v208
	v_fmac_f32_e32 v52, v5, v192
	v_fmac_f32_e32 v53, v5, v174
	v_fmac_f32_e32 v54, v5, v154
	v_fmac_f32_e32 v55, v5, v138
	v_fmac_f32_e32 v56, v5, v120
	v_fmac_f32_e32 v60, v6, v6
	v_fmac_f32_e32 v49, v6, v241
	v_fmac_f32_e32 v50, v6, v225
	v_fmac_f32_e32 v51, v6, v209
	v_fmac_f32_e32 v52, v6, v193
	v_fmac_f32_e32 v53, v6, v175
	v_fmac_f32_e32 v54, v6, v155
	v_fmac_f32_e32 v55, v6, v139
	v_fmac_f32_e32 v56, v6, v121
	v_fmac_f32_e32 v60, v7, v7
	v_fmac_f32_e32 v49, v7, v242
	v_fmac_f32_e32 v50, v7, v226
	v_fmac_f32_e32 v51, v7, v210
	v_fmac_f32_e32 v52, v7, v194
	v_fmac_f32_e32 v53, v7, v176
	v_fmac_f32_e32 v54, v7, v156
	v_fmac_f32_e32 v55, v7, v140
	v_fmac_f32_e32 v56, v7, v122
	v_fmac_f32_e32 v60, v8, v8
	v_fmac_f32_e32 v49, v8, v243
	v_fmac_f32_e32 v50, v8, v227
	v_fmac_f32_e32 v51, v8, v211
	v_fmac_f32_e32 v52, v8, v195
	v_fmac_f32_e32 v53, v8, v177
	v_fmac_f32_e32 v54, v8, v157
	v_fmac_f32_e32 v55, v8, v141
	v_fmac_f32_e32 v56, v8, v123
	v_fmac_f32_e32 v60, v9, v9
	v_fmac_f32_e32 v49, v9, v236
	v_fmac_f32_e32 v50, v9, v220
	v_fmac_f32_e32 v51, v9, v204
	v_fmac_f32_e32 v52, v9, v188
	v_fmac_f32_e32 v53, v9, v170
	v_fmac_f32_e32 v54, v9, v150
	v_fmac_f32_e32 v55, v9, v134
	v_fmac_f32_e32 v56, v9, v116
; __device__ __forceinline__ float lane_get(float v, int src_lane) { return __builtin_bit_cast(float, __builtin_amdgcn_ds_bpermute(src_lane << 2, __builtin_bit_cast(int, v))); }
; __device__ __forceinline__ void fgate_phase(const bfr* x, const float* wf, const float* bfg, float* cl, float* ctot, LAS float* scr, int bx, int G, int tid, int lane, int wave) {
;     ...
;                 for (int jj = 0; jj < 4; ++jj) { const f32x4 w = wr[64 * jj]; da += (va[jj].x * w.x + va[jj].y * w.y) + (va[jj].z * w.z + va[jj].w * w.w); db += (vb[jj].x * w.x + vb[jj].y * w.y) + (vb[jj].z * w.z + vb[jj].w * w.w); }
;                 r[h] = da; r[8 + h] = db; }
; #pragma unroll
;             for (int o = 1; o < 64; o <<= 1) {
; #pragma unroll
;                 for (int q = 0; q < 18; ++q) r[q] += lane_get(r[q], lane ^ o); }
;             const float rsa = rsqrtf(r[16] * (1.f / D) + EPS), rsb = rsqrtf(r[17] * (1.f / D) + EPS);
;             if (lane < 16) { const int h = lane & 7; float dsel = r[0];
; #pragma unroll
;                 for (int q = 1; q < 16; ++q) dsel = (lane == q) ? r[q] : dsel;
;                 const float zz = dsel * (lane < 8 ? rsa : rsb) + bfg[h]; const float lf = fminf(zz, 0.f) - 0.6931471805599453f * __builtin_amdgcn_logf(1.0f + __builtin_amdgcn_exp2f(-LOG2E * fabsf(zz)));
;                 scr[(wave * 8 + j + (lane >> 3)) * 8 + h] = lf; } }
	v_fmac_f32_e32 v60, v10, v10
	v_fmac_f32_e32 v49, v10, v237
	v_fmac_f32_e32 v50, v10, v221
	v_fmac_f32_e32 v51, v10, v205
	v_fmac_f32_e32 v52, v10, v189
	v_fmac_f32_e32 v53, v10, v171
	v_fmac_f32_e32 v54, v10, v151
	v_fmac_f32_e32 v55, v10, v135
	v_fmac_f32_e32 v56, v10, v117
	v_fmac_f32_e32 v60, v11, v11
	v_fmac_f32_e32 v49, v11, v238
	v_fmac_f32_e32 v50, v11, v222
	v_fmac_f32_e32 v51, v11, v206
	v_fmac_f32_e32 v52, v11, v190
	v_fmac_f32_e32 v53, v11, v172
	v_fmac_f32_e32 v54, v11, v152
	v_fmac_f32_e32 v55, v11, v136
	v_fmac_f32_e32 v56, v11, v118
	v_fmac_f32_e32 v60, v12, v12
	v_fmac_f32_e32 v49, v12, v239
	v_fmac_f32_e32 v50, v12, v223
	v_fmac_f32_e32 v51, v12, v207
	v_fmac_f32_e32 v52, v12, v191
	v_fmac_f32_e32 v53, v12, v173
	v_fmac_f32_e32 v54, v12, v153
	v_fmac_f32_e32 v55, v12, v137
	v_fmac_f32_e32 v56, v12, v119
	s_nop 1
	v_permlane32_swap_b32_e32 v13, v41
	v_permlane32_swap_b32_e32 v14, v42
	v_permlane32_swap_b32_e32 v15, v43
	v_permlane32_swap_b32_e32 v16, v44
	v_permlane32_swap_b32_e32 v17, v45
	v_permlane32_swap_b32_e32 v18, v46
	v_permlane32_swap_b32_e32 v19, v47
	v_permlane32_swap_b32_e32 v20, v48
	v_permlane32_swap_b32_e32 v21, v49
	v_permlane32_swap_b32_e32 v22, v50
	v_permlane32_swap_b32_e32 v23, v51
	v_permlane32_swap_b32_e32 v24, v52
	v_permlane32_swap_b32_e32 v25, v53
	v_permlane32_swap_b32_e32 v26, v54
	v_permlane32_swap_b32_e32 v27, v55
	v_permlane32_swap_b32_e32 v40, v56
	v_permlane32_swap_b32_e32 v57, v59
	v_permlane32_swap_b32_e32 v58, v60
	s_nop 1
	v_add_f32_e32 v13, v13, v41
	v_add_f32_e32 v14, v14, v42
	v_add_f32_e32 v15, v15, v43
	v_add_f32_e32 v16, v16, v44
	v_add_f32_e32 v17, v17, v45
	v_add_f32_e32 v18, v18, v46
	v_add_f32_e32 v19, v19, v47
	v_add_f32_e32 v20, v20, v48
	v_add_f32_e32 v21, v21, v49
	v_add_f32_e32 v22, v22, v50
	v_add_f32_e32 v23, v23, v51
	v_add_f32_e32 v24, v24, v52
	v_add_f32_e32 v25, v25, v53
	v_add_f32_e32 v26, v26, v54
	v_add_f32_e32 v27, v27, v55
	v_add_f32_e32 v40, v40, v56
	v_add_f32_e32 v57, v57, v59
	v_add_f32_e32 v58, v58, v60
	s_nop 1
	v_permlane16_swap_b32_e32 v13, v21
	v_permlane16_swap_b32_e32 v14, v22
	v_permlane16_swap_b32_e32 v15, v23
	v_permlane16_swap_b32_e32 v16, v24
	v_permlane16_swap_b32_e32 v17, v25
	v_permlane16_swap_b32_e32 v18, v26
	v_permlane16_swap_b32_e32 v19, v27
	v_permlane16_swap_b32_e32 v20, v40
	v_permlane16_swap_b32_e32 v57, v58
	s_nop 1
	v_add_f32_e32 v13, v13, v21
	v_add_f32_e32 v14, v14, v22
	v_add_f32_e32 v15, v15, v23
	v_add_f32_e32 v16, v16, v24
	v_add_f32_e32 v17, v17, v25
	v_add_f32_e32 v18, v18, v26
	v_add_f32_e32 v19, v19, v27
	v_add_f32_e32 v20, v20, v40
	v_add_f32_e32 v57, v57, v58
	s_nop 1
	v_add_f32_dpp v13, v13, v13 quad_perm:[1,0,3,2] row_mask:0xf bank_mask:0xf
	v_add_f32_dpp v14, v14, v14 quad_perm:[1,0,3,2] row_mask:0xf bank_mask:0xf
	v_add_f32_dpp v15, v15, v15 quad_perm:[1,0,3,2] row_mask:0xf bank_mask:0xf
	v_add_f32_dpp v16, v16, v16 quad_perm:[1,0,3,2] row_mask:0xf bank_mask:0xf
	v_add_f32_dpp v17, v17, v17 quad_perm:[1,0,3,2] row_mask:0xf bank_mask:0xf
	v_add_f32_dpp v18, v18, v18 quad_perm:[1,0,3,2] row_mask:0xf bank_mask:0xf
	v_add_f32_dpp v19, v19, v19 quad_perm:[1,0,3,2] row_mask:0xf bank_mask:0xf
	v_add_f32_dpp v20, v20, v20 quad_perm:[1,0,3,2] row_mask:0xf bank_mask:0xf
	v_add_f32_dpp v57, v57, v57 quad_perm:[1,0,3,2] row_mask:0xf bank_mask:0xf
	s_nop 1
	v_add_f32_dpp v13, v13, v13 quad_perm:[2,3,0,1] row_mask:0xf bank_mask:0xf
	v_add_f32_dpp v14, v14, v14 quad_perm:[2,3,0,1] row_mask:0xf bank_mask:0xf
	v_add_f32_dpp v15, v15, v15 quad_perm:[2,3,0,1] row_mask:0xf bank_mask:0xf
	v_add_f32_dpp v16, v16, v16 quad_perm:[2,3,0,1] row_mask:0xf bank_mask:0xf
	v_add_f32_dpp v17, v17, v17 quad_perm:[2,3,0,1] row_mask:0xf bank_mask:0xf
	v_add_f32_dpp v18, v18, v18 quad_perm:[2,3,0,1] row_mask:0xf bank_mask:0xf
	v_add_f32_dpp v19, v19, v19 quad_perm:[2,3,0,1] row_mask:0xf bank_mask:0xf
	v_add_f32_dpp v20, v20, v20 quad_perm:[2,3,0,1] row_mask:0xf bank_mask:0xf
	v_add_f32_dpp v57, v57, v57 quad_perm:[2,3,0,1] row_mask:0xf bank_mask:0xf
	s_nop 1
	v_add_f32_dpp v13, v13, v13 row_half_mirror row_mask:0xf bank_mask:0xf
	v_add_f32_dpp v14, v14, v14 row_half_mirror row_mask:0xf bank_mask:0xf
	v_add_f32_dpp v15, v15, v15 row_half_mirror row_mask:0xf bank_mask:0xf
	v_add_f32_dpp v16, v16, v16 row_half_mirror row_mask:0xf bank_mask:0xf
	v_add_f32_dpp v17, v17, v17 row_half_mirror row_mask:0xf bank_mask:0xf
	v_add_f32_dpp v18, v18, v18 row_half_mirror row_mask:0xf bank_mask:0xf
	v_add_f32_dpp v19, v19, v19 row_half_mirror row_mask:0xf bank_mask:0xf
	v_add_f32_dpp v20, v20, v20 row_half_mirror row_mask:0xf bank_mask:0xf
	v_add_f32_dpp v57, v57, v57 row_half_mirror row_mask:0xf bank_mask:0xf
	s_nop 1
	v_add_f32_dpp v13, v13, v13 row_mirror row_mask:0xf bank_mask:0xf
	v_add_f32_dpp v14, v14, v14 row_mirror row_mask:0xf bank_mask:0xf
	v_add_f32_dpp v15, v15, v15 row_mirror row_mask:0xf bank_mask:0xf
	v_add_f32_dpp v16, v16, v16 row_mirror row_mask:0xf bank_mask:0xf
	v_add_f32_dpp v17, v17, v17 row_mirror row_mask:0xf bank_mask:0xf
	v_add_f32_dpp v18, v18, v18 row_mirror row_mask:0xf bank_mask:0xf
	v_add_f32_dpp v19, v19, v19 row_mirror row_mask:0xf bank_mask:0xf
	v_add_f32_dpp v20, v20, v20 row_mirror row_mask:0xf bank_mask:0xf
	v_add_f32_dpp v57, v57, v57 row_mirror row_mask:0xf bank_mask:0xf
	s_nop 1
	v_mov_b32_e32 v62, v13
	v_cndmask_b32_e64 v62, v62, v14, s[6:7]
	v_cndmask_b32_e64 v62, v62, v15, s[8:9]
	v_cndmask_b32_e64 v62, v62, v16, s[10:11]
	v_cndmask_b32_e64 v62, v62, v17, s[12:13]
	v_cndmask_b32_e64 v62, v62, v18, s[14:15]
	v_cndmask_b32_e64 v62, v62, v19, s[16:17]
	v_cndmask_b32_e64 v62, v62, v20, s[18:19]
	v_mul_f32_e32 v63, 0x3a800000, v57
	v_add_f32_e32 v63, 0x358637bd, v63
	v_rsq_f32_e32 v63, v63
	s_nop 0
	v_fma_f32 v62, v62, v63, v61
	v_mul_f32_e64 v63, |v62|, s65
	v_exp_f32_e32 v63, v63
	v_min_f32_e32 v62, 0, v62
	v_add_f32_e32 v63, 1.0, v63
	v_log_f32_e32 v63, v63
	s_nop 0
	v_fmac_f32_e32 v62, 0xbf317218, v63
	s_mov_b64 s[54:55], exec
	s_mov_b32 exec_lo, 0xff00ff
	s_mov_b32 exec_hi, 0xff00ff
	ds_write_b32 v65, v62
	s_mov_b64 exec, s[54:55]
	s_waitcnt vmcnt(0) lgkmcnt(0)
; __device__ __forceinline__ void fgate_phase(const bfr* x, const float* wf, const float* bfg, float* cl, float* ctot, LAS float* scr, int bx, int G, int tid, int lane, int wave) {
;     ...
;             for (int jj = 0; jj < 4; ++jj) { const u32x2 wa = xa[64 * jj], wb = xb2[64 * jj]; va[jj] = (f32x4){bf_lo(wa.x), bf_hi(wa.x), bf_lo(wa.y), bf_hi(wa.y)}; vb[jj] = (f32x4){bf_lo(wb.x), bf_hi(wb.x), bf_lo(wb.y), bf_hi(wb.y)}; }
;             r[16] = 0.f; r[17] = 0.f;
; #pragma unroll
;             for (int jj = 0; jj < 4; ++jj) { r[16] += (va[jj].x * va[jj].x + va[jj].y * va[jj].y) + (va[jj].z * va[jj].z + va[jj].w * va[jj].w); r[17] += (vb[jj].x * vb[jj].x + vb[jj].y * vb[jj].y) + (vb[jj].z * vb[jj].z + vb[jj].w * vb[jj].w); }
; #pragma unroll
;             for (int h = 0; h < NH; ++h) { const f32x4* wr = (const f32x4*)(wf + h * D) + lane + zo; float da = 0.f, db = 0.f;
; #pragma unroll
;                 for (int jj = 0; jj < 4; ++jj) { const f32x4 w = wr[64 * jj]; da += (va[jj].x * w.x + va[jj].y * w.y) + (va[jj].z * w.z + va[jj].w * w.w); db += (vb[jj].x * w.x + vb[jj].y * w.y) + (vb[jj].z * w.z + vb[jj].w * w.w); }
;                 r[h] = da; r[8 + h] = db; }
	v_lshlrev_b32_e32 v97, 16, v112
	v_and_b32_e32 v159, s40, v112
	v_lshlrev_b32_e32 v187, 16, v113
	v_and_b32_e32 v0, s40, v113
	v_lshlrev_b32_e32 v1, 16, v114
	v_and_b32_e32 v2, s40, v114
	v_lshlrev_b32_e32 v3, 16, v115
	v_and_b32_e32 v4, s40, v115
	v_lshlrev_b32_e32 v5, 16, v108
	v_and_b32_e32 v6, s40, v108
	v_lshlrev_b32_e32 v7, 16, v109
	v_and_b32_e32 v8, s40, v109
	v_lshlrev_b32_e32 v9, 16, v110
	v_and_b32_e32 v10, s40, v110
	v_lshlrev_b32_e32 v11, 16, v111
	v_and_b32_e32 v12, s40, v111
	v_mul_f32_e32 v57, v97, v97
	v_mul_f32_e32 v13, v97, v248
	v_mul_f32_e32 v14, v97, v232
	v_mul_f32_e32 v15, v97, v216
	v_mul_f32_e32 v16, v97, v200
	v_mul_f32_e32 v17, v97, v182
	v_mul_f32_e32 v18, v97, v166
	v_mul_f32_e32 v19, v97, v146
	v_mul_f32_e32 v20, v97, v130
	v_fmac_f32_e32 v57, v159, v159
	v_fmac_f32_e32 v13, v159, v249
	v_fmac_f32_e32 v14, v159, v233
	v_fmac_f32_e32 v15, v159, v217
	v_fmac_f32_e32 v16, v159, v201
	v_fmac_f32_e32 v17, v159, v183
	v_fmac_f32_e32 v18, v159, v167
	v_fmac_f32_e32 v19, v159, v147
	v_fmac_f32_e32 v20, v159, v131
	v_fmac_f32_e32 v57, v187, v187
	v_fmac_f32_e32 v13, v187, v250
	v_fmac_f32_e32 v14, v187, v234
	v_fmac_f32_e32 v15, v187, v218
	v_fmac_f32_e32 v16, v187, v202
	v_fmac_f32_e32 v17, v187, v184
	v_fmac_f32_e32 v18, v187, v168
	v_fmac_f32_e32 v19, v187, v148
	v_fmac_f32_e32 v20, v187, v132
	v_fmac_f32_e32 v57, v0, v0
	v_fmac_f32_e32 v13, v0, v251
	v_fmac_f32_e32 v14, v0, v235
	v_fmac_f32_e32 v15, v0, v219
	v_fmac_f32_e32 v16, v0, v203
	v_fmac_f32_e32 v17, v0, v185
	v_fmac_f32_e32 v18, v0, v169
	v_fmac_f32_e32 v19, v0, v149
	v_fmac_f32_e32 v20, v0, v133
	v_fmac_f32_e32 v57, v1, v1
	v_fmac_f32_e32 v13, v1, v244
	v_fmac_f32_e32 v14, v1, v228
	v_fmac_f32_e32 v15, v1, v212
	v_fmac_f32_e32 v16, v1, v196
	v_fmac_f32_e32 v17, v1, v178
	v_fmac_f32_e32 v18, v1, v162
	v_fmac_f32_e32 v19, v1, v142
	v_fmac_f32_e32 v20, v1, v124
	v_fmac_f32_e32 v57, v2, v2
	v_fmac_f32_e32 v13, v2, v245
	v_fmac_f32_e32 v14, v2, v229
	v_fmac_f32_e32 v15, v2, v213
	v_fmac_f32_e32 v16, v2, v197
	v_fmac_f32_e32 v17, v2, v179
	v_fmac_f32_e32 v18, v2, v163
	v_fmac_f32_e32 v19, v2, v143
	v_fmac_f32_e32 v20, v2, v125
	v_fmac_f32_e32 v57, v3, v3
	v_fmac_f32_e32 v13, v3, v246
	v_fmac_f32_e32 v14, v3, v230
	v_fmac_f32_e32 v15, v3, v214
	v_fmac_f32_e32 v16, v3, v198
	v_fmac_f32_e32 v17, v3, v180
	v_fmac_f32_e32 v18, v3, v164
	v_fmac_f32_e32 v19, v3, v144
	v_fmac_f32_e32 v20, v3, v126
	v_fmac_f32_e32 v57, v4, v4
	v_fmac_f32_e32 v13, v4, v247
	v_fmac_f32_e32 v14, v4, v231
	v_fmac_f32_e32 v15, v4, v215
	v_fmac_f32_e32 v16, v4, v199
	v_fmac_f32_e32 v17, v4, v181
	v_fmac_f32_e32 v18, v4, v165
	v_fmac_f32_e32 v19, v4, v145
	v_fmac_f32_e32 v20, v4, v127
	v_fmac_f32_e32 v57, v5, v5
	v_fmac_f32_e32 v13, v5, v240
	v_fmac_f32_e32 v14, v5, v224
	v_fmac_f32_e32 v15, v5, v208
	v_fmac_f32_e32 v16, v5, v192
	v_fmac_f32_e32 v17, v5, v174
	v_fmac_f32_e32 v18, v5, v154
	v_fmac_f32_e32 v19, v5, v138
	v_fmac_f32_e32 v20, v5, v120
	v_fmac_f32_e32 v57, v6, v6
	v_fmac_f32_e32 v13, v6, v241
	v_fmac_f32_e32 v14, v6, v225
	v_fmac_f32_e32 v15, v6, v209
	v_fmac_f32_e32 v16, v6, v193
	v_fmac_f32_e32 v17, v6, v175
	v_fmac_f32_e32 v18, v6, v155
	v_fmac_f32_e32 v19, v6, v139
	v_fmac_f32_e32 v20, v6, v121
	v_fmac_f32_e32 v57, v7, v7
	v_fmac_f32_e32 v13, v7, v242
	v_fmac_f32_e32 v14, v7, v226
	v_fmac_f32_e32 v15, v7, v210
	v_fmac_f32_e32 v16, v7, v194
	v_fmac_f32_e32 v17, v7, v176
	v_fmac_f32_e32 v18, v7, v156
	v_fmac_f32_e32 v19, v7, v140
	v_fmac_f32_e32 v20, v7, v122
	v_fmac_f32_e32 v57, v8, v8
	v_fmac_f32_e32 v13, v8, v243
	v_fmac_f32_e32 v14, v8, v227
	v_fmac_f32_e32 v15, v8, v211
	v_fmac_f32_e32 v16, v8, v195
	v_fmac_f32_e32 v17, v8, v177
	v_fmac_f32_e32 v18, v8, v157
	v_fmac_f32_e32 v19, v8, v141
	v_fmac_f32_e32 v20, v8, v123
	v_fmac_f32_e32 v57, v9, v9
	v_fmac_f32_e32 v13, v9, v236
	v_fmac_f32_e32 v14, v9, v220
	v_fmac_f32_e32 v15, v9, v204
	v_fmac_f32_e32 v16, v9, v188
	v_fmac_f32_e32 v17, v9, v170
	v_fmac_f32_e32 v18, v9, v150
	v_fmac_f32_e32 v19, v9, v134
	v_fmac_f32_e32 v20, v9, v116
	v_fmac_f32_e32 v57, v10, v10
	v_fmac_f32_e32 v13, v10, v237
	v_fmac_f32_e32 v14, v10, v221
	v_fmac_f32_e32 v15, v10, v205
	v_fmac_f32_e32 v16, v10, v189
	v_fmac_f32_e32 v17, v10, v171
	v_fmac_f32_e32 v18, v10, v151
	v_fmac_f32_e32 v19, v10, v135
	v_fmac_f32_e32 v20, v10, v117
	v_fmac_f32_e32 v57, v11, v11
	v_fmac_f32_e32 v13, v11, v238
	v_fmac_f32_e32 v14, v11, v222
	v_fmac_f32_e32 v15, v11, v206
	v_fmac_f32_e32 v16, v11, v190
	v_fmac_f32_e32 v17, v11, v172
	v_fmac_f32_e32 v18, v11, v152
	v_fmac_f32_e32 v19, v11, v136
	v_fmac_f32_e32 v20, v11, v118
	v_fmac_f32_e32 v57, v12, v12
	v_fmac_f32_e32 v13, v12, v239
	v_fmac_f32_e32 v14, v12, v223
	v_fmac_f32_e32 v15, v12, v207
	v_fmac_f32_e32 v16, v12, v191
	v_fmac_f32_e32 v17, v12, v173
	v_fmac_f32_e32 v18, v12, v153
	v_fmac_f32_e32 v19, v12, v137
	v_fmac_f32_e32 v20, v12, v119
	v_lshlrev_b32_e32 v97, 16, v104
	v_and_b32_e32 v159, s40, v104
	v_lshlrev_b32_e32 v187, 16, v105
	v_and_b32_e32 v0, s40, v105
	v_lshlrev_b32_e32 v1, 16, v106
	v_and_b32_e32 v2, s40, v106
	v_lshlrev_b32_e32 v3, 16, v107
	v_and_b32_e32 v4, s40, v107
	v_lshlrev_b32_e32 v5, 16, v100
	v_and_b32_e32 v6, s40, v100
	v_lshlrev_b32_e32 v7, 16, v101
	v_and_b32_e32 v8, s40, v101
	v_lshlrev_b32_e32 v9, 16, v102
	v_and_b32_e32 v10, s40, v102
	v_lshlrev_b32_e32 v11, 16, v103
	v_and_b32_e32 v12, s40, v103
	v_mul_f32_e32 v58, v97, v97
	v_mul_f32_e32 v21, v97, v248
	v_mul_f32_e32 v22, v97, v232
	v_mul_f32_e32 v23, v97, v216
	v_mul_f32_e32 v24, v97, v200
	v_mul_f32_e32 v25, v97, v182
	v_mul_f32_e32 v26, v97, v166
	v_mul_f32_e32 v27, v97, v146
	v_mul_f32_e32 v40, v97, v130
	v_fmac_f32_e32 v58, v159, v159
; __device__ __forceinline__ void fgate_phase(const bfr* x, const float* wf, const float* bfg, float* cl, float* ctot, LAS float* scr, int bx, int G, int tid, int lane, int wave) {
;     ...
;             for (int jj = 0; jj < 4; ++jj) { const u32x2 wa = xa[64 * jj], wb = xb2[64 * jj]; va[jj] = (f32x4){bf_lo(wa.x), bf_hi(wa.x), bf_lo(wa.y), bf_hi(wa.y)}; vb[jj] = (f32x4){bf_lo(wb.x), bf_hi(wb.x), bf_lo(wb.y), bf_hi(wb.y)}; }
;             r[16] = 0.f; r[17] = 0.f;
; #pragma unroll
;             for (int jj = 0; jj < 4; ++jj) { r[16] += (va[jj].x * va[jj].x + va[jj].y * va[jj].y) + (va[jj].z * va[jj].z + va[jj].w * va[jj].w); r[17] += (vb[jj].x * vb[jj].x + vb[jj].y * vb[jj].y) + (vb[jj].z * vb[jj].z + vb[jj].w * vb[jj].w); }
; #pragma unroll
;             for (int h = 0; h < NH; ++h) { const f32x4* wr = (const f32x4*)(wf + h * D) + lane + zo; float da = 0.f, db = 0.f;
; #pragma unroll
;                 for (int jj = 0; jj < 4; ++jj) { const f32x4 w = wr[64 * jj]; da += (va[jj].x * w.x + va[jj].y * w.y) + (va[jj].z * w.z + va[jj].w * w.w); db += (vb[jj].x * w.x + vb[jj].y * w.y) + (vb[jj].z * w.z + vb[jj].w * w.w); }
;                 r[h] = da; r[8 + h] = db; }
	v_fmac_f32_e32 v21, v159, v249
	v_fmac_f32_e32 v22, v159, v233
	v_fmac_f32_e32 v23, v159, v217
	v_fmac_f32_e32 v24, v159, v201
	v_fmac_f32_e32 v25, v159, v183
	v_fmac_f32_e32 v26, v159, v167
	v_fmac_f32_e32 v27, v159, v147
	v_fmac_f32_e32 v40, v159, v131
	v_fmac_f32_e32 v58, v187, v187
	v_fmac_f32_e32 v21, v187, v250
	v_fmac_f32_e32 v22, v187, v234
	v_fmac_f32_e32 v23, v187, v218
	v_fmac_f32_e32 v24, v187, v202
	v_fmac_f32_e32 v25, v187, v184
	v_fmac_f32_e32 v26, v187, v168
	v_fmac_f32_e32 v27, v187, v148
	v_fmac_f32_e32 v40, v187, v132
	v_fmac_f32_e32 v58, v0, v0
	v_fmac_f32_e32 v21, v0, v251
	v_fmac_f32_e32 v22, v0, v235
	v_fmac_f32_e32 v23, v0, v219
	v_fmac_f32_e32 v24, v0, v203
	v_fmac_f32_e32 v25, v0, v185
	v_fmac_f32_e32 v26, v0, v169
	v_fmac_f32_e32 v27, v0, v149
	v_fmac_f32_e32 v40, v0, v133
	v_fmac_f32_e32 v58, v1, v1
	v_fmac_f32_e32 v21, v1, v244
	v_fmac_f32_e32 v22, v1, v228
	v_fmac_f32_e32 v23, v1, v212
	v_fmac_f32_e32 v24, v1, v196
	v_fmac_f32_e32 v25, v1, v178
	v_fmac_f32_e32 v26, v1, v162
	v_fmac_f32_e32 v27, v1, v142
	v_fmac_f32_e32 v40, v1, v124
	v_fmac_f32_e32 v58, v2, v2
	v_fmac_f32_e32 v21, v2, v245
	v_fmac_f32_e32 v22, v2, v229
	v_fmac_f32_e32 v23, v2, v213
	v_fmac_f32_e32 v24, v2, v197
	v_fmac_f32_e32 v25, v2, v179
	v_fmac_f32_e32 v26, v2, v163
	v_fmac_f32_e32 v27, v2, v143
	v_fmac_f32_e32 v40, v2, v125
	v_fmac_f32_e32 v58, v3, v3
	v_fmac_f32_e32 v21, v3, v246
	v_fmac_f32_e32 v22, v3, v230
	v_fmac_f32_e32 v23, v3, v214
	v_fmac_f32_e32 v24, v3, v198
	v_fmac_f32_e32 v25, v3, v180
	v_fmac_f32_e32 v26, v3, v164
	v_fmac_f32_e32 v27, v3, v144
	v_fmac_f32_e32 v40, v3, v126
	v_fmac_f32_e32 v58, v4, v4
	v_fmac_f32_e32 v21, v4, v247
	v_fmac_f32_e32 v22, v4, v231
	v_fmac_f32_e32 v23, v4, v215
	v_fmac_f32_e32 v24, v4, v199
	v_fmac_f32_e32 v25, v4, v181
	v_fmac_f32_e32 v26, v4, v165
	v_fmac_f32_e32 v27, v4, v145
	v_fmac_f32_e32 v40, v4, v127
	v_fmac_f32_e32 v58, v5, v5
	v_fmac_f32_e32 v21, v5, v240
	v_fmac_f32_e32 v22, v5, v224
	v_fmac_f32_e32 v23, v5, v208
	v_fmac_f32_e32 v24, v5, v192
	v_fmac_f32_e32 v25, v5, v174
	v_fmac_f32_e32 v26, v5, v154
	v_fmac_f32_e32 v27, v5, v138
	v_fmac_f32_e32 v40, v5, v120
	v_fmac_f32_e32 v58, v6, v6
	v_fmac_f32_e32 v21, v6, v241
	v_fmac_f32_e32 v22, v6, v225
	v_fmac_f32_e32 v23, v6, v209
	v_fmac_f32_e32 v24, v6, v193
	v_fmac_f32_e32 v25, v6, v175
	v_fmac_f32_e32 v26, v6, v155
	v_fmac_f32_e32 v27, v6, v139
	v_fmac_f32_e32 v40, v6, v121
	v_fmac_f32_e32 v58, v7, v7
	v_fmac_f32_e32 v21, v7, v242
	v_fmac_f32_e32 v22, v7, v226
	v_fmac_f32_e32 v23, v7, v210
	v_fmac_f32_e32 v24, v7, v194
	v_fmac_f32_e32 v25, v7, v176
	v_fmac_f32_e32 v26, v7, v156
	v_fmac_f32_e32 v27, v7, v140
	v_fmac_f32_e32 v40, v7, v122
	v_fmac_f32_e32 v58, v8, v8
	v_fmac_f32_e32 v21, v8, v243
	v_fmac_f32_e32 v22, v8, v227
	v_fmac_f32_e32 v23, v8, v211
	v_fmac_f32_e32 v24, v8, v195
	v_fmac_f32_e32 v25, v8, v177
	v_fmac_f32_e32 v26, v8, v157
	v_fmac_f32_e32 v27, v8, v141
	v_fmac_f32_e32 v40, v8, v123
	v_fmac_f32_e32 v58, v9, v9
	v_fmac_f32_e32 v21, v9, v236
	v_fmac_f32_e32 v22, v9, v220
	v_fmac_f32_e32 v23, v9, v204
	v_fmac_f32_e32 v24, v9, v188
	v_fmac_f32_e32 v25, v9, v170
	v_fmac_f32_e32 v26, v9, v150
	v_fmac_f32_e32 v27, v9, v134
	v_fmac_f32_e32 v40, v9, v116
	v_fmac_f32_e32 v58, v10, v10
	v_fmac_f32_e32 v21, v10, v237
	v_fmac_f32_e32 v22, v10, v221
	v_fmac_f32_e32 v23, v10, v205
	v_fmac_f32_e32 v24, v10, v189
	v_fmac_f32_e32 v25, v10, v171
	v_fmac_f32_e32 v26, v10, v151
	v_fmac_f32_e32 v27, v10, v135
	v_fmac_f32_e32 v40, v10, v117
	v_fmac_f32_e32 v58, v11, v11
	v_fmac_f32_e32 v21, v11, v238
	v_fmac_f32_e32 v22, v11, v222
	v_fmac_f32_e32 v23, v11, v206
	v_fmac_f32_e32 v24, v11, v190
	v_fmac_f32_e32 v25, v11, v172
	v_fmac_f32_e32 v26, v11, v152
	v_fmac_f32_e32 v27, v11, v136
	v_fmac_f32_e32 v40, v11, v118
	v_fmac_f32_e32 v58, v12, v12
	v_fmac_f32_e32 v21, v12, v239
	v_fmac_f32_e32 v22, v12, v223
	v_fmac_f32_e32 v23, v12, v207
	v_fmac_f32_e32 v24, v12, v191
	v_fmac_f32_e32 v25, v12, v173
	v_fmac_f32_e32 v26, v12, v153
	v_fmac_f32_e32 v27, v12, v137
	v_fmac_f32_e32 v40, v12, v119
	v_lshlrev_b32_e32 v97, 16, v84
	v_and_b32_e32 v159, s40, v84
	v_lshlrev_b32_e32 v187, 16, v85
	v_and_b32_e32 v0, s40, v85
	v_lshlrev_b32_e32 v1, 16, v86
	v_and_b32_e32 v2, s40, v86
	v_lshlrev_b32_e32 v3, 16, v87
	v_and_b32_e32 v4, s40, v87
	v_lshlrev_b32_e32 v5, 16, v80
	v_and_b32_e32 v6, s40, v80
	v_lshlrev_b32_e32 v7, 16, v81
	v_and_b32_e32 v8, s40, v81
	v_lshlrev_b32_e32 v9, 16, v82
	v_and_b32_e32 v10, s40, v82
	v_lshlrev_b32_e32 v11, 16, v83
	v_and_b32_e32 v12, s40, v83
	v_mul_f32_e32 v59, v97, v97
	v_mul_f32_e32 v41, v97, v248
	v_mul_f32_e32 v42, v97, v232
	v_mul_f32_e32 v43, v97, v216
	v_mul_f32_e32 v44, v97, v200
	v_mul_f32_e32 v45, v97, v182
	v_mul_f32_e32 v46, v97, v166
	v_mul_f32_e32 v47, v97, v146
	v_mul_f32_e32 v48, v97, v130
	v_fmac_f32_e32 v59, v159, v159
	v_fmac_f32_e32 v41, v159, v249
	v_fmac_f32_e32 v42, v159, v233
	v_fmac_f32_e32 v43, v159, v217
	v_fmac_f32_e32 v44, v159, v201
	v_fmac_f32_e32 v45, v159, v183
	v_fmac_f32_e32 v46, v159, v167
	v_fmac_f32_e32 v47, v159, v147
	v_fmac_f32_e32 v48, v159, v131
	v_fmac_f32_e32 v59, v187, v187
	v_fmac_f32_e32 v41, v187, v250
	v_fmac_f32_e32 v42, v187, v234
	v_fmac_f32_e32 v43, v187, v218
	v_fmac_f32_e32 v44, v187, v202
	v_fmac_f32_e32 v45, v187, v184
	v_fmac_f32_e32 v46, v187, v168
	v_fmac_f32_e32 v47, v187, v148
	v_fmac_f32_e32 v48, v187, v132
	v_fmac_f32_e32 v59, v0, v0
	v_fmac_f32_e32 v41, v0, v251
	v_fmac_f32_e32 v42, v0, v235
	v_fmac_f32_e32 v43, v0, v219
	v_fmac_f32_e32 v44, v0, v203
	v_fmac_f32_e32 v45, v0, v185
	v_fmac_f32_e32 v46, v0, v169
	v_fmac_f32_e32 v47, v0, v149
	v_fmac_f32_e32 v48, v0, v133
; __device__ __forceinline__ void fgate_phase(const bfr* x, const float* wf, const float* bfg, float* cl, float* ctot, LAS float* scr, int bx, int G, int tid, int lane, int wave) {
;     ...
;             for (int jj = 0; jj < 4; ++jj) { const u32x2 wa = xa[64 * jj], wb = xb2[64 * jj]; va[jj] = (f32x4){bf_lo(wa.x), bf_hi(wa.x), bf_lo(wa.y), bf_hi(wa.y)}; vb[jj] = (f32x4){bf_lo(wb.x), bf_hi(wb.x), bf_lo(wb.y), bf_hi(wb.y)}; }
;             r[16] = 0.f; r[17] = 0.f;
; #pragma unroll
;             for (int jj = 0; jj < 4; ++jj) { r[16] += (va[jj].x * va[jj].x + va[jj].y * va[jj].y) + (va[jj].z * va[jj].z + va[jj].w * va[jj].w); r[17] += (vb[jj].x * vb[jj].x + vb[jj].y * vb[jj].y) + (vb[jj].z * vb[jj].z + vb[jj].w * vb[jj].w); }
; #pragma unroll
;             for (int h = 0; h < NH; ++h) { const f32x4* wr = (const f32x4*)(wf + h * D) + lane + zo; float da = 0.f, db = 0.f;
; #pragma unroll
;                 for (int jj = 0; jj < 4; ++jj) { const f32x4 w = wr[64 * jj]; da += (va[jj].x * w.x + va[jj].y * w.y) + (va[jj].z * w.z + va[jj].w * w.w); db += (vb[jj].x * w.x + vb[jj].y * w.y) + (vb[jj].z * w.z + vb[jj].w * w.w); }
;                 r[h] = da; r[8 + h] = db; }
	v_fmac_f32_e32 v59, v1, v1
	v_fmac_f32_e32 v41, v1, v244
	v_fmac_f32_e32 v42, v1, v228
	v_fmac_f32_e32 v43, v1, v212
	v_fmac_f32_e32 v44, v1, v196
	v_fmac_f32_e32 v45, v1, v178
	v_fmac_f32_e32 v46, v1, v162
	v_fmac_f32_e32 v47, v1, v142
	v_fmac_f32_e32 v48, v1, v124
	v_fmac_f32_e32 v59, v2, v2
	v_fmac_f32_e32 v41, v2, v245
	v_fmac_f32_e32 v42, v2, v229
	v_fmac_f32_e32 v43, v2, v213
	v_fmac_f32_e32 v44, v2, v197
	v_fmac_f32_e32 v45, v2, v179
	v_fmac_f32_e32 v46, v2, v163
	v_fmac_f32_e32 v47, v2, v143
	v_fmac_f32_e32 v48, v2, v125
	v_fmac_f32_e32 v59, v3, v3
	v_fmac_f32_e32 v41, v3, v246
	v_fmac_f32_e32 v42, v3, v230
	v_fmac_f32_e32 v43, v3, v214
	v_fmac_f32_e32 v44, v3, v198
	v_fmac_f32_e32 v45, v3, v180
	v_fmac_f32_e32 v46, v3, v164
	v_fmac_f32_e32 v47, v3, v144
	v_fmac_f32_e32 v48, v3, v126
	v_fmac_f32_e32 v59, v4, v4
	v_fmac_f32_e32 v41, v4, v247
	v_fmac_f32_e32 v42, v4, v231
	v_fmac_f32_e32 v43, v4, v215
	v_fmac_f32_e32 v44, v4, v199
	v_fmac_f32_e32 v45, v4, v181
	v_fmac_f32_e32 v46, v4, v165
	v_fmac_f32_e32 v47, v4, v145
	v_fmac_f32_e32 v48, v4, v127
	v_fmac_f32_e32 v59, v5, v5
	v_fmac_f32_e32 v41, v5, v240
	v_fmac_f32_e32 v42, v5, v224
	v_fmac_f32_e32 v43, v5, v208
	v_fmac_f32_e32 v44, v5, v192
	v_fmac_f32_e32 v45, v5, v174
	v_fmac_f32_e32 v46, v5, v154
	v_fmac_f32_e32 v47, v5, v138
	v_fmac_f32_e32 v48, v5, v120
	v_fmac_f32_e32 v59, v6, v6
	v_fmac_f32_e32 v41, v6, v241
	v_fmac_f32_e32 v42, v6, v225
	v_fmac_f32_e32 v43, v6, v209
	v_fmac_f32_e32 v44, v6, v193
	v_fmac_f32_e32 v45, v6, v175
	v_fmac_f32_e32 v46, v6, v155
	v_fmac_f32_e32 v47, v6, v139
	v_fmac_f32_e32 v48, v6, v121
	v_fmac_f32_e32 v59, v7, v7
	v_fmac_f32_e32 v41, v7, v242
	v_fmac_f32_e32 v42, v7, v226
	v_fmac_f32_e32 v43, v7, v210
	v_fmac_f32_e32 v44, v7, v194
	v_fmac_f32_e32 v45, v7, v176
	v_fmac_f32_e32 v46, v7, v156
	v_fmac_f32_e32 v47, v7, v140
	v_fmac_f32_e32 v48, v7, v122
	v_fmac_f32_e32 v59, v8, v8
	v_fmac_f32_e32 v41, v8, v243
	v_fmac_f32_e32 v42, v8, v227
	v_fmac_f32_e32 v43, v8, v211
	v_fmac_f32_e32 v44, v8, v195
	v_fmac_f32_e32 v45, v8, v177
	v_fmac_f32_e32 v46, v8, v157
	v_fmac_f32_e32 v47, v8, v141
	v_fmac_f32_e32 v48, v8, v123
	v_fmac_f32_e32 v59, v9, v9
	v_fmac_f32_e32 v41, v9, v236
	v_fmac_f32_e32 v42, v9, v220
	v_fmac_f32_e32 v43, v9, v204
	v_fmac_f32_e32 v44, v9, v188
	v_fmac_f32_e32 v45, v9, v170
	v_fmac_f32_e32 v46, v9, v150
	v_fmac_f32_e32 v47, v9, v134
	v_fmac_f32_e32 v48, v9, v116
	v_fmac_f32_e32 v59, v10, v10
	v_fmac_f32_e32 v41, v10, v237
	v_fmac_f32_e32 v42, v10, v221
	v_fmac_f32_e32 v43, v10, v205
	v_fmac_f32_e32 v44, v10, v189
	v_fmac_f32_e32 v45, v10, v171
	v_fmac_f32_e32 v46, v10, v151
	v_fmac_f32_e32 v47, v10, v135
	v_fmac_f32_e32 v48, v10, v117
	v_fmac_f32_e32 v59, v11, v11
	v_fmac_f32_e32 v41, v11, v238
	v_fmac_f32_e32 v42, v11, v222
	v_fmac_f32_e32 v43, v11, v206
	v_fmac_f32_e32 v44, v11, v190
	v_fmac_f32_e32 v45, v11, v172
	v_fmac_f32_e32 v46, v11, v152
	v_fmac_f32_e32 v47, v11, v136
	v_fmac_f32_e32 v48, v11, v118
	v_fmac_f32_e32 v59, v12, v12
	v_fmac_f32_e32 v41, v12, v239
	v_fmac_f32_e32 v42, v12, v223
	v_fmac_f32_e32 v43, v12, v207
	v_fmac_f32_e32 v44, v12, v191
	v_fmac_f32_e32 v45, v12, v173
	v_fmac_f32_e32 v46, v12, v153
	v_fmac_f32_e32 v47, v12, v137
	v_fmac_f32_e32 v48, v12, v119
	v_lshlrev_b32_e32 v97, 16, v76
	v_and_b32_e32 v159, s40, v76
	v_lshlrev_b32_e32 v187, 16, v77
	v_and_b32_e32 v0, s40, v77
	v_lshlrev_b32_e32 v1, 16, v78
	v_and_b32_e32 v2, s40, v78
	v_lshlrev_b32_e32 v3, 16, v79
	v_and_b32_e32 v4, s40, v79
	v_lshlrev_b32_e32 v5, 16, v72
	v_and_b32_e32 v6, s40, v72
	v_lshlrev_b32_e32 v7, 16, v73
	v_and_b32_e32 v8, s40, v73
	v_lshlrev_b32_e32 v9, 16, v74
	v_and_b32_e32 v10, s40, v74
	v_lshlrev_b32_e32 v11, 16, v75
	v_and_b32_e32 v12, s40, v75
	v_mul_f32_e32 v60, v97, v97
	v_mul_f32_e32 v49, v97, v248
	v_mul_f32_e32 v50, v97, v232
	v_mul_f32_e32 v51, v97, v216
	v_mul_f32_e32 v52, v97, v200
	v_mul_f32_e32 v53, v97, v182
	v_mul_f32_e32 v54, v97, v166
	v_mul_f32_e32 v55, v97, v146
	v_mul_f32_e32 v56, v97, v130
	v_fmac_f32_e32 v60, v159, v159
	v_fmac_f32_e32 v49, v159, v249
	v_fmac_f32_e32 v50, v159, v233
	v_fmac_f32_e32 v51, v159, v217
	v_fmac_f32_e32 v52, v159, v201
	v_fmac_f32_e32 v53, v159, v183
	v_fmac_f32_e32 v54, v159, v167
	v_fmac_f32_e32 v55, v159, v147
	v_fmac_f32_e32 v56, v159, v131
	v_fmac_f32_e32 v60, v187, v187
	v_fmac_f32_e32 v49, v187, v250
	v_fmac_f32_e32 v50, v187, v234
	v_fmac_f32_e32 v51, v187, v218
	v_fmac_f32_e32 v52, v187, v202
	v_fmac_f32_e32 v53, v187, v184
	v_fmac_f32_e32 v54, v187, v168
	v_fmac_f32_e32 v55, v187, v148
	v_fmac_f32_e32 v56, v187, v132
	v_fmac_f32_e32 v60, v0, v0
	v_fmac_f32_e32 v49, v0, v251
	v_fmac_f32_e32 v50, v0, v235
	v_fmac_f32_e32 v51, v0, v219
	v_fmac_f32_e32 v52, v0, v203
	v_fmac_f32_e32 v53, v0, v185
	v_fmac_f32_e32 v54, v0, v169
	v_fmac_f32_e32 v55, v0, v149
	v_fmac_f32_e32 v56, v0, v133
	v_fmac_f32_e32 v60, v1, v1
	v_fmac_f32_e32 v49, v1, v244
	v_fmac_f32_e32 v50, v1, v228
	v_fmac_f32_e32 v51, v1, v212
	v_fmac_f32_e32 v52, v1, v196
	v_fmac_f32_e32 v53, v1, v178
	v_fmac_f32_e32 v54, v1, v162
	v_fmac_f32_e32 v55, v1, v142
	v_fmac_f32_e32 v56, v1, v124
	v_fmac_f32_e32 v60, v2, v2
	v_fmac_f32_e32 v49, v2, v245
	v_fmac_f32_e32 v50, v2, v229
	v_fmac_f32_e32 v51, v2, v213
	v_fmac_f32_e32 v52, v2, v197
	v_fmac_f32_e32 v53, v2, v179
	v_fmac_f32_e32 v54, v2, v163
	v_fmac_f32_e32 v55, v2, v143
	v_fmac_f32_e32 v56, v2, v125
	v_fmac_f32_e32 v60, v3, v3
	v_fmac_f32_e32 v49, v3, v246
	v_fmac_f32_e32 v50, v3, v230
	v_fmac_f32_e32 v51, v3, v214
	v_fmac_f32_e32 v52, v3, v198
	v_fmac_f32_e32 v53, v3, v180
	v_fmac_f32_e32 v54, v3, v164
	v_fmac_f32_e32 v55, v3, v144
	v_fmac_f32_e32 v56, v3, v126
; __device__ __forceinline__ float lane_get(float v, int src_lane) { return __builtin_bit_cast(float, __builtin_amdgcn_ds_bpermute(src_lane << 2, __builtin_bit_cast(int, v))); }
; __device__ __forceinline__ void fgate_phase(const bfr* x, const float* wf, const float* bfg, float* cl, float* ctot, LAS float* scr, int bx, int G, int tid, int lane, int wave) {
;     ...
;                 for (int jj = 0; jj < 4; ++jj) { const f32x4 w = wr[64 * jj]; da += (va[jj].x * w.x + va[jj].y * w.y) + (va[jj].z * w.z + va[jj].w * w.w); db += (vb[jj].x * w.x + vb[jj].y * w.y) + (vb[jj].z * w.z + vb[jj].w * w.w); }
;                 r[h] = da; r[8 + h] = db; }
; #pragma unroll
;             for (int o = 1; o < 64; o <<= 1) {
; #pragma unroll
;                 for (int q = 0; q < 18; ++q) r[q] += lane_get(r[q], lane ^ o); }
	v_fmac_f32_e32 v60, v4, v4
	v_fmac_f32_e32 v49, v4, v247
	v_fmac_f32_e32 v50, v4, v231
	v_fmac_f32_e32 v51, v4, v215
	v_fmac_f32_e32 v52, v4, v199
	v_fmac_f32_e32 v53, v4, v181
	v_fmac_f32_e32 v54, v4, v165
	v_fmac_f32_e32 v55, v4, v145
	v_fmac_f32_e32 v56, v4, v127
	v_fmac_f32_e32 v60, v5, v5
	v_fmac_f32_e32 v49, v5, v240
	v_fmac_f32_e32 v50, v5, v224
	v_fmac_f32_e32 v51, v5, v208
	v_fmac_f32_e32 v52, v5, v192
	v_fmac_f32_e32 v53, v5, v174
	v_fmac_f32_e32 v54, v5, v154
	v_fmac_f32_e32 v55, v5, v138
	v_fmac_f32_e32 v56, v5, v120
	v_fmac_f32_e32 v60, v6, v6
	v_fmac_f32_e32 v49, v6, v241
	v_fmac_f32_e32 v50, v6, v225
	v_fmac_f32_e32 v51, v6, v209
	v_fmac_f32_e32 v52, v6, v193
	v_fmac_f32_e32 v53, v6, v175
	v_fmac_f32_e32 v54, v6, v155
	v_fmac_f32_e32 v55, v6, v139
	v_fmac_f32_e32 v56, v6, v121
	v_fmac_f32_e32 v60, v7, v7
	v_fmac_f32_e32 v49, v7, v242
	v_fmac_f32_e32 v50, v7, v226
	v_fmac_f32_e32 v51, v7, v210
	v_fmac_f32_e32 v52, v7, v194
	v_fmac_f32_e32 v53, v7, v176
	v_fmac_f32_e32 v54, v7, v156
	v_fmac_f32_e32 v55, v7, v140
	v_fmac_f32_e32 v56, v7, v122
	v_fmac_f32_e32 v60, v8, v8
	v_fmac_f32_e32 v49, v8, v243
	v_fmac_f32_e32 v50, v8, v227
	v_fmac_f32_e32 v51, v8, v211
	v_fmac_f32_e32 v52, v8, v195
	v_fmac_f32_e32 v53, v8, v177
	v_fmac_f32_e32 v54, v8, v157
	v_fmac_f32_e32 v55, v8, v141
	v_fmac_f32_e32 v56, v8, v123
	v_fmac_f32_e32 v60, v9, v9
	v_fmac_f32_e32 v49, v9, v236
	v_fmac_f32_e32 v50, v9, v220
	v_fmac_f32_e32 v51, v9, v204
	v_fmac_f32_e32 v52, v9, v188
	v_fmac_f32_e32 v53, v9, v170
	v_fmac_f32_e32 v54, v9, v150
	v_fmac_f32_e32 v55, v9, v134
	v_fmac_f32_e32 v56, v9, v116
	v_fmac_f32_e32 v60, v10, v10
	v_fmac_f32_e32 v49, v10, v237
	v_fmac_f32_e32 v50, v10, v221
	v_fmac_f32_e32 v51, v10, v205
	v_fmac_f32_e32 v52, v10, v189
	v_fmac_f32_e32 v53, v10, v171
	v_fmac_f32_e32 v54, v10, v151
	v_fmac_f32_e32 v55, v10, v135
	v_fmac_f32_e32 v56, v10, v117
	v_fmac_f32_e32 v60, v11, v11
	v_fmac_f32_e32 v49, v11, v238
	v_fmac_f32_e32 v50, v11, v222
	v_fmac_f32_e32 v51, v11, v206
	v_fmac_f32_e32 v52, v11, v190
	v_fmac_f32_e32 v53, v11, v172
	v_fmac_f32_e32 v54, v11, v152
	v_fmac_f32_e32 v55, v11, v136
	v_fmac_f32_e32 v56, v11, v118
	v_fmac_f32_e32 v60, v12, v12
	v_fmac_f32_e32 v49, v12, v239
	v_fmac_f32_e32 v50, v12, v223
	v_fmac_f32_e32 v51, v12, v207
	v_fmac_f32_e32 v52, v12, v191
	v_fmac_f32_e32 v53, v12, v173
	v_fmac_f32_e32 v54, v12, v153
	v_fmac_f32_e32 v55, v12, v137
	v_fmac_f32_e32 v56, v12, v119
	s_nop 1
	v_permlane32_swap_b32_e32 v13, v41
	v_permlane32_swap_b32_e32 v14, v42
	v_permlane32_swap_b32_e32 v15, v43
	v_permlane32_swap_b32_e32 v16, v44
	v_permlane32_swap_b32_e32 v17, v45
	v_permlane32_swap_b32_e32 v18, v46
	v_permlane32_swap_b32_e32 v19, v47
	v_permlane32_swap_b32_e32 v20, v48
	v_permlane32_swap_b32_e32 v21, v49
	v_permlane32_swap_b32_e32 v22, v50
	v_permlane32_swap_b32_e32 v23, v51
	v_permlane32_swap_b32_e32 v24, v52
	v_permlane32_swap_b32_e32 v25, v53
	v_permlane32_swap_b32_e32 v26, v54
	v_permlane32_swap_b32_e32 v27, v55
	v_permlane32_swap_b32_e32 v40, v56
	v_permlane32_swap_b32_e32 v57, v59
	v_permlane32_swap_b32_e32 v58, v60
	s_nop 1
	v_add_f32_e32 v13, v13, v41
	v_add_f32_e32 v14, v14, v42
	v_add_f32_e32 v15, v15, v43
	v_add_f32_e32 v16, v16, v44
	v_add_f32_e32 v17, v17, v45
	v_add_f32_e32 v18, v18, v46
	v_add_f32_e32 v19, v19, v47
	v_add_f32_e32 v20, v20, v48
	v_add_f32_e32 v21, v21, v49
	v_add_f32_e32 v22, v22, v50
	v_add_f32_e32 v23, v23, v51
	v_add_f32_e32 v24, v24, v52
	v_add_f32_e32 v25, v25, v53
	v_add_f32_e32 v26, v26, v54
	v_add_f32_e32 v27, v27, v55
	v_add_f32_e32 v40, v40, v56
	v_add_f32_e32 v57, v57, v59
	v_add_f32_e32 v58, v58, v60
	s_nop 1
	v_permlane16_swap_b32_e32 v13, v21
	v_permlane16_swap_b32_e32 v14, v22
	v_permlane16_swap_b32_e32 v15, v23
	v_permlane16_swap_b32_e32 v16, v24
	v_permlane16_swap_b32_e32 v17, v25
	v_permlane16_swap_b32_e32 v18, v26
; __device__ __forceinline__ float lane_get(float v, int src_lane) { return __builtin_bit_cast(float, __builtin_amdgcn_ds_bpermute(src_lane << 2, __builtin_bit_cast(int, v))); }
; __device__ __forceinline__ void fgate_phase(const bfr* x, const float* wf, const float* bfg, float* cl, float* ctot, LAS float* scr, int bx, int G, int tid, int lane, int wave) {
;     ...
;             for (int o = 1; o < 64; o <<= 1) {
; #pragma unroll
;                 for (int q = 0; q < 18; ++q) r[q] += lane_get(r[q], lane ^ o); }
;             const float rsa = rsqrtf(r[16] * (1.f / D) + EPS), rsb = rsqrtf(r[17] * (1.f / D) + EPS);
;             if (lane < 16) { const int h = lane & 7; float dsel = r[0];
; #pragma unroll
;                 for (int q = 1; q < 16; ++q) dsel = (lane == q) ? r[q] : dsel;
;                 const float zz = dsel * (lane < 8 ? rsa : rsb) + bfg[h]; const float lf = fminf(zz, 0.f) - 0.6931471805599453f * __builtin_amdgcn_logf(1.0f + __builtin_amdgcn_exp2f(-LOG2E * fabsf(zz)));
;                 scr[(wave * 8 + j + (lane >> 3)) * 8 + h] = lf; } }
	v_permlane16_swap_b32_e32 v19, v27
	v_permlane16_swap_b32_e32 v20, v40
	v_permlane16_swap_b32_e32 v57, v58
	s_nop 1
	v_add_f32_e32 v13, v13, v21
	v_add_f32_e32 v14, v14, v22
	v_add_f32_e32 v15, v15, v23
	v_add_f32_e32 v16, v16, v24
	v_add_f32_e32 v17, v17, v25
	v_add_f32_e32 v18, v18, v26
	v_add_f32_e32 v19, v19, v27
	v_add_f32_e32 v20, v20, v40
	v_add_f32_e32 v57, v57, v58
	s_nop 1
	v_add_f32_dpp v13, v13, v13 quad_perm:[1,0,3,2] row_mask:0xf bank_mask:0xf
	v_add_f32_dpp v14, v14, v14 quad_perm:[1,0,3,2] row_mask:0xf bank_mask:0xf
	v_add_f32_dpp v15, v15, v15 quad_perm:[1,0,3,2] row_mask:0xf bank_mask:0xf
	v_add_f32_dpp v16, v16, v16 quad_perm:[1,0,3,2] row_mask:0xf bank_mask:0xf
	v_add_f32_dpp v17, v17, v17 quad_perm:[1,0,3,2] row_mask:0xf bank_mask:0xf
	v_add_f32_dpp v18, v18, v18 quad_perm:[1,0,3,2] row_mask:0xf bank_mask:0xf
	v_add_f32_dpp v19, v19, v19 quad_perm:[1,0,3,2] row_mask:0xf bank_mask:0xf
	v_add_f32_dpp v20, v20, v20 quad_perm:[1,0,3,2] row_mask:0xf bank_mask:0xf
	v_add_f32_dpp v57, v57, v57 quad_perm:[1,0,3,2] row_mask:0xf bank_mask:0xf
	s_nop 1
	v_add_f32_dpp v13, v13, v13 quad_perm:[2,3,0,1] row_mask:0xf bank_mask:0xf
	v_add_f32_dpp v14, v14, v14 quad_perm:[2,3,0,1] row_mask:0xf bank_mask:0xf
	v_add_f32_dpp v15, v15, v15 quad_perm:[2,3,0,1] row_mask:0xf bank_mask:0xf
	v_add_f32_dpp v16, v16, v16 quad_perm:[2,3,0,1] row_mask:0xf bank_mask:0xf
	v_add_f32_dpp v17, v17, v17 quad_perm:[2,3,0,1] row_mask:0xf bank_mask:0xf
	v_add_f32_dpp v18, v18, v18 quad_perm:[2,3,0,1] row_mask:0xf bank_mask:0xf
	v_add_f32_dpp v19, v19, v19 quad_perm:[2,3,0,1] row_mask:0xf bank_mask:0xf
	v_add_f32_dpp v20, v20, v20 quad_perm:[2,3,0,1] row_mask:0xf bank_mask:0xf
	v_add_f32_dpp v57, v57, v57 quad_perm:[2,3,0,1] row_mask:0xf bank_mask:0xf
	s_nop 1
	v_add_f32_dpp v13, v13, v13 row_half_mirror row_mask:0xf bank_mask:0xf
	v_add_f32_dpp v14, v14, v14 row_half_mirror row_mask:0xf bank_mask:0xf
	v_add_f32_dpp v15, v15, v15 row_half_mirror row_mask:0xf bank_mask:0xf
	v_add_f32_dpp v16, v16, v16 row_half_mirror row_mask:0xf bank_mask:0xf
	v_add_f32_dpp v17, v17, v17 row_half_mirror row_mask:0xf bank_mask:0xf
	v_add_f32_dpp v18, v18, v18 row_half_mirror row_mask:0xf bank_mask:0xf
	v_add_f32_dpp v19, v19, v19 row_half_mirror row_mask:0xf bank_mask:0xf
	v_add_f32_dpp v20, v20, v20 row_half_mirror row_mask:0xf bank_mask:0xf
	v_add_f32_dpp v57, v57, v57 row_half_mirror row_mask:0xf bank_mask:0xf
	s_nop 1
	v_add_f32_dpp v13, v13, v13 row_mirror row_mask:0xf bank_mask:0xf
	v_add_f32_dpp v14, v14, v14 row_mirror row_mask:0xf bank_mask:0xf
	v_add_f32_dpp v15, v15, v15 row_mirror row_mask:0xf bank_mask:0xf
	v_add_f32_dpp v16, v16, v16 row_mirror row_mask:0xf bank_mask:0xf
	v_add_f32_dpp v17, v17, v17 row_mirror row_mask:0xf bank_mask:0xf
	v_add_f32_dpp v18, v18, v18 row_mirror row_mask:0xf bank_mask:0xf
	v_add_f32_dpp v19, v19, v19 row_mirror row_mask:0xf bank_mask:0xf
	v_add_f32_dpp v20, v20, v20 row_mirror row_mask:0xf bank_mask:0xf
	v_add_f32_dpp v57, v57, v57 row_mirror row_mask:0xf bank_mask:0xf
	s_nop 1
	v_mov_b32_e32 v62, v13
	v_cndmask_b32_e64 v62, v62, v14, s[6:7]
	v_cndmask_b32_e64 v62, v62, v15, s[8:9]
	v_cndmask_b32_e64 v62, v62, v16, s[10:11]
	v_cndmask_b32_e64 v62, v62, v17, s[12:13]
	v_cndmask_b32_e64 v62, v62, v18, s[14:15]
	v_cndmask_b32_e64 v62, v62, v19, s[16:17]
	v_cndmask_b32_e64 v62, v62, v20, s[18:19]
	v_mul_f32_e32 v63, 0x3a800000, v57
	v_add_f32_e32 v63, 0x358637bd, v63
	v_rsq_f32_e32 v63, v63
	s_nop 0
	v_fma_f32 v62, v62, v63, v61
	v_mul_f32_e64 v63, |v62|, s65
	v_exp_f32_e32 v63, v63
	v_min_f32_e32 v62, 0, v62
	v_add_f32_e32 v63, 1.0, v63
	v_log_f32_e32 v63, v63
	s_nop 0
	v_fmac_f32_e32 v62, 0xbf317218, v63
	s_mov_b64 s[54:55], exec
	s_mov_b32 exec_lo, 0xff00ff
	s_mov_b32 exec_hi, 0xff00ff
	ds_write_b32 v65, v62 offset:128
	s_mov_b64 exec, s[54:55]

; __device__ __forceinline__ void fgate_phase(const bfr* x, const float* wf, const float* bfg, float* cl, float* ctot, LAS float* scr, int bx, int G, int tid, int lane, int wave) {
;     ...
;         for (int j = 0; j < 8; j += 2) { const int row = chunk * 64 + wave * 8 + j; typedef unsigned u32x2 __attribute__((ext_vector_type(2))); const u32x2* xa = (const u32x2*)(x + (size_t)row * D) + lane; const u32x2* xb2 = xa + D / 4; f32x4 va[4], vb[4]; float r[18]; int zo = 0; asm volatile("" : "+v"(zo));
; #pragma unroll
;             for (int jj = 0; jj < 4; ++jj) { const u32x2 wa = xa[64 * jj], wb = xb2[64 * jj]; va[jj] = (f32x4){bf_lo(wa.x), bf_hi(wa.x), bf_lo(wa.y), bf_hi(wa.y)}; vb[jj] = (f32x4){bf_lo(wb.x), bf_hi(wb.x), bf_lo(wb.y), bf_hi(wb.y)}; }
;             r[16] = 0.f; r[17] = 0.f;
; #pragma unroll
;             for (int jj = 0; jj < 4; ++jj) { r[16] += (va[jj].x * va[jj].x + va[jj].y * va[jj].y) + (va[jj].z * va[jj].z + va[jj].w * va[jj].w); r[17] += (vb[jj].x * vb[jj].x + vb[jj].y * vb[jj].y) + (vb[jj].z * vb[jj].z + vb[jj].w * vb[jj].w); }
; #pragma unroll
;             for (int h = 0; h < NH; ++h) { const f32x4* wr = (const f32x4*)(wf + h * D) + lane + zo; float da = 0.f, db = 0.f;
; #pragma unroll
;                 for (int jj = 0; jj < 4; ++jj) { const f32x4 w = wr[64 * jj]; da += (va[jj].x * w.x + va[jj].y * w.y) + (va[jj].z * w.z + va[jj].w * w.w); db += (vb[jj].x * w.x + vb[jj].y * w.y) + (vb[jj].z * w.z + vb[jj].w * w.w); }
;                 r[h] = da; r[8 + h] = db; }
.LBB0_1459:
	s_mov_b32 s38, s33
	s_ashr_i32 s39, s33, 31
	s_lshl_b64 s[38:39], s[38:39], 11
	s_mov_b64 s[98:99], 0x1000
	s_mov_b64 s[100:101], 0x2000
	v_lshl_add_u64 v[38:39], v[28:29], 0, s[38:39]
	v_mov_b32_e32 v160, v158
	v_mov_b32_e32 v161, 0
	v_lshl_add_u64 v[38:39], v[160:161], 3, v[38:39]
	v_lshl_add_u64 v[98:99], v[38:39], 0, s[98:99]
	global_load_dwordx4 v[112:115], v[38:39], off
	global_load_dwordx4 v[108:111], v[38:39], off offset:1024
	global_load_dwordx4 v[104:107], v[38:39], off offset:2048
	global_load_dwordx4 v[100:103], v[38:39], off offset:3072
	global_load_dwordx4 v[84:87], v[98:99], off
	global_load_dwordx4 v[80:83], v[98:99], off offset:1024
	global_load_dwordx4 v[76:79], v[98:99], off offset:2048
	global_load_dwordx4 v[72:75], v[98:99], off offset:3072
	global_load_dword v61, v[32:33], off offset:32
	v_lshrrev_b32_e32 v62, 6, v128
	v_lshlrev_b32_e32 v63, 4, v158
	v_readfirstlane_b32 s20, v30
	v_readfirstlane_b32 s21, v31
	v_readfirstlane_b32 s66, v62
	s_lshl_b32 s66, s66, 12
	s_add_u32 s20, s20, s66
	s_addc_u32 s21, s21, 0
	s_add_i32 s66, s66, 0x1000
	s_mov_b32 m0, s66
	s_nop 0
	global_load_lds_dwordx4 v63, s[20:21]
	s_add_u32 s20, s20, 0x400
	s_addc_u32 s21, s21, 0
	s_add_i32 s66, s66, 0x400
	s_mov_b32 m0, s66
	s_nop 0
	global_load_lds_dwordx4 v63, s[20:21]
	s_add_u32 s20, s20, 0x400
	s_addc_u32 s21, s21, 0
	s_add_i32 s66, s66, 0x400
	s_mov_b32 m0, s66
	s_nop 0
	global_load_lds_dwordx4 v63, s[20:21]
	s_add_u32 s20, s20, 0x400
	s_addc_u32 s21, s21, 0
	s_add_i32 s66, s66, 0x400
	s_mov_b32 m0, s66
	s_nop 0
	global_load_lds_dwordx4 v63, s[20:21]
	s_waitcnt vmcnt(0)
	s_barrier
	v_lshlrev_b32_e32 v63, 5, v158
	ds_read_b128 v[248:251], v63 offset:4096
	ds_read_b128 v[244:247], v63 offset:4112
	ds_read_b128 v[240:243], v63 offset:6144
	ds_read_b128 v[236:239], v63 offset:6160
	ds_read_b128 v[232:235], v63 offset:8192
	ds_read_b128 v[228:231], v63 offset:8208
	ds_read_b128 v[224:227], v63 offset:10240
	ds_read_b128 v[220:223], v63 offset:10256
	ds_read_b128 v[216:219], v63 offset:12288
	ds_read_b128 v[212:215], v63 offset:12304
	ds_read_b128 v[208:211], v63 offset:14336
	ds_read_b128 v[204:207], v63 offset:14352
	ds_read_b128 v[200:203], v63 offset:16384
	ds_read_b128 v[196:199], v63 offset:16400
	ds_read_b128 v[192:195], v63 offset:18432
	ds_read_b128 v[188:191], v63 offset:18448
	ds_read_b128 v[182:185], v63 offset:20480
	ds_read_b128 v[178:181], v63 offset:20496
	ds_read_b128 v[174:177], v63 offset:22528
	ds_read_b128 v[170:173], v63 offset:22544
	ds_read_b128 v[166:169], v63 offset:24576
	ds_read_b128 v[162:165], v63 offset:24592
	ds_read_b128 v[154:157], v63 offset:26624
	ds_read_b128 v[150:153], v63 offset:26640
	ds_read_b128 v[146:149], v63 offset:28672
	ds_read_b128 v[142:145], v63 offset:28688
	ds_read_b128 v[138:141], v63 offset:30720
	ds_read_b128 v[134:137], v63 offset:30736
	ds_read_b128 v[130:133], v63 offset:32768
	ds_read_b128 v[124:127], v63 offset:32784
	ds_read_b128 v[120:123], v63 offset:34816
	ds_read_b128 v[116:119], v63 offset:34832
	v_and_b32_e32 v64, 7, v158
	v_cmp_eq_u32_e64 s[6:7], 1, v64
	v_cmp_eq_u32_e64 s[8:9], 2, v64
	v_cmp_eq_u32_e64 s[10:11], 3, v64
	v_cmp_eq_u32_e64 s[12:13], 4, v64
	v_cmp_eq_u32_e64 s[14:15], 5, v64
	v_cmp_eq_u32_e64 s[16:17], 6, v64
	v_cmp_eq_u32_e64 s[18:19], 7, v64
	v_lshrrev_b32_e32 v62, 4, v158
	v_lshlrev_b32_e32 v62, 5, v62
	v_sub_u32_e32 v65, v95, v62
	s_mov_b32 s40, 0xffff0000
	s_waitcnt vmcnt(0) lgkmcnt(0)
	v_lshlrev_b32_e32 v97, 16, v112
	v_and_b32_e32 v159, s40, v112
	v_lshlrev_b32_e32 v187, 16, v113
	v_and_b32_e32 v0, s40, v113
	v_lshlrev_b32_e32 v1, 16, v114
	v_and_b32_e32 v2, s40, v114
	v_lshlrev_b32_e32 v3, 16, v115
	v_and_b32_e32 v4, s40, v115
	v_lshlrev_b32_e32 v5, 16, v108
	v_and_b32_e32 v6, s40, v108
	v_lshlrev_b32_e32 v7, 16, v109
	v_and_b32_e32 v8, s40, v109
	v_lshlrev_b32_e32 v9, 16, v110
	v_and_b32_e32 v10, s40, v110
	v_lshlrev_b32_e32 v11, 16, v111
	v_and_b32_e32 v12, s40, v111
	v_lshl_add_u64 v[38:39], v[38:39], 0, s[100:101]
	v_lshl_add_u64 v[98:99], v[98:99], 0, s[100:101]
	global_load_dwordx4 v[112:115], v[38:39], off
	global_load_dwordx4 v[108:111], v[38:39], off offset:1024
	v_mul_f32_e32 v57, v97, v97
	v_mul_f32_e32 v13, v97, v248
	v_mul_f32_e32 v14, v97, v232
	v_mul_f32_e32 v15, v97, v216
	v_mul_f32_e32 v16, v97, v200
	v_mul_f32_e32 v17, v97, v182
	v_mul_f32_e32 v18, v97, v166
	v_mul_f32_e32 v19, v97, v146
	v_mul_f32_e32 v20, v97, v130
	v_fmac_f32_e32 v57, v159, v159
	v_fmac_f32_e32 v13, v159, v249
	v_fmac_f32_e32 v14, v159, v233
	v_fmac_f32_e32 v15, v159, v217
	v_fmac_f32_e32 v16, v159, v201
	v_fmac_f32_e32 v17, v159, v183
	v_fmac_f32_e32 v18, v159, v167
	v_fmac_f32_e32 v19, v159, v147
	v_fmac_f32_e32 v20, v159, v131
	v_fmac_f32_e32 v57, v187, v187
	v_fmac_f32_e32 v13, v187, v250
	v_fmac_f32_e32 v14, v187, v234
	v_fmac_f32_e32 v15, v187, v218
	v_fmac_f32_e32 v16, v187, v202
	v_fmac_f32_e32 v17, v187, v184
	v_fmac_f32_e32 v18, v187, v168
	v_fmac_f32_e32 v19, v187, v148
	v_fmac_f32_e32 v20, v187, v132
	v_fmac_f32_e32 v57, v0, v0
	v_fmac_f32_e32 v13, v0, v251
	v_fmac_f32_e32 v14, v0, v235
	v_fmac_f32_e32 v15, v0, v219
	v_fmac_f32_e32 v16, v0, v203
	v_fmac_f32_e32 v17, v0, v185
	v_fmac_f32_e32 v18, v0, v169
	v_fmac_f32_e32 v19, v0, v149
	v_fmac_f32_e32 v20, v0, v133
	v_fmac_f32_e32 v57, v1, v1
	v_fmac_f32_e32 v13, v1, v244
	v_fmac_f32_e32 v14, v1, v228
	v_fmac_f32_e32 v15, v1, v212
	v_fmac_f32_e32 v16, v1, v196
	v_fmac_f32_e32 v17, v1, v178
	v_fmac_f32_e32 v18, v1, v162
	v_fmac_f32_e32 v19, v1, v142
	v_fmac_f32_e32 v20, v1, v124
	v_fmac_f32_e32 v57, v2, v2
	v_fmac_f32_e32 v13, v2, v245
	v_fmac_f32_e32 v14, v2, v229
	v_fmac_f32_e32 v15, v2, v213
; __device__ __forceinline__ void fgate_phase(const bfr* x, const float* wf, const float* bfg, float* cl, float* ctot, LAS float* scr, int bx, int G, int tid, int lane, int wave) {
;     ...
;             for (int jj = 0; jj < 4; ++jj) { const u32x2 wa = xa[64 * jj], wb = xb2[64 * jj]; va[jj] = (f32x4){bf_lo(wa.x), bf_hi(wa.x), bf_lo(wa.y), bf_hi(wa.y)}; vb[jj] = (f32x4){bf_lo(wb.x), bf_hi(wb.x), bf_lo(wb.y), bf_hi(wb.y)}; }
;             r[16] = 0.f; r[17] = 0.f;
; #pragma unroll
;             for (int jj = 0; jj < 4; ++jj) { r[16] += (va[jj].x * va[jj].x + va[jj].y * va[jj].y) + (va[jj].z * va[jj].z + va[jj].w * va[jj].w); r[17] += (vb[jj].x * vb[jj].x + vb[jj].y * vb[jj].y) + (vb[jj].z * vb[jj].z + vb[jj].w * vb[jj].w); }
; #pragma unroll
;             for (int h = 0; h < NH; ++h) { const f32x4* wr = (const f32x4*)(wf + h * D) + lane + zo; float da = 0.f, db = 0.f;
; #pragma unroll
;                 for (int jj = 0; jj < 4; ++jj) { const f32x4 w = wr[64 * jj]; da += (va[jj].x * w.x + va[jj].y * w.y) + (va[jj].z * w.z + va[jj].w * w.w); db += (vb[jj].x * w.x + vb[jj].y * w.y) + (vb[jj].z * w.z + vb[jj].w * w.w); }
;                 r[h] = da; r[8 + h] = db; }
	v_fmac_f32_e32 v16, v2, v197
	v_fmac_f32_e32 v17, v2, v179
	v_fmac_f32_e32 v18, v2, v163
	v_fmac_f32_e32 v19, v2, v143
	v_fmac_f32_e32 v20, v2, v125
	v_fmac_f32_e32 v57, v3, v3
	v_fmac_f32_e32 v13, v3, v246
	v_fmac_f32_e32 v14, v3, v230
	v_fmac_f32_e32 v15, v3, v214
	v_fmac_f32_e32 v16, v3, v198
	v_fmac_f32_e32 v17, v3, v180
	v_fmac_f32_e32 v18, v3, v164
	v_fmac_f32_e32 v19, v3, v144
	v_fmac_f32_e32 v20, v3, v126
	v_fmac_f32_e32 v57, v4, v4
	v_fmac_f32_e32 v13, v4, v247
	v_fmac_f32_e32 v14, v4, v231
	v_fmac_f32_e32 v15, v4, v215
	v_fmac_f32_e32 v16, v4, v199
	v_fmac_f32_e32 v17, v4, v181
	v_fmac_f32_e32 v18, v4, v165
	v_fmac_f32_e32 v19, v4, v145
	v_fmac_f32_e32 v20, v4, v127
	v_fmac_f32_e32 v57, v5, v5
	v_fmac_f32_e32 v13, v5, v240
	v_fmac_f32_e32 v14, v5, v224
	v_fmac_f32_e32 v15, v5, v208
	v_fmac_f32_e32 v16, v5, v192
	v_fmac_f32_e32 v17, v5, v174
	v_fmac_f32_e32 v18, v5, v154
	v_fmac_f32_e32 v19, v5, v138
	v_fmac_f32_e32 v20, v5, v120
	v_fmac_f32_e32 v57, v6, v6
	v_fmac_f32_e32 v13, v6, v241
	v_fmac_f32_e32 v14, v6, v225
	v_fmac_f32_e32 v15, v6, v209
	v_fmac_f32_e32 v16, v6, v193
	v_fmac_f32_e32 v17, v6, v175
	v_fmac_f32_e32 v18, v6, v155
	v_fmac_f32_e32 v19, v6, v139
	v_fmac_f32_e32 v20, v6, v121
	v_fmac_f32_e32 v57, v7, v7
	v_fmac_f32_e32 v13, v7, v242
	v_fmac_f32_e32 v14, v7, v226
	v_fmac_f32_e32 v15, v7, v210
	v_fmac_f32_e32 v16, v7, v194
	v_fmac_f32_e32 v17, v7, v176
	v_fmac_f32_e32 v18, v7, v156
	v_fmac_f32_e32 v19, v7, v140
	v_fmac_f32_e32 v20, v7, v122
	v_fmac_f32_e32 v57, v8, v8
	v_fmac_f32_e32 v13, v8, v243
	v_fmac_f32_e32 v14, v8, v227
	v_fmac_f32_e32 v15, v8, v211
	v_fmac_f32_e32 v16, v8, v195
	v_fmac_f32_e32 v17, v8, v177
	v_fmac_f32_e32 v18, v8, v157
	v_fmac_f32_e32 v19, v8, v141
	v_fmac_f32_e32 v20, v8, v123
	v_fmac_f32_e32 v57, v9, v9
	v_fmac_f32_e32 v13, v9, v236
	v_fmac_f32_e32 v14, v9, v220
	v_fmac_f32_e32 v15, v9, v204
	v_fmac_f32_e32 v16, v9, v188
	v_fmac_f32_e32 v17, v9, v170
	v_fmac_f32_e32 v18, v9, v150
	v_fmac_f32_e32 v19, v9, v134
	v_fmac_f32_e32 v20, v9, v116
	v_fmac_f32_e32 v57, v10, v10
	v_fmac_f32_e32 v13, v10, v237
	v_fmac_f32_e32 v14, v10, v221
	v_fmac_f32_e32 v15, v10, v205
	v_fmac_f32_e32 v16, v10, v189
	v_fmac_f32_e32 v17, v10, v171
	v_fmac_f32_e32 v18, v10, v151
	v_fmac_f32_e32 v19, v10, v135
	v_fmac_f32_e32 v20, v10, v117
	v_fmac_f32_e32 v57, v11, v11
	v_fmac_f32_e32 v13, v11, v238
	v_fmac_f32_e32 v14, v11, v222
	v_fmac_f32_e32 v15, v11, v206
	v_fmac_f32_e32 v16, v11, v190
	v_fmac_f32_e32 v17, v11, v172
	v_fmac_f32_e32 v18, v11, v152
	v_fmac_f32_e32 v19, v11, v136
	v_fmac_f32_e32 v20, v11, v118
	v_fmac_f32_e32 v57, v12, v12
	v_fmac_f32_e32 v13, v12, v239
	v_fmac_f32_e32 v14, v12, v223
	v_fmac_f32_e32 v15, v12, v207
	v_fmac_f32_e32 v16, v12, v191
	v_fmac_f32_e32 v17, v12, v173
	v_fmac_f32_e32 v18, v12, v153
	v_fmac_f32_e32 v19, v12, v137
	v_fmac_f32_e32 v20, v12, v119
	v_lshlrev_b32_e32 v97, 16, v104
	v_and_b32_e32 v159, s40, v104
	v_lshlrev_b32_e32 v187, 16, v105
	v_and_b32_e32 v0, s40, v105
	v_lshlrev_b32_e32 v1, 16, v106
	v_and_b32_e32 v2, s40, v106
	v_lshlrev_b32_e32 v3, 16, v107
	v_and_b32_e32 v4, s40, v107
	v_lshlrev_b32_e32 v5, 16, v100
	v_and_b32_e32 v6, s40, v100
	v_lshlrev_b32_e32 v7, 16, v101
	v_and_b32_e32 v8, s40, v101
	v_lshlrev_b32_e32 v9, 16, v102
	v_and_b32_e32 v10, s40, v102
	v_lshlrev_b32_e32 v11, 16, v103
	v_and_b32_e32 v12, s40, v103
	global_load_dwordx4 v[104:107], v[38:39], off offset:2048
	global_load_dwordx4 v[100:103], v[38:39], off offset:3072
	v_mul_f32_e32 v58, v97, v97
	v_mul_f32_e32 v21, v97, v248
	v_mul_f32_e32 v22, v97, v232
	v_mul_f32_e32 v23, v97, v216
	v_mul_f32_e32 v24, v97, v200
	v_mul_f32_e32 v25, v97, v182
	v_mul_f32_e32 v26, v97, v166
	v_mul_f32_e32 v27, v97, v146
	v_mul_f32_e32 v40, v97, v130
	v_fmac_f32_e32 v58, v159, v159
	v_fmac_f32_e32 v21, v159, v249
	v_fmac_f32_e32 v22, v159, v233
	v_fmac_f32_e32 v23, v159, v217
	v_fmac_f32_e32 v24, v159, v201
	v_fmac_f32_e32 v25, v159, v183
	v_fmac_f32_e32 v26, v159, v167
	v_fmac_f32_e32 v27, v159, v147
	v_fmac_f32_e32 v40, v159, v131
	v_fmac_f32_e32 v58, v187, v187
	v_fmac_f32_e32 v21, v187, v250
	v_fmac_f32_e32 v22, v187, v234
	v_fmac_f32_e32 v23, v187, v218
	v_fmac_f32_e32 v24, v187, v202
	v_fmac_f32_e32 v25, v187, v184
	v_fmac_f32_e32 v26, v187, v168
	v_fmac_f32_e32 v27, v187, v148
	v_fmac_f32_e32 v40, v187, v132
	v_fmac_f32_e32 v58, v0, v0
	v_fmac_f32_e32 v21, v0, v251
	v_fmac_f32_e32 v22, v0, v235
	v_fmac_f32_e32 v23, v0, v219
	v_fmac_f32_e32 v24, v0, v203
	v_fmac_f32_e32 v25, v0, v185
	v_fmac_f32_e32 v26, v0, v169
	v_fmac_f32_e32 v27, v0, v149
	v_fmac_f32_e32 v40, v0, v133
	v_fmac_f32_e32 v58, v1, v1
	v_fmac_f32_e32 v21, v1, v244
	v_fmac_f32_e32 v22, v1, v228
	v_fmac_f32_e32 v23, v1, v212
	v_fmac_f32_e32 v24, v1, v196
	v_fmac_f32_e32 v25, v1, v178
	v_fmac_f32_e32 v26, v1, v162
	v_fmac_f32_e32 v27, v1, v142
	v_fmac_f32_e32 v40, v1, v124
	v_fmac_f32_e32 v58, v2, v2
	v_fmac_f32_e32 v21, v2, v245
	v_fmac_f32_e32 v22, v2, v229
	v_fmac_f32_e32 v23, v2, v213
	v_fmac_f32_e32 v24, v2, v197
	v_fmac_f32_e32 v25, v2, v179
	v_fmac_f32_e32 v26, v2, v163
	v_fmac_f32_e32 v27, v2, v143
	v_fmac_f32_e32 v40, v2, v125
	v_fmac_f32_e32 v58, v3, v3
	v_fmac_f32_e32 v21, v3, v246
	v_fmac_f32_e32 v22, v3, v230
	v_fmac_f32_e32 v23, v3, v214
	v_fmac_f32_e32 v24, v3, v198
	v_fmac_f32_e32 v25, v3, v180
	v_fmac_f32_e32 v26, v3, v164
	v_fmac_f32_e32 v27, v3, v144
	v_fmac_f32_e32 v40, v3, v126
	v_fmac_f32_e32 v58, v4, v4
	v_fmac_f32_e32 v21, v4, v247
	v_fmac_f32_e32 v22, v4, v231
	v_fmac_f32_e32 v23, v4, v215
	v_fmac_f32_e32 v24, v4, v199
	v_fmac_f32_e32 v25, v4, v181
	v_fmac_f32_e32 v26, v4, v165
	v_fmac_f32_e32 v27, v4, v145
; __device__ __forceinline__ void fgate_phase(const bfr* x, const float* wf, const float* bfg, float* cl, float* ctot, LAS float* scr, int bx, int G, int tid, int lane, int wave) {
;     ...
;             for (int jj = 0; jj < 4; ++jj) { const u32x2 wa = xa[64 * jj], wb = xb2[64 * jj]; va[jj] = (f32x4){bf_lo(wa.x), bf_hi(wa.x), bf_lo(wa.y), bf_hi(wa.y)}; vb[jj] = (f32x4){bf_lo(wb.x), bf_hi(wb.x), bf_lo(wb.y), bf_hi(wb.y)}; }
;             r[16] = 0.f; r[17] = 0.f;
; #pragma unroll
;             for (int jj = 0; jj < 4; ++jj) { r[16] += (va[jj].x * va[jj].x + va[jj].y * va[jj].y) + (va[jj].z * va[jj].z + va[jj].w * va[jj].w); r[17] += (vb[jj].x * vb[jj].x + vb[jj].y * vb[jj].y) + (vb[jj].z * vb[jj].z + vb[jj].w * vb[jj].w); }
; #pragma unroll
;             for (int h = 0; h < NH; ++h) { const f32x4* wr = (const f32x4*)(wf + h * D) + lane + zo; float da = 0.f, db = 0.f;
; #pragma unroll
;                 for (int jj = 0; jj < 4; ++jj) { const f32x4 w = wr[64 * jj]; da += (va[jj].x * w.x + va[jj].y * w.y) + (va[jj].z * w.z + va[jj].w * w.w); db += (vb[jj].x * w.x + vb[jj].y * w.y) + (vb[jj].z * w.z + vb[jj].w * w.w); }
;                 r[h] = da; r[8 + h] = db; }
	v_fmac_f32_e32 v40, v4, v127
	v_fmac_f32_e32 v58, v5, v5
	v_fmac_f32_e32 v21, v5, v240
	v_fmac_f32_e32 v22, v5, v224
	v_fmac_f32_e32 v23, v5, v208
	v_fmac_f32_e32 v24, v5, v192
	v_fmac_f32_e32 v25, v5, v174
	v_fmac_f32_e32 v26, v5, v154
	v_fmac_f32_e32 v27, v5, v138
	v_fmac_f32_e32 v40, v5, v120
	v_fmac_f32_e32 v58, v6, v6
	v_fmac_f32_e32 v21, v6, v241
	v_fmac_f32_e32 v22, v6, v225
	v_fmac_f32_e32 v23, v6, v209
	v_fmac_f32_e32 v24, v6, v193
	v_fmac_f32_e32 v25, v6, v175
	v_fmac_f32_e32 v26, v6, v155
	v_fmac_f32_e32 v27, v6, v139
	v_fmac_f32_e32 v40, v6, v121
	v_fmac_f32_e32 v58, v7, v7
	v_fmac_f32_e32 v21, v7, v242
	v_fmac_f32_e32 v22, v7, v226
	v_fmac_f32_e32 v23, v7, v210
	v_fmac_f32_e32 v24, v7, v194
	v_fmac_f32_e32 v25, v7, v176
	v_fmac_f32_e32 v26, v7, v156
	v_fmac_f32_e32 v27, v7, v140
	v_fmac_f32_e32 v40, v7, v122
	v_fmac_f32_e32 v58, v8, v8
	v_fmac_f32_e32 v21, v8, v243
	v_fmac_f32_e32 v22, v8, v227
	v_fmac_f32_e32 v23, v8, v211
	v_fmac_f32_e32 v24, v8, v195
	v_fmac_f32_e32 v25, v8, v177
	v_fmac_f32_e32 v26, v8, v157
	v_fmac_f32_e32 v27, v8, v141
	v_fmac_f32_e32 v40, v8, v123
	v_fmac_f32_e32 v58, v9, v9
	v_fmac_f32_e32 v21, v9, v236
	v_fmac_f32_e32 v22, v9, v220
	v_fmac_f32_e32 v23, v9, v204
	v_fmac_f32_e32 v24, v9, v188
	v_fmac_f32_e32 v25, v9, v170
	v_fmac_f32_e32 v26, v9, v150
	v_fmac_f32_e32 v27, v9, v134
	v_fmac_f32_e32 v40, v9, v116
	v_fmac_f32_e32 v58, v10, v10
	v_fmac_f32_e32 v21, v10, v237
	v_fmac_f32_e32 v22, v10, v221
	v_fmac_f32_e32 v23, v10, v205
	v_fmac_f32_e32 v24, v10, v189
	v_fmac_f32_e32 v25, v10, v171
	v_fmac_f32_e32 v26, v10, v151
	v_fmac_f32_e32 v27, v10, v135
	v_fmac_f32_e32 v40, v10, v117
	v_fmac_f32_e32 v58, v11, v11
	v_fmac_f32_e32 v21, v11, v238
	v_fmac_f32_e32 v22, v11, v222
	v_fmac_f32_e32 v23, v11, v206
	v_fmac_f32_e32 v24, v11, v190
	v_fmac_f32_e32 v25, v11, v172
	v_fmac_f32_e32 v26, v11, v152
	v_fmac_f32_e32 v27, v11, v136
	v_fmac_f32_e32 v40, v11, v118
	v_fmac_f32_e32 v58, v12, v12
	v_fmac_f32_e32 v21, v12, v239
	v_fmac_f32_e32 v22, v12, v223
	v_fmac_f32_e32 v23, v12, v207
	v_fmac_f32_e32 v24, v12, v191
	v_fmac_f32_e32 v25, v12, v173
	v_fmac_f32_e32 v26, v12, v153
	v_fmac_f32_e32 v27, v12, v137
	v_fmac_f32_e32 v40, v12, v119
	v_lshlrev_b32_e32 v97, 16, v84
	v_and_b32_e32 v159, s40, v84
	v_lshlrev_b32_e32 v187, 16, v85
	v_and_b32_e32 v0, s40, v85
	v_lshlrev_b32_e32 v1, 16, v86
	v_and_b32_e32 v2, s40, v86
	v_lshlrev_b32_e32 v3, 16, v87
	v_and_b32_e32 v4, s40, v87
	v_lshlrev_b32_e32 v5, 16, v80
	v_and_b32_e32 v6, s40, v80
	v_lshlrev_b32_e32 v7, 16, v81
	v_and_b32_e32 v8, s40, v81
	v_lshlrev_b32_e32 v9, 16, v82
	v_and_b32_e32 v10, s40, v82
	v_lshlrev_b32_e32 v11, 16, v83
	v_and_b32_e32 v12, s40, v83
	global_load_dwordx4 v[84:87], v[98:99], off
	global_load_dwordx4 v[80:83], v[98:99], off offset:1024
	v_mul_f32_e32 v59, v97, v97
	v_mul_f32_e32 v41, v97, v248
	v_mul_f32_e32 v42, v97, v232
	v_mul_f32_e32 v43, v97, v216
	v_mul_f32_e32 v44, v97, v200
	v_mul_f32_e32 v45, v97, v182
	v_mul_f32_e32 v46, v97, v166
	v_mul_f32_e32 v47, v97, v146
	v_mul_f32_e32 v48, v97, v130
	v_fmac_f32_e32 v59, v159, v159
	v_fmac_f32_e32 v41, v159, v249
	v_fmac_f32_e32 v42, v159, v233
	v_fmac_f32_e32 v43, v159, v217
	v_fmac_f32_e32 v44, v159, v201
	v_fmac_f32_e32 v45, v159, v183
	v_fmac_f32_e32 v46, v159, v167
	v_fmac_f32_e32 v47, v159, v147
	v_fmac_f32_e32 v48, v159, v131
	v_fmac_f32_e32 v59, v187, v187
	v_fmac_f32_e32 v41, v187, v250
	v_fmac_f32_e32 v42, v187, v234
	v_fmac_f32_e32 v43, v187, v218
	v_fmac_f32_e32 v44, v187, v202
	v_fmac_f32_e32 v45, v187, v184
	v_fmac_f32_e32 v46, v187, v168
	v_fmac_f32_e32 v47, v187, v148
	v_fmac_f32_e32 v48, v187, v132
	v_fmac_f32_e32 v59, v0, v0
	v_fmac_f32_e32 v41, v0, v251
	v_fmac_f32_e32 v42, v0, v235
	v_fmac_f32_e32 v43, v0, v219
	v_fmac_f32_e32 v44, v0, v203
	v_fmac_f32_e32 v45, v0, v185
	v_fmac_f32_e32 v46, v0, v169
	v_fmac_f32_e32 v47, v0, v149
	v_fmac_f32_e32 v48, v0, v133
	v_fmac_f32_e32 v59, v1, v1
	v_fmac_f32_e32 v41, v1, v244
	v_fmac_f32_e32 v42, v1, v228
	v_fmac_f32_e32 v43, v1, v212
	v_fmac_f32_e32 v44, v1, v196
	v_fmac_f32_e32 v45, v1, v178
	v_fmac_f32_e32 v46, v1, v162
	v_fmac_f32_e32 v47, v1, v142
	v_fmac_f32_e32 v48, v1, v124
	v_fmac_f32_e32 v59, v2, v2
	v_fmac_f32_e32 v41, v2, v245
	v_fmac_f32_e32 v42, v2, v229
	v_fmac_f32_e32 v43, v2, v213
	v_fmac_f32_e32 v44, v2, v197
	v_fmac_f32_e32 v45, v2, v179
	v_fmac_f32_e32 v46, v2, v163
	v_fmac_f32_e32 v47, v2, v143
	v_fmac_f32_e32 v48, v2, v125
	v_fmac_f32_e32 v59, v3, v3
	v_fmac_f32_e32 v41, v3, v246
	v_fmac_f32_e32 v42, v3, v230
	v_fmac_f32_e32 v43, v3, v214
	v_fmac_f32_e32 v44, v3, v198
	v_fmac_f32_e32 v45, v3, v180
	v_fmac_f32_e32 v46, v3, v164
	v_fmac_f32_e32 v47, v3, v144
	v_fmac_f32_e32 v48, v3, v126
	v_fmac_f32_e32 v59, v4, v4
	v_fmac_f32_e32 v41, v4, v247
	v_fmac_f32_e32 v42, v4, v231
	v_fmac_f32_e32 v43, v4, v215
	v_fmac_f32_e32 v44, v4, v199
	v_fmac_f32_e32 v45, v4, v181
	v_fmac_f32_e32 v46, v4, v165
	v_fmac_f32_e32 v47, v4, v145
	v_fmac_f32_e32 v48, v4, v127
	v_fmac_f32_e32 v59, v5, v5
	v_fmac_f32_e32 v41, v5, v240
	v_fmac_f32_e32 v42, v5, v224
	v_fmac_f32_e32 v43, v5, v208
	v_fmac_f32_e32 v44, v5, v192
	v_fmac_f32_e32 v45, v5, v174
	v_fmac_f32_e32 v46, v5, v154
	v_fmac_f32_e32 v47, v5, v138
	v_fmac_f32_e32 v48, v5, v120
	v_fmac_f32_e32 v59, v6, v6
	v_fmac_f32_e32 v41, v6, v241
	v_fmac_f32_e32 v42, v6, v225
	v_fmac_f32_e32 v43, v6, v209
	v_fmac_f32_e32 v44, v6, v193
	v_fmac_f32_e32 v45, v6, v175
	v_fmac_f32_e32 v46, v6, v155
	v_fmac_f32_e32 v47, v6, v139
	v_fmac_f32_e32 v48, v6, v121
	v_fmac_f32_e32 v59, v7, v7
	v_fmac_f32_e32 v41, v7, v242
	v_fmac_f32_e32 v42, v7, v226
	v_fmac_f32_e32 v43, v7, v210
; __device__ __forceinline__ void fgate_phase(const bfr* x, const float* wf, const float* bfg, float* cl, float* ctot, LAS float* scr, int bx, int G, int tid, int lane, int wave) {
;     ...
;             for (int jj = 0; jj < 4; ++jj) { const u32x2 wa = xa[64 * jj], wb = xb2[64 * jj]; va[jj] = (f32x4){bf_lo(wa.x), bf_hi(wa.x), bf_lo(wa.y), bf_hi(wa.y)}; vb[jj] = (f32x4){bf_lo(wb.x), bf_hi(wb.x), bf_lo(wb.y), bf_hi(wb.y)}; }
;             r[16] = 0.f; r[17] = 0.f;
; #pragma unroll
;             for (int jj = 0; jj < 4; ++jj) { r[16] += (va[jj].x * va[jj].x + va[jj].y * va[jj].y) + (va[jj].z * va[jj].z + va[jj].w * va[jj].w); r[17] += (vb[jj].x * vb[jj].x + vb[jj].y * vb[jj].y) + (vb[jj].z * vb[jj].z + vb[jj].w * vb[jj].w); }
; #pragma unroll
;             for (int h = 0; h < NH; ++h) { const f32x4* wr = (const f32x4*)(wf + h * D) + lane + zo; float da = 0.f, db = 0.f;
; #pragma unroll
;                 for (int jj = 0; jj < 4; ++jj) { const f32x4 w = wr[64 * jj]; da += (va[jj].x * w.x + va[jj].y * w.y) + (va[jj].z * w.z + va[jj].w * w.w); db += (vb[jj].x * w.x + vb[jj].y * w.y) + (vb[jj].z * w.z + vb[jj].w * w.w); }
;                 r[h] = da; r[8 + h] = db; }
	v_fmac_f32_e32 v44, v7, v194
	v_fmac_f32_e32 v45, v7, v176
	v_fmac_f32_e32 v46, v7, v156
	v_fmac_f32_e32 v47, v7, v140
	v_fmac_f32_e32 v48, v7, v122
	v_fmac_f32_e32 v59, v8, v8
	v_fmac_f32_e32 v41, v8, v243
	v_fmac_f32_e32 v42, v8, v227
	v_fmac_f32_e32 v43, v8, v211
	v_fmac_f32_e32 v44, v8, v195
	v_fmac_f32_e32 v45, v8, v177
	v_fmac_f32_e32 v46, v8, v157
	v_fmac_f32_e32 v47, v8, v141
	v_fmac_f32_e32 v48, v8, v123
	v_fmac_f32_e32 v59, v9, v9
	v_fmac_f32_e32 v41, v9, v236
	v_fmac_f32_e32 v42, v9, v220
	v_fmac_f32_e32 v43, v9, v204
	v_fmac_f32_e32 v44, v9, v188
	v_fmac_f32_e32 v45, v9, v170
	v_fmac_f32_e32 v46, v9, v150
	v_fmac_f32_e32 v47, v9, v134
	v_fmac_f32_e32 v48, v9, v116
	v_fmac_f32_e32 v59, v10, v10
	v_fmac_f32_e32 v41, v10, v237
	v_fmac_f32_e32 v42, v10, v221
	v_fmac_f32_e32 v43, v10, v205
	v_fmac_f32_e32 v44, v10, v189
	v_fmac_f32_e32 v45, v10, v171
	v_fmac_f32_e32 v46, v10, v151
	v_fmac_f32_e32 v47, v10, v135
	v_fmac_f32_e32 v48, v10, v117
	v_fmac_f32_e32 v59, v11, v11
	v_fmac_f32_e32 v41, v11, v238
	v_fmac_f32_e32 v42, v11, v222
	v_fmac_f32_e32 v43, v11, v206
	v_fmac_f32_e32 v44, v11, v190
	v_fmac_f32_e32 v45, v11, v172
	v_fmac_f32_e32 v46, v11, v152
	v_fmac_f32_e32 v47, v11, v136
	v_fmac_f32_e32 v48, v11, v118
	v_fmac_f32_e32 v59, v12, v12
	v_fmac_f32_e32 v41, v12, v239
	v_fmac_f32_e32 v42, v12, v223
	v_fmac_f32_e32 v43, v12, v207
	v_fmac_f32_e32 v44, v12, v191
	v_fmac_f32_e32 v45, v12, v173
	v_fmac_f32_e32 v46, v12, v153
	v_fmac_f32_e32 v47, v12, v137
	v_fmac_f32_e32 v48, v12, v119
	v_lshlrev_b32_e32 v97, 16, v76
	v_and_b32_e32 v159, s40, v76
	v_lshlrev_b32_e32 v187, 16, v77
	v_and_b32_e32 v0, s40, v77
	v_lshlrev_b32_e32 v1, 16, v78
	v_and_b32_e32 v2, s40, v78
	v_lshlrev_b32_e32 v3, 16, v79
	v_and_b32_e32 v4, s40, v79
	v_lshlrev_b32_e32 v5, 16, v72
	v_and_b32_e32 v6, s40, v72
	v_lshlrev_b32_e32 v7, 16, v73
	v_and_b32_e32 v8, s40, v73
	v_lshlrev_b32_e32 v9, 16, v74
	v_and_b32_e32 v10, s40, v74
	v_lshlrev_b32_e32 v11, 16, v75
	v_and_b32_e32 v12, s40, v75
	global_load_dwordx4 v[76:79], v[98:99], off offset:2048
	global_load_dwordx4 v[72:75], v[98:99], off offset:3072
	v_mul_f32_e32 v60, v97, v97
	v_mul_f32_e32 v49, v97, v248
	v_mul_f32_e32 v50, v97, v232
	v_mul_f32_e32 v51, v97, v216
	v_mul_f32_e32 v52, v97, v200
	v_mul_f32_e32 v53, v97, v182
	v_mul_f32_e32 v54, v97, v166
	v_mul_f32_e32 v55, v97, v146
	v_mul_f32_e32 v56, v97, v130
	v_fmac_f32_e32 v60, v159, v159
	v_fmac_f32_e32 v49, v159, v249
	v_fmac_f32_e32 v50, v159, v233
	v_fmac_f32_e32 v51, v159, v217
	v_fmac_f32_e32 v52, v159, v201
	v_fmac_f32_e32 v53, v159, v183
	v_fmac_f32_e32 v54, v159, v167
	v_fmac_f32_e32 v55, v159, v147
	v_fmac_f32_e32 v56, v159, v131
	v_fmac_f32_e32 v60, v187, v187
	v_fmac_f32_e32 v49, v187, v250
	v_fmac_f32_e32 v50, v187, v234
	v_fmac_f32_e32 v51, v187, v218
	v_fmac_f32_e32 v52, v187, v202
	v_fmac_f32_e32 v53, v187, v184
	v_fmac_f32_e32 v54, v187, v168
	v_fmac_f32_e32 v55, v187, v148
	v_fmac_f32_e32 v56, v187, v132
	v_fmac_f32_e32 v60, v0, v0
	v_fmac_f32_e32 v49, v0, v251
	v_fmac_f32_e32 v50, v0, v235
	v_fmac_f32_e32 v51, v0, v219
	v_fmac_f32_e32 v52, v0, v203
	v_fmac_f32_e32 v53, v0, v185
	v_fmac_f32_e32 v54, v0, v169
	v_fmac_f32_e32 v55, v0, v149
	v_fmac_f32_e32 v56, v0, v133
	v_fmac_f32_e32 v60, v1, v1
	v_fmac_f32_e32 v49, v1, v244
	v_fmac_f32_e32 v50, v1, v228
	v_fmac_f32_e32 v51, v1, v212
	v_fmac_f32_e32 v52, v1, v196
	v_fmac_f32_e32 v53, v1, v178
	v_fmac_f32_e32 v54, v1, v162
	v_fmac_f32_e32 v55, v1, v142
	v_fmac_f32_e32 v56, v1, v124
	v_fmac_f32_e32 v60, v2, v2
	v_fmac_f32_e32 v49, v2, v245
	v_fmac_f32_e32 v50, v2, v229
	v_fmac_f32_e32 v51, v2, v213
	v_fmac_f32_e32 v52, v2, v197
	v_fmac_f32_e32 v53, v2, v179
	v_fmac_f32_e32 v54, v2, v163
	v_fmac_f32_e32 v55, v2, v143
	v_fmac_f32_e32 v56, v2, v125
	v_fmac_f32_e32 v60, v3, v3
	v_fmac_f32_e32 v49, v3, v246
	v_fmac_f32_e32 v50, v3, v230
	v_fmac_f32_e32 v51, v3, v214
	v_fmac_f32_e32 v52, v3, v198
	v_fmac_f32_e32 v53, v3, v180
	v_fmac_f32_e32 v54, v3, v164
	v_fmac_f32_e32 v55, v3, v144
	v_fmac_f32_e32 v56, v3, v126
	v_fmac_f32_e32 v60, v4, v4
	v_fmac_f32_e32 v49, v4, v247
	v_fmac_f32_e32 v50, v4, v231
	v_fmac_f32_e32 v51, v4, v215
	v_fmac_f32_e32 v52, v4, v199
	v_fmac_f32_e32 v53, v4, v181
	v_fmac_f32_e32 v54, v4, v165
	v_fmac_f32_e32 v55, v4, v145
	v_fmac_f32_e32 v56, v4, v127
	v_fmac_f32_e32 v60, v5, v5
	v_fmac_f32_e32 v49, v5, v240
	v_fmac_f32_e32 v50, v5, v224
	v_fmac_f32_e32 v51, v5, v208
	v_fmac_f32_e32 v52, v5, v192
	v_fmac_f32_e32 v53, v5, v174
	v_fmac_f32_e32 v54, v5, v154
	v_fmac_f32_e32 v55, v5, v138
	v_fmac_f32_e32 v56, v5, v120
	v_fmac_f32_e32 v60, v6, v6
	v_fmac_f32_e32 v49, v6, v241
	v_fmac_f32_e32 v50, v6, v225
	v_fmac_f32_e32 v51, v6, v209
	v_fmac_f32_e32 v52, v6, v193
	v_fmac_f32_e32 v53, v6, v175
	v_fmac_f32_e32 v54, v6, v155
	v_fmac_f32_e32 v55, v6, v139
	v_fmac_f32_e32 v56, v6, v121
	v_fmac_f32_e32 v60, v7, v7
	v_fmac_f32_e32 v49, v7, v242
	v_fmac_f32_e32 v50, v7, v226
	v_fmac_f32_e32 v51, v7, v210
	v_fmac_f32_e32 v52, v7, v194
	v_fmac_f32_e32 v53, v7, v176
	v_fmac_f32_e32 v54, v7, v156
	v_fmac_f32_e32 v55, v7, v140
	v_fmac_f32_e32 v56, v7, v122
	v_fmac_f32_e32 v60, v8, v8
	v_fmac_f32_e32 v49, v8, v243
	v_fmac_f32_e32 v50, v8, v227
	v_fmac_f32_e32 v51, v8, v211
	v_fmac_f32_e32 v52, v8, v195
	v_fmac_f32_e32 v53, v8, v177
	v_fmac_f32_e32 v54, v8, v157
	v_fmac_f32_e32 v55, v8, v141
	v_fmac_f32_e32 v56, v8, v123
	v_fmac_f32_e32 v60, v9, v9
	v_fmac_f32_e32 v49, v9, v236
	v_fmac_f32_e32 v50, v9, v220
	v_fmac_f32_e32 v51, v9, v204
	v_fmac_f32_e32 v52, v9, v188
	v_fmac_f32_e32 v53, v9, v170
	v_fmac_f32_e32 v54, v9, v150
	v_fmac_f32_e32 v55, v9, v134
	v_fmac_f32_e32 v56, v9, v116
; __device__ __forceinline__ float lane_get(float v, int src_lane) { return __builtin_bit_cast(float, __builtin_amdgcn_ds_bpermute(src_lane << 2, __builtin_bit_cast(int, v))); }
; __device__ __forceinline__ void fgate_phase(const bfr* x, const float* wf, const float* bfg, float* cl, float* ctot, LAS float* scr, int bx, int G, int tid, int lane, int wave) {
;     ...
;                 for (int jj = 0; jj < 4; ++jj) { const f32x4 w = wr[64 * jj]; da += (va[jj].x * w.x + va[jj].y * w.y) + (va[jj].z * w.z + va[jj].w * w.w); db += (vb[jj].x * w.x + vb[jj].y * w.y) + (vb[jj].z * w.z + vb[jj].w * w.w); }
;                 r[h] = da; r[8 + h] = db; }
; #pragma unroll
;             for (int o = 1; o < 64; o <<= 1) {
; #pragma unroll
;                 for (int q = 0; q < 18; ++q) r[q] += lane_get(r[q], lane ^ o); }
;             const float rsa = rsqrtf(r[16] * (1.f / D) + EPS), rsb = rsqrtf(r[17] * (1.f / D) + EPS);
;             if (lane < 16) { const int h = lane & 7; float dsel = r[0];
; #pragma unroll
;                 for (int q = 1; q < 16; ++q) dsel = (lane == q) ? r[q] : dsel;
;                 const float zz = dsel * (lane < 8 ? rsa : rsb) + bfg[h]; const float lf = fminf(zz, 0.f) - 0.6931471805599453f * __builtin_amdgcn_logf(1.0f + __builtin_amdgcn_exp2f(-LOG2E * fabsf(zz)));
;                 scr[(wave * 8 + j + (lane >> 3)) * 8 + h] = lf; } }
	v_fmac_f32_e32 v60, v10, v10
	v_fmac_f32_e32 v49, v10, v237
	v_fmac_f32_e32 v50, v10, v221
	v_fmac_f32_e32 v51, v10, v205
	v_fmac_f32_e32 v52, v10, v189
	v_fmac_f32_e32 v53, v10, v171
	v_fmac_f32_e32 v54, v10, v151
	v_fmac_f32_e32 v55, v10, v135
	v_fmac_f32_e32 v56, v10, v117
	v_fmac_f32_e32 v60, v11, v11
	v_fmac_f32_e32 v49, v11, v238
	v_fmac_f32_e32 v50, v11, v222
	v_fmac_f32_e32 v51, v11, v206
	v_fmac_f32_e32 v52, v11, v190
	v_fmac_f32_e32 v53, v11, v172
	v_fmac_f32_e32 v54, v11, v152
	v_fmac_f32_e32 v55, v11, v136
	v_fmac_f32_e32 v56, v11, v118
	v_fmac_f32_e32 v60, v12, v12
	v_fmac_f32_e32 v49, v12, v239
	v_fmac_f32_e32 v50, v12, v223
	v_fmac_f32_e32 v51, v12, v207
	v_fmac_f32_e32 v52, v12, v191
	v_fmac_f32_e32 v53, v12, v173
	v_fmac_f32_e32 v54, v12, v153
	v_fmac_f32_e32 v55, v12, v137
	v_fmac_f32_e32 v56, v12, v119
	s_nop 1
	v_permlane32_swap_b32_e32 v13, v41
	v_permlane32_swap_b32_e32 v14, v42
	v_permlane32_swap_b32_e32 v15, v43
	v_permlane32_swap_b32_e32 v16, v44
	v_permlane32_swap_b32_e32 v17, v45
	v_permlane32_swap_b32_e32 v18, v46
	v_permlane32_swap_b32_e32 v19, v47
	v_permlane32_swap_b32_e32 v20, v48
	v_permlane32_swap_b32_e32 v21, v49
	v_permlane32_swap_b32_e32 v22, v50
	v_permlane32_swap_b32_e32 v23, v51
	v_permlane32_swap_b32_e32 v24, v52
	v_permlane32_swap_b32_e32 v25, v53
	v_permlane32_swap_b32_e32 v26, v54
	v_permlane32_swap_b32_e32 v27, v55
	v_permlane32_swap_b32_e32 v40, v56
	v_permlane32_swap_b32_e32 v57, v59
	v_permlane32_swap_b32_e32 v58, v60
	s_nop 1
	v_add_f32_e32 v13, v13, v41
	v_add_f32_e32 v14, v14, v42
	v_add_f32_e32 v15, v15, v43
	v_add_f32_e32 v16, v16, v44
	v_add_f32_e32 v17, v17, v45
	v_add_f32_e32 v18, v18, v46
	v_add_f32_e32 v19, v19, v47
	v_add_f32_e32 v20, v20, v48
	v_add_f32_e32 v21, v21, v49
	v_add_f32_e32 v22, v22, v50
	v_add_f32_e32 v23, v23, v51
	v_add_f32_e32 v24, v24, v52
	v_add_f32_e32 v25, v25, v53
	v_add_f32_e32 v26, v26, v54
	v_add_f32_e32 v27, v27, v55
	v_add_f32_e32 v40, v40, v56
	v_add_f32_e32 v57, v57, v59
	v_add_f32_e32 v58, v58, v60
	s_nop 1
	v_permlane16_swap_b32_e32 v13, v21
	v_permlane16_swap_b32_e32 v14, v22
	v_permlane16_swap_b32_e32 v15, v23
	v_permlane16_swap_b32_e32 v16, v24
	v_permlane16_swap_b32_e32 v17, v25
	v_permlane16_swap_b32_e32 v18, v26
	v_permlane16_swap_b32_e32 v19, v27
	v_permlane16_swap_b32_e32 v20, v40
	v_permlane16_swap_b32_e32 v57, v58
	s_nop 1
	v_add_f32_e32 v13, v13, v21
	v_add_f32_e32 v14, v14, v22
	v_add_f32_e32 v15, v15, v23
	v_add_f32_e32 v16, v16, v24
	v_add_f32_e32 v17, v17, v25
	v_add_f32_e32 v18, v18, v26
	v_add_f32_e32 v19, v19, v27
	v_add_f32_e32 v20, v20, v40
	v_add_f32_e32 v57, v57, v58
	s_nop 1
	v_add_f32_dpp v13, v13, v13 quad_perm:[1,0,3,2] row_mask:0xf bank_mask:0xf
	v_add_f32_dpp v14, v14, v14 quad_perm:[1,0,3,2] row_mask:0xf bank_mask:0xf
	v_add_f32_dpp v15, v15, v15 quad_perm:[1,0,3,2] row_mask:0xf bank_mask:0xf
	v_add_f32_dpp v16, v16, v16 quad_perm:[1,0,3,2] row_mask:0xf bank_mask:0xf
	v_add_f32_dpp v17, v17, v17 quad_perm:[1,0,3,2] row_mask:0xf bank_mask:0xf
	v_add_f32_dpp v18, v18, v18 quad_perm:[1,0,3,2] row_mask:0xf bank_mask:0xf
	v_add_f32_dpp v19, v19, v19 quad_perm:[1,0,3,2] row_mask:0xf bank_mask:0xf
	v_add_f32_dpp v20, v20, v20 quad_perm:[1,0,3,2] row_mask:0xf bank_mask:0xf
	v_add_f32_dpp v57, v57, v57 quad_perm:[1,0,3,2] row_mask:0xf bank_mask:0xf
	s_nop 1
	v_add_f32_dpp v13, v13, v13 quad_perm:[2,3,0,1] row_mask:0xf bank_mask:0xf
	v_add_f32_dpp v14, v14, v14 quad_perm:[2,3,0,1] row_mask:0xf bank_mask:0xf
	v_add_f32_dpp v15, v15, v15 quad_perm:[2,3,0,1] row_mask:0xf bank_mask:0xf
	v_add_f32_dpp v16, v16, v16 quad_perm:[2,3,0,1] row_mask:0xf bank_mask:0xf
	v_add_f32_dpp v17, v17, v17 quad_perm:[2,3,0,1] row_mask:0xf bank_mask:0xf
	v_add_f32_dpp v18, v18, v18 quad_perm:[2,3,0,1] row_mask:0xf bank_mask:0xf
	v_add_f32_dpp v19, v19, v19 quad_perm:[2,3,0,1] row_mask:0xf bank_mask:0xf
	v_add_f32_dpp v20, v20, v20 quad_perm:[2,3,0,1] row_mask:0xf bank_mask:0xf
	v_add_f32_dpp v57, v57, v57 quad_perm:[2,3,0,1] row_mask:0xf bank_mask:0xf
	s_nop 1
	v_add_f32_dpp v13, v13, v13 row_half_mirror row_mask:0xf bank_mask:0xf
	v_add_f32_dpp v14, v14, v14 row_half_mirror row_mask:0xf bank_mask:0xf
	v_add_f32_dpp v15, v15, v15 row_half_mirror row_mask:0xf bank_mask:0xf
	v_add_f32_dpp v16, v16, v16 row_half_mirror row_mask:0xf bank_mask:0xf
	v_add_f32_dpp v17, v17, v17 row_half_mirror row_mask:0xf bank_mask:0xf
	v_add_f32_dpp v18, v18, v18 row_half_mirror row_mask:0xf bank_mask:0xf
	v_add_f32_dpp v19, v19, v19 row_half_mirror row_mask:0xf bank_mask:0xf
	v_add_f32_dpp v20, v20, v20 row_half_mirror row_mask:0xf bank_mask:0xf
	v_add_f32_dpp v57, v57, v57 row_half_mirror row_mask:0xf bank_mask:0xf
	s_nop 1
	v_add_f32_dpp v13, v13, v13 row_mirror row_mask:0xf bank_mask:0xf
	v_add_f32_dpp v14, v14, v14 row_mirror row_mask:0xf bank_mask:0xf
	v_add_f32_dpp v15, v15, v15 row_mirror row_mask:0xf bank_mask:0xf
	v_add_f32_dpp v16, v16, v16 row_mirror row_mask:0xf bank_mask:0xf
	v_add_f32_dpp v17, v17, v17 row_mirror row_mask:0xf bank_mask:0xf
	v_add_f32_dpp v18, v18, v18 row_mirror row_mask:0xf bank_mask:0xf
	v_add_f32_dpp v19, v19, v19 row_mirror row_mask:0xf bank_mask:0xf
	v_add_f32_dpp v20, v20, v20 row_mirror row_mask:0xf bank_mask:0xf
	v_add_f32_dpp v57, v57, v57 row_mirror row_mask:0xf bank_mask:0xf
	s_nop 1
	v_mov_b32_e32 v62, v13
	v_cndmask_b32_e64 v62, v62, v14, s[6:7]
	v_cndmask_b32_e64 v62, v62, v15, s[8:9]
	v_cndmask_b32_e64 v62, v62, v16, s[10:11]
	v_cndmask_b32_e64 v62, v62, v17, s[12:13]
	v_cndmask_b32_e64 v62, v62, v18, s[14:15]
	v_cndmask_b32_e64 v62, v62, v19, s[16:17]
	v_cndmask_b32_e64 v62, v62, v20, s[18:19]
	v_mul_f32_e32 v63, 0x3a800000, v57
	v_add_f32_e32 v63, 0x358637bd, v63
	v_rsq_f32_e32 v63, v63
	s_nop 0
	v_fma_f32 v62, v62, v63, v61
	v_mul_f32_e64 v63, |v62|, s65
	v_exp_f32_e32 v63, v63
	v_min_f32_e32 v62, 0, v62
	v_add_f32_e32 v63, 1.0, v63
	v_log_f32_e32 v63, v63
	s_nop 0
	v_fmac_f32_e32 v62, 0xbf317218, v63
	s_mov_b64 s[54:55], exec
	s_mov_b32 exec_lo, 0xff00ff
	s_mov_b32 exec_hi, 0xff00ff
	ds_write_b32 v65, v62
	s_mov_b64 exec, s[54:55]
	s_waitcnt vmcnt(0) lgkmcnt(0)
; __device__ __forceinline__ void fgate_phase(const bfr* x, const float* wf, const float* bfg, float* cl, float* ctot, LAS float* scr, int bx, int G, int tid, int lane, int wave) {
;     ...
;             for (int jj = 0; jj < 4; ++jj) { const u32x2 wa = xa[64 * jj], wb = xb2[64 * jj]; va[jj] = (f32x4){bf_lo(wa.x), bf_hi(wa.x), bf_lo(wa.y), bf_hi(wa.y)}; vb[jj] = (f32x4){bf_lo(wb.x), bf_hi(wb.x), bf_lo(wb.y), bf_hi(wb.y)}; }
;             r[16] = 0.f; r[17] = 0.f;
; #pragma unroll
;             for (int jj = 0; jj < 4; ++jj) { r[16] += (va[jj].x * va[jj].x + va[jj].y * va[jj].y) + (va[jj].z * va[jj].z + va[jj].w * va[jj].w); r[17] += (vb[jj].x * vb[jj].x + vb[jj].y * vb[jj].y) + (vb[jj].z * vb[jj].z + vb[jj].w * vb[jj].w); }
; #pragma unroll
;             for (int h = 0; h < NH; ++h) { const f32x4* wr = (const f32x4*)(wf + h * D) + lane + zo; float da = 0.f, db = 0.f;
; #pragma unroll
;                 for (int jj = 0; jj < 4; ++jj) { const f32x4 w = wr[64 * jj]; da += (va[jj].x * w.x + va[jj].y * w.y) + (va[jj].z * w.z + va[jj].w * w.w); db += (vb[jj].x * w.x + vb[jj].y * w.y) + (vb[jj].z * w.z + vb[jj].w * w.w); }
;                 r[h] = da; r[8 + h] = db; }
	v_lshlrev_b32_e32 v97, 16, v112
	v_and_b32_e32 v159, s40, v112
	v_lshlrev_b32_e32 v187, 16, v113
	v_and_b32_e32 v0, s40, v113
	v_lshlrev_b32_e32 v1, 16, v114
	v_and_b32_e32 v2, s40, v114
	v_lshlrev_b32_e32 v3, 16, v115
	v_and_b32_e32 v4, s40, v115
	v_lshlrev_b32_e32 v5, 16, v108
	v_and_b32_e32 v6, s40, v108
	v_lshlrev_b32_e32 v7, 16, v109
	v_and_b32_e32 v8, s40, v109
	v_lshlrev_b32_e32 v9, 16, v110
	v_and_b32_e32 v10, s40, v110
	v_lshlrev_b32_e32 v11, 16, v111
	v_and_b32_e32 v12, s40, v111
	v_mul_f32_e32 v57, v97, v97
	v_mul_f32_e32 v13, v97, v248
	v_mul_f32_e32 v14, v97, v232
	v_mul_f32_e32 v15, v97, v216
	v_mul_f32_e32 v16, v97, v200
	v_mul_f32_e32 v17, v97, v182
	v_mul_f32_e32 v18, v97, v166
	v_mul_f32_e32 v19, v97, v146
	v_mul_f32_e32 v20, v97, v130
	v_fmac_f32_e32 v57, v159, v159
	v_fmac_f32_e32 v13, v159, v249
	v_fmac_f32_e32 v14, v159, v233
	v_fmac_f32_e32 v15, v159, v217
	v_fmac_f32_e32 v16, v159, v201
	v_fmac_f32_e32 v17, v159, v183
	v_fmac_f32_e32 v18, v159, v167
	v_fmac_f32_e32 v19, v159, v147
	v_fmac_f32_e32 v20, v159, v131
	v_fmac_f32_e32 v57, v187, v187
	v_fmac_f32_e32 v13, v187, v250
	v_fmac_f32_e32 v14, v187, v234
	v_fmac_f32_e32 v15, v187, v218
	v_fmac_f32_e32 v16, v187, v202
	v_fmac_f32_e32 v17, v187, v184
	v_fmac_f32_e32 v18, v187, v168
	v_fmac_f32_e32 v19, v187, v148
	v_fmac_f32_e32 v20, v187, v132
	v_fmac_f32_e32 v57, v0, v0
	v_fmac_f32_e32 v13, v0, v251
	v_fmac_f32_e32 v14, v0, v235
	v_fmac_f32_e32 v15, v0, v219
	v_fmac_f32_e32 v16, v0, v203
	v_fmac_f32_e32 v17, v0, v185
	v_fmac_f32_e32 v18, v0, v169
	v_fmac_f32_e32 v19, v0, v149
	v_fmac_f32_e32 v20, v0, v133
	v_fmac_f32_e32 v57, v1, v1
	v_fmac_f32_e32 v13, v1, v244
	v_fmac_f32_e32 v14, v1, v228
	v_fmac_f32_e32 v15, v1, v212
	v_fmac_f32_e32 v16, v1, v196
	v_fmac_f32_e32 v17, v1, v178
	v_fmac_f32_e32 v18, v1, v162
	v_fmac_f32_e32 v19, v1, v142
	v_fmac_f32_e32 v20, v1, v124
	v_fmac_f32_e32 v57, v2, v2
	v_fmac_f32_e32 v13, v2, v245
	v_fmac_f32_e32 v14, v2, v229
	v_fmac_f32_e32 v15, v2, v213
	v_fmac_f32_e32 v16, v2, v197
	v_fmac_f32_e32 v17, v2, v179
	v_fmac_f32_e32 v18, v2, v163
	v_fmac_f32_e32 v19, v2, v143
	v_fmac_f32_e32 v20, v2, v125
	v_fmac_f32_e32 v57, v3, v3
	v_fmac_f32_e32 v13, v3, v246
	v_fmac_f32_e32 v14, v3, v230
	v_fmac_f32_e32 v15, v3, v214
	v_fmac_f32_e32 v16, v3, v198
	v_fmac_f32_e32 v17, v3, v180
	v_fmac_f32_e32 v18, v3, v164
	v_fmac_f32_e32 v19, v3, v144
	v_fmac_f32_e32 v20, v3, v126
	v_fmac_f32_e32 v57, v4, v4
	v_fmac_f32_e32 v13, v4, v247
	v_fmac_f32_e32 v14, v4, v231
	v_fmac_f32_e32 v15, v4, v215
	v_fmac_f32_e32 v16, v4, v199
	v_fmac_f32_e32 v17, v4, v181
	v_fmac_f32_e32 v18, v4, v165
	v_fmac_f32_e32 v19, v4, v145
	v_fmac_f32_e32 v20, v4, v127
	v_fmac_f32_e32 v57, v5, v5
	v_fmac_f32_e32 v13, v5, v240
	v_fmac_f32_e32 v14, v5, v224
	v_fmac_f32_e32 v15, v5, v208
	v_fmac_f32_e32 v16, v5, v192
	v_fmac_f32_e32 v17, v5, v174
	v_fmac_f32_e32 v18, v5, v154
	v_fmac_f32_e32 v19, v5, v138
	v_fmac_f32_e32 v20, v5, v120
	v_fmac_f32_e32 v57, v6, v6
	v_fmac_f32_e32 v13, v6, v241
	v_fmac_f32_e32 v14, v6, v225
	v_fmac_f32_e32 v15, v6, v209
	v_fmac_f32_e32 v16, v6, v193
	v_fmac_f32_e32 v17, v6, v175
	v_fmac_f32_e32 v18, v6, v155
	v_fmac_f32_e32 v19, v6, v139
	v_fmac_f32_e32 v20, v6, v121
	v_fmac_f32_e32 v57, v7, v7
	v_fmac_f32_e32 v13, v7, v242
	v_fmac_f32_e32 v14, v7, v226
	v_fmac_f32_e32 v15, v7, v210
	v_fmac_f32_e32 v16, v7, v194
	v_fmac_f32_e32 v17, v7, v176
	v_fmac_f32_e32 v18, v7, v156
	v_fmac_f32_e32 v19, v7, v140
	v_fmac_f32_e32 v20, v7, v122
	v_fmac_f32_e32 v57, v8, v8
	v_fmac_f32_e32 v13, v8, v243
	v_fmac_f32_e32 v14, v8, v227
	v_fmac_f32_e32 v15, v8, v211
	v_fmac_f32_e32 v16, v8, v195
	v_fmac_f32_e32 v17, v8, v177
	v_fmac_f32_e32 v18, v8, v157
	v_fmac_f32_e32 v19, v8, v141
	v_fmac_f32_e32 v20, v8, v123
	v_fmac_f32_e32 v57, v9, v9
	v_fmac_f32_e32 v13, v9, v236
	v_fmac_f32_e32 v14, v9, v220
	v_fmac_f32_e32 v15, v9, v204
	v_fmac_f32_e32 v16, v9, v188
	v_fmac_f32_e32 v17, v9, v170
	v_fmac_f32_e32 v18, v9, v150
	v_fmac_f32_e32 v19, v9, v134
	v_fmac_f32_e32 v20, v9, v116
	v_fmac_f32_e32 v57, v10, v10
	v_fmac_f32_e32 v13, v10, v237
	v_fmac_f32_e32 v14, v10, v221
	v_fmac_f32_e32 v15, v10, v205
	v_fmac_f32_e32 v16, v10, v189
	v_fmac_f32_e32 v17, v10, v171
	v_fmac_f32_e32 v18, v10, v151
	v_fmac_f32_e32 v19, v10, v135
	v_fmac_f32_e32 v20, v10, v117
	v_fmac_f32_e32 v57, v11, v11
	v_fmac_f32_e32 v13, v11, v238
	v_fmac_f32_e32 v14, v11, v222
	v_fmac_f32_e32 v15, v11, v206
	v_fmac_f32_e32 v16, v11, v190
	v_fmac_f32_e32 v17, v11, v172
	v_fmac_f32_e32 v18, v11, v152
	v_fmac_f32_e32 v19, v11, v136
	v_fmac_f32_e32 v20, v11, v118
	v_fmac_f32_e32 v57, v12, v12
	v_fmac_f32_e32 v13, v12, v239
	v_fmac_f32_e32 v14, v12, v223
	v_fmac_f32_e32 v15, v12, v207
	v_fmac_f32_e32 v16, v12, v191
	v_fmac_f32_e32 v17, v12, v173
	v_fmac_f32_e32 v18, v12, v153
	v_fmac_f32_e32 v19, v12, v137
	v_fmac_f32_e32 v20, v12, v119
	v_lshlrev_b32_e32 v97, 16, v104
	v_and_b32_e32 v159, s40, v104
	v_lshlrev_b32_e32 v187, 16, v105
	v_and_b32_e32 v0, s40, v105
	v_lshlrev_b32_e32 v1, 16, v106
	v_and_b32_e32 v2, s40, v106
	v_lshlrev_b32_e32 v3, 16, v107
	v_and_b32_e32 v4, s40, v107
	v_lshlrev_b32_e32 v5, 16, v100
	v_and_b32_e32 v6, s40, v100
	v_lshlrev_b32_e32 v7, 16, v101
	v_and_b32_e32 v8, s40, v101
	v_lshlrev_b32_e32 v9, 16, v102
	v_and_b32_e32 v10, s40, v102
	v_lshlrev_b32_e32 v11, 16, v103
	v_and_b32_e32 v12, s40, v103
	v_mul_f32_e32 v58, v97, v97
	v_mul_f32_e32 v21, v97, v248
	v_mul_f32_e32 v22, v97, v232
	v_mul_f32_e32 v23, v97, v216
	v_mul_f32_e32 v24, v97, v200
	v_mul_f32_e32 v25, v97, v182
	v_mul_f32_e32 v26, v97, v166
	v_mul_f32_e32 v27, v97, v146
	v_mul_f32_e32 v40, v97, v130
	v_fmac_f32_e32 v58, v159, v159
; __device__ __forceinline__ void fgate_phase(const bfr* x, const float* wf, const float* bfg, float* cl, float* ctot, LAS float* scr, int bx, int G, int tid, int lane, int wave) {
;     ...
;             for (int jj = 0; jj < 4; ++jj) { const u32x2 wa = xa[64 * jj], wb = xb2[64 * jj]; va[jj] = (f32x4){bf_lo(wa.x), bf_hi(wa.x), bf_lo(wa.y), bf_hi(wa.y)}; vb[jj] = (f32x4){bf_lo(wb.x), bf_hi(wb.x), bf_lo(wb.y), bf_hi(wb.y)}; }
;             r[16] = 0.f; r[17] = 0.f;
; #pragma unroll
;             for (int jj = 0; jj < 4; ++jj) { r[16] += (va[jj].x * va[jj].x + va[jj].y * va[jj].y) + (va[jj].z * va[jj].z + va[jj].w * va[jj].w); r[17] += (vb[jj].x * vb[jj].x + vb[jj].y * vb[jj].y) + (vb[jj].z * vb[jj].z + vb[jj].w * vb[jj].w); }
; #pragma unroll
;             for (int h = 0; h < NH; ++h) { const f32x4* wr = (const f32x4*)(wf + h * D) + lane + zo; float da = 0.f, db = 0.f;
; #pragma unroll
;                 for (int jj = 0; jj < 4; ++jj) { const f32x4 w = wr[64 * jj]; da += (va[jj].x * w.x + va[jj].y * w.y) + (va[jj].z * w.z + va[jj].w * w.w); db += (vb[jj].x * w.x + vb[jj].y * w.y) + (vb[jj].z * w.z + vb[jj].w * w.w); }
;                 r[h] = da; r[8 + h] = db; }
	v_fmac_f32_e32 v21, v159, v249
	v_fmac_f32_e32 v22, v159, v233
	v_fmac_f32_e32 v23, v159, v217
	v_fmac_f32_e32 v24, v159, v201
	v_fmac_f32_e32 v25, v159, v183
	v_fmac_f32_e32 v26, v159, v167
	v_fmac_f32_e32 v27, v159, v147
	v_fmac_f32_e32 v40, v159, v131
	v_fmac_f32_e32 v58, v187, v187
	v_fmac_f32_e32 v21, v187, v250
	v_fmac_f32_e32 v22, v187, v234
	v_fmac_f32_e32 v23, v187, v218
	v_fmac_f32_e32 v24, v187, v202
	v_fmac_f32_e32 v25, v187, v184
	v_fmac_f32_e32 v26, v187, v168
	v_fmac_f32_e32 v27, v187, v148
	v_fmac_f32_e32 v40, v187, v132
	v_fmac_f32_e32 v58, v0, v0
	v_fmac_f32_e32 v21, v0, v251
	v_fmac_f32_e32 v22, v0, v235
	v_fmac_f32_e32 v23, v0, v219
	v_fmac_f32_e32 v24, v0, v203
	v_fmac_f32_e32 v25, v0, v185
	v_fmac_f32_e32 v26, v0, v169
	v_fmac_f32_e32 v27, v0, v149
	v_fmac_f32_e32 v40, v0, v133
	v_fmac_f32_e32 v58, v1, v1
	v_fmac_f32_e32 v21, v1, v244
	v_fmac_f32_e32 v22, v1, v228
	v_fmac_f32_e32 v23, v1, v212
	v_fmac_f32_e32 v24, v1, v196
	v_fmac_f32_e32 v25, v1, v178
	v_fmac_f32_e32 v26, v1, v162
	v_fmac_f32_e32 v27, v1, v142
	v_fmac_f32_e32 v40, v1, v124
	v_fmac_f32_e32 v58, v2, v2
	v_fmac_f32_e32 v21, v2, v245
	v_fmac_f32_e32 v22, v2, v229
	v_fmac_f32_e32 v23, v2, v213
	v_fmac_f32_e32 v24, v2, v197
	v_fmac_f32_e32 v25, v2, v179
	v_fmac_f32_e32 v26, v2, v163
	v_fmac_f32_e32 v27, v2, v143
	v_fmac_f32_e32 v40, v2, v125
	v_fmac_f32_e32 v58, v3, v3
	v_fmac_f32_e32 v21, v3, v246
	v_fmac_f32_e32 v22, v3, v230
	v_fmac_f32_e32 v23, v3, v214
	v_fmac_f32_e32 v24, v3, v198
	v_fmac_f32_e32 v25, v3, v180
	v_fmac_f32_e32 v26, v3, v164
	v_fmac_f32_e32 v27, v3, v144
	v_fmac_f32_e32 v40, v3, v126
	v_fmac_f32_e32 v58, v4, v4
	v_fmac_f32_e32 v21, v4, v247
	v_fmac_f32_e32 v22, v4, v231
	v_fmac_f32_e32 v23, v4, v215
	v_fmac_f32_e32 v24, v4, v199
	v_fmac_f32_e32 v25, v4, v181
	v_fmac_f32_e32 v26, v4, v165
	v_fmac_f32_e32 v27, v4, v145
	v_fmac_f32_e32 v40, v4, v127
	v_fmac_f32_e32 v58, v5, v5
	v_fmac_f32_e32 v21, v5, v240
	v_fmac_f32_e32 v22, v5, v224
	v_fmac_f32_e32 v23, v5, v208
	v_fmac_f32_e32 v24, v5, v192
	v_fmac_f32_e32 v25, v5, v174
	v_fmac_f32_e32 v26, v5, v154
	v_fmac_f32_e32 v27, v5, v138
	v_fmac_f32_e32 v40, v5, v120
	v_fmac_f32_e32 v58, v6, v6
	v_fmac_f32_e32 v21, v6, v241
	v_fmac_f32_e32 v22, v6, v225
	v_fmac_f32_e32 v23, v6, v209
	v_fmac_f32_e32 v24, v6, v193
	v_fmac_f32_e32 v25, v6, v175
	v_fmac_f32_e32 v26, v6, v155
	v_fmac_f32_e32 v27, v6, v139
	v_fmac_f32_e32 v40, v6, v121
	v_fmac_f32_e32 v58, v7, v7
	v_fmac_f32_e32 v21, v7, v242
	v_fmac_f32_e32 v22, v7, v226
	v_fmac_f32_e32 v23, v7, v210
	v_fmac_f32_e32 v24, v7, v194
	v_fmac_f32_e32 v25, v7, v176
	v_fmac_f32_e32 v26, v7, v156
	v_fmac_f32_e32 v27, v7, v140
	v_fmac_f32_e32 v40, v7, v122
	v_fmac_f32_e32 v58, v8, v8
	v_fmac_f32_e32 v21, v8, v243
	v_fmac_f32_e32 v22, v8, v227
	v_fmac_f32_e32 v23, v8, v211
	v_fmac_f32_e32 v24, v8, v195
	v_fmac_f32_e32 v25, v8, v177
	v_fmac_f32_e32 v26, v8, v157
	v_fmac_f32_e32 v27, v8, v141
	v_fmac_f32_e32 v40, v8, v123
	v_fmac_f32_e32 v58, v9, v9
	v_fmac_f32_e32 v21, v9, v236
	v_fmac_f32_e32 v22, v9, v220
	v_fmac_f32_e32 v23, v9, v204
	v_fmac_f32_e32 v24, v9, v188
	v_fmac_f32_e32 v25, v9, v170
	v_fmac_f32_e32 v26, v9, v150
	v_fmac_f32_e32 v27, v9, v134
	v_fmac_f32_e32 v40, v9, v116
	v_fmac_f32_e32 v58, v10, v10
	v_fmac_f32_e32 v21, v10, v237
	v_fmac_f32_e32 v22, v10, v221
	v_fmac_f32_e32 v23, v10, v205
	v_fmac_f32_e32 v24, v10, v189
	v_fmac_f32_e32 v25, v10, v171
	v_fmac_f32_e32 v26, v10, v151
	v_fmac_f32_e32 v27, v10, v135
	v_fmac_f32_e32 v40, v10, v117
	v_fmac_f32_e32 v58, v11, v11
	v_fmac_f32_e32 v21, v11, v238
	v_fmac_f32_e32 v22, v11, v222
	v_fmac_f32_e32 v23, v11, v206
	v_fmac_f32_e32 v24, v11, v190
	v_fmac_f32_e32 v25, v11, v172
	v_fmac_f32_e32 v26, v11, v152
	v_fmac_f32_e32 v27, v11, v136
	v_fmac_f32_e32 v40, v11, v118
	v_fmac_f32_e32 v58, v12, v12
	v_fmac_f32_e32 v21, v12, v239
	v_fmac_f32_e32 v22, v12, v223
	v_fmac_f32_e32 v23, v12, v207
	v_fmac_f32_e32 v24, v12, v191
	v_fmac_f32_e32 v25, v12, v173
	v_fmac_f32_e32 v26, v12, v153
	v_fmac_f32_e32 v27, v12, v137
	v_fmac_f32_e32 v40, v12, v119
	v_lshlrev_b32_e32 v97, 16, v84
	v_and_b32_e32 v159, s40, v84
	v_lshlrev_b32_e32 v187, 16, v85
	v_and_b32_e32 v0, s40, v85
	v_lshlrev_b32_e32 v1, 16, v86
	v_and_b32_e32 v2, s40, v86
	v_lshlrev_b32_e32 v3, 16, v87
	v_and_b32_e32 v4, s40, v87
	v_lshlrev_b32_e32 v5, 16, v80
	v_and_b32_e32 v6, s40, v80
	v_lshlrev_b32_e32 v7, 16, v81
	v_and_b32_e32 v8, s40, v81
	v_lshlrev_b32_e32 v9, 16, v82
	v_and_b32_e32 v10, s40, v82
	v_lshlrev_b32_e32 v11, 16, v83
	v_and_b32_e32 v12, s40, v83
	v_mul_f32_e32 v59, v97, v97
	v_mul_f32_e32 v41, v97, v248
	v_mul_f32_e32 v42, v97, v232
	v_mul_f32_e32 v43, v97, v216
	v_mul_f32_e32 v44, v97, v200
	v_mul_f32_e32 v45, v97, v182
	v_mul_f32_e32 v46, v97, v166
	v_mul_f32_e32 v47, v97, v146
	v_mul_f32_e32 v48, v97, v130
	v_fmac_f32_e32 v59, v159, v159
	v_fmac_f32_e32 v41, v159, v249
	v_fmac_f32_e32 v42, v159, v233
	v_fmac_f32_e32 v43, v159, v217
	v_fmac_f32_e32 v44, v159, v201
	v_fmac_f32_e32 v45, v159, v183
	v_fmac_f32_e32 v46, v159, v167
	v_fmac_f32_e32 v47, v159, v147
	v_fmac_f32_e32 v48, v159, v131
	v_fmac_f32_e32 v59, v187, v187
	v_fmac_f32_e32 v41, v187, v250
	v_fmac_f32_e32 v42, v187, v234
	v_fmac_f32_e32 v43, v187, v218
	v_fmac_f32_e32 v44, v187, v202
	v_fmac_f32_e32 v45, v187, v184
	v_fmac_f32_e32 v46, v187, v168
	v_fmac_f32_e32 v47, v187, v148
	v_fmac_f32_e32 v48, v187, v132
	v_fmac_f32_e32 v59, v0, v0
	v_fmac_f32_e32 v41, v0, v251
	v_fmac_f32_e32 v42, v0, v235
	v_fmac_f32_e32 v43, v0, v219
	v_fmac_f32_e32 v44, v0, v203
	v_fmac_f32_e32 v45, v0, v185
	v_fmac_f32_e32 v46, v0, v169
	v_fmac_f32_e32 v47, v0, v149
	v_fmac_f32_e32 v48, v0, v133
; __device__ __forceinline__ void fgate_phase(const bfr* x, const float* wf, const float* bfg, float* cl, float* ctot, LAS float* scr, int bx, int G, int tid, int lane, int wave) {
;     ...
;             for (int jj = 0; jj < 4; ++jj) { const u32x2 wa = xa[64 * jj], wb = xb2[64 * jj]; va[jj] = (f32x4){bf_lo(wa.x), bf_hi(wa.x), bf_lo(wa.y), bf_hi(wa.y)}; vb[jj] = (f32x4){bf_lo(wb.x), bf_hi(wb.x), bf_lo(wb.y), bf_hi(wb.y)}; }
;             r[16] = 0.f; r[17] = 0.f;
; #pragma unroll
;             for (int jj = 0; jj < 4; ++jj) { r[16] += (va[jj].x * va[jj].x + va[jj].y * va[jj].y) + (va[jj].z * va[jj].z + va[jj].w * va[jj].w); r[17] += (vb[jj].x * vb[jj].x + vb[jj].y * vb[jj].y) + (vb[jj].z * vb[jj].z + vb[jj].w * vb[jj].w); }
; #pragma unroll
;             for (int h = 0; h < NH; ++h) { const f32x4* wr = (const f32x4*)(wf + h * D) + lane + zo; float da = 0.f, db = 0.f;
; #pragma unroll
;                 for (int jj = 0; jj < 4; ++jj) { const f32x4 w = wr[64 * jj]; da += (va[jj].x * w.x + va[jj].y * w.y) + (va[jj].z * w.z + va[jj].w * w.w); db += (vb[jj].x * w.x + vb[jj].y * w.y) + (vb[jj].z * w.z + vb[jj].w * w.w); }
;                 r[h] = da; r[8 + h] = db; }
	v_fmac_f32_e32 v59, v1, v1
	v_fmac_f32_e32 v41, v1, v244
	v_fmac_f32_e32 v42, v1, v228
	v_fmac_f32_e32 v43, v1, v212
	v_fmac_f32_e32 v44, v1, v196
	v_fmac_f32_e32 v45, v1, v178
	v_fmac_f32_e32 v46, v1, v162
	v_fmac_f32_e32 v47, v1, v142
	v_fmac_f32_e32 v48, v1, v124
	v_fmac_f32_e32 v59, v2, v2
	v_fmac_f32_e32 v41, v2, v245
	v_fmac_f32_e32 v42, v2, v229
	v_fmac_f32_e32 v43, v2, v213
	v_fmac_f32_e32 v44, v2, v197
	v_fmac_f32_e32 v45, v2, v179
	v_fmac_f32_e32 v46, v2, v163
	v_fmac_f32_e32 v47, v2, v143
	v_fmac_f32_e32 v48, v2, v125
	v_fmac_f32_e32 v59, v3, v3
	v_fmac_f32_e32 v41, v3, v246
	v_fmac_f32_e32 v42, v3, v230
	v_fmac_f32_e32 v43, v3, v214
	v_fmac_f32_e32 v44, v3, v198
	v_fmac_f32_e32 v45, v3, v180
	v_fmac_f32_e32 v46, v3, v164
	v_fmac_f32_e32 v47, v3, v144
	v_fmac_f32_e32 v48, v3, v126
	v_fmac_f32_e32 v59, v4, v4
	v_fmac_f32_e32 v41, v4, v247
	v_fmac_f32_e32 v42, v4, v231
	v_fmac_f32_e32 v43, v4, v215
	v_fmac_f32_e32 v44, v4, v199
	v_fmac_f32_e32 v45, v4, v181
	v_fmac_f32_e32 v46, v4, v165
	v_fmac_f32_e32 v47, v4, v145
	v_fmac_f32_e32 v48, v4, v127
	v_fmac_f32_e32 v59, v5, v5
	v_fmac_f32_e32 v41, v5, v240
	v_fmac_f32_e32 v42, v5, v224
	v_fmac_f32_e32 v43, v5, v208
	v_fmac_f32_e32 v44, v5, v192
	v_fmac_f32_e32 v45, v5, v174
	v_fmac_f32_e32 v46, v5, v154
	v_fmac_f32_e32 v47, v5, v138
	v_fmac_f32_e32 v48, v5, v120
	v_fmac_f32_e32 v59, v6, v6
	v_fmac_f32_e32 v41, v6, v241
	v_fmac_f32_e32 v42, v6, v225
	v_fmac_f32_e32 v43, v6, v209
	v_fmac_f32_e32 v44, v6, v193
	v_fmac_f32_e32 v45, v6, v175
	v_fmac_f32_e32 v46, v6, v155
	v_fmac_f32_e32 v47, v6, v139
	v_fmac_f32_e32 v48, v6, v121
	v_fmac_f32_e32 v59, v7, v7
	v_fmac_f32_e32 v41, v7, v242
	v_fmac_f32_e32 v42, v7, v226
	v_fmac_f32_e32 v43, v7, v210
	v_fmac_f32_e32 v44, v7, v194
	v_fmac_f32_e32 v45, v7, v176
	v_fmac_f32_e32 v46, v7, v156
	v_fmac_f32_e32 v47, v7, v140
	v_fmac_f32_e32 v48, v7, v122
	v_fmac_f32_e32 v59, v8, v8
	v_fmac_f32_e32 v41, v8, v243
	v_fmac_f32_e32 v42, v8, v227
	v_fmac_f32_e32 v43, v8, v211
	v_fmac_f32_e32 v44, v8, v195
	v_fmac_f32_e32 v45, v8, v177
	v_fmac_f32_e32 v46, v8, v157
	v_fmac_f32_e32 v47, v8, v141
	v_fmac_f32_e32 v48, v8, v123
	v_fmac_f32_e32 v59, v9, v9
	v_fmac_f32_e32 v41, v9, v236
	v_fmac_f32_e32 v42, v9, v220
	v_fmac_f32_e32 v43, v9, v204
	v_fmac_f32_e32 v44, v9, v188
	v_fmac_f32_e32 v45, v9, v170
	v_fmac_f32_e32 v46, v9, v150
	v_fmac_f32_e32 v47, v9, v134
	v_fmac_f32_e32 v48, v9, v116
	v_fmac_f32_e32 v59, v10, v10
	v_fmac_f32_e32 v41, v10, v237
	v_fmac_f32_e32 v42, v10, v221
	v_fmac_f32_e32 v43, v10, v205
	v_fmac_f32_e32 v44, v10, v189
	v_fmac_f32_e32 v45, v10, v171
	v_fmac_f32_e32 v46, v10, v151
	v_fmac_f32_e32 v47, v10, v135
	v_fmac_f32_e32 v48, v10, v117
	v_fmac_f32_e32 v59, v11, v11
	v_fmac_f32_e32 v41, v11, v238
	v_fmac_f32_e32 v42, v11, v222
	v_fmac_f32_e32 v43, v11, v206
	v_fmac_f32_e32 v44, v11, v190
	v_fmac_f32_e32 v45, v11, v172
	v_fmac_f32_e32 v46, v11, v152
	v_fmac_f32_e32 v47, v11, v136
	v_fmac_f32_e32 v48, v11, v118
	v_fmac_f32_e32 v59, v12, v12
	v_fmac_f32_e32 v41, v12, v239
	v_fmac_f32_e32 v42, v12, v223
	v_fmac_f32_e32 v43, v12, v207
	v_fmac_f32_e32 v44, v12, v191
	v_fmac_f32_e32 v45, v12, v173
	v_fmac_f32_e32 v46, v12, v153
	v_fmac_f32_e32 v47, v12, v137
	v_fmac_f32_e32 v48, v12, v119
	v_lshlrev_b32_e32 v97, 16, v76
	v_and_b32_e32 v159, s40, v76
	v_lshlrev_b32_e32 v187, 16, v77
	v_and_b32_e32 v0, s40, v77
	v_lshlrev_b32_e32 v1, 16, v78
	v_and_b32_e32 v2, s40, v78
	v_lshlrev_b32_e32 v3, 16, v79
	v_and_b32_e32 v4, s40, v79
	v_lshlrev_b32_e32 v5, 16, v72
	v_and_b32_e32 v6, s40, v72
	v_lshlrev_b32_e32 v7, 16, v73
	v_and_b32_e32 v8, s40, v73
	v_lshlrev_b32_e32 v9, 16, v74
	v_and_b32_e32 v10, s40, v74
	v_lshlrev_b32_e32 v11, 16, v75
	v_and_b32_e32 v12, s40, v75
	v_mul_f32_e32 v60, v97, v97
	v_mul_f32_e32 v49, v97, v248
	v_mul_f32_e32 v50, v97, v232
	v_mul_f32_e32 v51, v97, v216
	v_mul_f32_e32 v52, v97, v200
	v_mul_f32_e32 v53, v97, v182
	v_mul_f32_e32 v54, v97, v166
	v_mul_f32_e32 v55, v97, v146
	v_mul_f32_e32 v56, v97, v130
	v_fmac_f32_e32 v60, v159, v159
	v_fmac_f32_e32 v49, v159, v249
	v_fmac_f32_e32 v50, v159, v233
	v_fmac_f32_e32 v51, v159, v217
	v_fmac_f32_e32 v52, v159, v201
	v_fmac_f32_e32 v53, v159, v183
	v_fmac_f32_e32 v54, v159, v167
	v_fmac_f32_e32 v55, v159, v147
	v_fmac_f32_e32 v56, v159, v131
	v_fmac_f32_e32 v60, v187, v187
	v_fmac_f32_e32 v49, v187, v250
	v_fmac_f32_e32 v50, v187, v234
	v_fmac_f32_e32 v51, v187, v218
	v_fmac_f32_e32 v52, v187, v202
	v_fmac_f32_e32 v53, v187, v184
	v_fmac_f32_e32 v54, v187, v168
	v_fmac_f32_e32 v55, v187, v148
	v_fmac_f32_e32 v56, v187, v132
	v_fmac_f32_e32 v60, v0, v0
	v_fmac_f32_e32 v49, v0, v251
	v_fmac_f32_e32 v50, v0, v235
	v_fmac_f32_e32 v51, v0, v219
	v_fmac_f32_e32 v52, v0, v203
	v_fmac_f32_e32 v53, v0, v185
	v_fmac_f32_e32 v54, v0, v169
	v_fmac_f32_e32 v55, v0, v149
	v_fmac_f32_e32 v56, v0, v133
	v_fmac_f32_e32 v60, v1, v1
	v_fmac_f32_e32 v49, v1, v244
	v_fmac_f32_e32 v50, v1, v228
	v_fmac_f32_e32 v51, v1, v212
	v_fmac_f32_e32 v52, v1, v196
	v_fmac_f32_e32 v53, v1, v178
	v_fmac_f32_e32 v54, v1, v162
	v_fmac_f32_e32 v55, v1, v142
	v_fmac_f32_e32 v56, v1, v124
	v_fmac_f32_e32 v60, v2, v2
	v_fmac_f32_e32 v49, v2, v245
	v_fmac_f32_e32 v50, v2, v229
	v_fmac_f32_e32 v51, v2, v213
	v_fmac_f32_e32 v52, v2, v197
	v_fmac_f32_e32 v53, v2, v179
	v_fmac_f32_e32 v54, v2, v163
	v_fmac_f32_e32 v55, v2, v143
	v_fmac_f32_e32 v56, v2, v125
	v_fmac_f32_e32 v60, v3, v3
	v_fmac_f32_e32 v49, v3, v246
	v_fmac_f32_e32 v50, v3, v230
	v_fmac_f32_e32 v51, v3, v214
	v_fmac_f32_e32 v52, v3, v198
	v_fmac_f32_e32 v53, v3, v180
	v_fmac_f32_e32 v54, v3, v164
	v_fmac_f32_e32 v55, v3, v144
	v_fmac_f32_e32 v56, v3, v126
; __device__ __forceinline__ float lane_get(float v, int src_lane) { return __builtin_bit_cast(float, __builtin_amdgcn_ds_bpermute(src_lane << 2, __builtin_bit_cast(int, v))); }
; __device__ __forceinline__ void fgate_phase(const bfr* x, const float* wf, const float* bfg, float* cl, float* ctot, LAS float* scr, int bx, int G, int tid, int lane, int wave) {
;     ...
;                 for (int jj = 0; jj < 4; ++jj) { const f32x4 w = wr[64 * jj]; da += (va[jj].x * w.x + va[jj].y * w.y) + (va[jj].z * w.z + va[jj].w * w.w); db += (vb[jj].x * w.x + vb[jj].y * w.y) + (vb[jj].z * w.z + vb[jj].w * w.w); }
;                 r[h] = da; r[8 + h] = db; }
; #pragma unroll
;             for (int o = 1; o < 64; o <<= 1) {
; #pragma unroll
;                 for (int q = 0; q < 18; ++q) r[q] += lane_get(r[q], lane ^ o); }
	v_fmac_f32_e32 v60, v4, v4
	v_fmac_f32_e32 v49, v4, v247
	v_fmac_f32_e32 v50, v4, v231
	v_fmac_f32_e32 v51, v4, v215
	v_fmac_f32_e32 v52, v4, v199
	v_fmac_f32_e32 v53, v4, v181
	v_fmac_f32_e32 v54, v4, v165
	v_fmac_f32_e32 v55, v4, v145
	v_fmac_f32_e32 v56, v4, v127
	v_fmac_f32_e32 v60, v5, v5
	v_fmac_f32_e32 v49, v5, v240
	v_fmac_f32_e32 v50, v5, v224
	v_fmac_f32_e32 v51, v5, v208
	v_fmac_f32_e32 v52, v5, v192
	v_fmac_f32_e32 v53, v5, v174
	v_fmac_f32_e32 v54, v5, v154
	v_fmac_f32_e32 v55, v5, v138
	v_fmac_f32_e32 v56, v5, v120
	v_fmac_f32_e32 v60, v6, v6
	v_fmac_f32_e32 v49, v6, v241
	v_fmac_f32_e32 v50, v6, v225
	v_fmac_f32_e32 v51, v6, v209
	v_fmac_f32_e32 v52, v6, v193
	v_fmac_f32_e32 v53, v6, v175
	v_fmac_f32_e32 v54, v6, v155
	v_fmac_f32_e32 v55, v6, v139
	v_fmac_f32_e32 v56, v6, v121
	v_fmac_f32_e32 v60, v7, v7
	v_fmac_f32_e32 v49, v7, v242
	v_fmac_f32_e32 v50, v7, v226
	v_fmac_f32_e32 v51, v7, v210
	v_fmac_f32_e32 v52, v7, v194
	v_fmac_f32_e32 v53, v7, v176
	v_fmac_f32_e32 v54, v7, v156
	v_fmac_f32_e32 v55, v7, v140
	v_fmac_f32_e32 v56, v7, v122
	v_fmac_f32_e32 v60, v8, v8
	v_fmac_f32_e32 v49, v8, v243
	v_fmac_f32_e32 v50, v8, v227
	v_fmac_f32_e32 v51, v8, v211
	v_fmac_f32_e32 v52, v8, v195
	v_fmac_f32_e32 v53, v8, v177
	v_fmac_f32_e32 v54, v8, v157
	v_fmac_f32_e32 v55, v8, v141
	v_fmac_f32_e32 v56, v8, v123
	v_fmac_f32_e32 v60, v9, v9
	v_fmac_f32_e32 v49, v9, v236
	v_fmac_f32_e32 v50, v9, v220
	v_fmac_f32_e32 v51, v9, v204
	v_fmac_f32_e32 v52, v9, v188
	v_fmac_f32_e32 v53, v9, v170
	v_fmac_f32_e32 v54, v9, v150
	v_fmac_f32_e32 v55, v9, v134
	v_fmac_f32_e32 v56, v9, v116
	v_fmac_f32_e32 v60, v10, v10
	v_fmac_f32_e32 v49, v10, v237
	v_fmac_f32_e32 v50, v10, v221
	v_fmac_f32_e32 v51, v10, v205
	v_fmac_f32_e32 v52, v10, v189
	v_fmac_f32_e32 v53, v10, v171
	v_fmac_f32_e32 v54, v10, v151
	v_fmac_f32_e32 v55, v10, v135
	v_fmac_f32_e32 v56, v10, v117
	v_fmac_f32_e32 v60, v11, v11
	v_fmac_f32_e32 v49, v11, v238
	v_fmac_f32_e32 v50, v11, v222
	v_fmac_f32_e32 v51, v11, v206
	v_fmac_f32_e32 v52, v11, v190
	v_fmac_f32_e32 v53, v11, v172
	v_fmac_f32_e32 v54, v11, v152
	v_fmac_f32_e32 v55, v11, v136
	v_fmac_f32_e32 v56, v11, v118
	v_fmac_f32_e32 v60, v12, v12
	v_fmac_f32_e32 v49, v12, v239
	v_fmac_f32_e32 v50, v12, v223
	v_fmac_f32_e32 v51, v12, v207
	v_fmac_f32_e32 v52, v12, v191
	v_fmac_f32_e32 v53, v12, v173
	v_fmac_f32_e32 v54, v12, v153
	v_fmac_f32_e32 v55, v12, v137
	v_fmac_f32_e32 v56, v12, v119
	s_nop 1
	v_permlane32_swap_b32_e32 v13, v41
	v_permlane32_swap_b32_e32 v14, v42
	v_permlane32_swap_b32_e32 v15, v43
	v_permlane32_swap_b32_e32 v16, v44
	v_permlane32_swap_b32_e32 v17, v45
	v_permlane32_swap_b32_e32 v18, v46
	v_permlane32_swap_b32_e32 v19, v47
	v_permlane32_swap_b32_e32 v20, v48
	v_permlane32_swap_b32_e32 v21, v49
	v_permlane32_swap_b32_e32 v22, v50
	v_permlane32_swap_b32_e32 v23, v51
	v_permlane32_swap_b32_e32 v24, v52
	v_permlane32_swap_b32_e32 v25, v53
	v_permlane32_swap_b32_e32 v26, v54
	v_permlane32_swap_b32_e32 v27, v55
	v_permlane32_swap_b32_e32 v40, v56
	v_permlane32_swap_b32_e32 v57, v59
	v_permlane32_swap_b32_e32 v58, v60
	s_nop 1
	v_add_f32_e32 v13, v13, v41
	v_add_f32_e32 v14, v14, v42
	v_add_f32_e32 v15, v15, v43
	v_add_f32_e32 v16, v16, v44
	v_add_f32_e32 v17, v17, v45
	v_add_f32_e32 v18, v18, v46
	v_add_f32_e32 v19, v19, v47
	v_add_f32_e32 v20, v20, v48
	v_add_f32_e32 v21, v21, v49
	v_add_f32_e32 v22, v22, v50
	v_add_f32_e32 v23, v23, v51
	v_add_f32_e32 v24, v24, v52
	v_add_f32_e32 v25, v25, v53
	v_add_f32_e32 v26, v26, v54
	v_add_f32_e32 v27, v27, v55
	v_add_f32_e32 v40, v40, v56
	v_add_f32_e32 v57, v57, v59
	v_add_f32_e32 v58, v58, v60
	s_nop 1
	v_permlane16_swap_b32_e32 v13, v21
	v_permlane16_swap_b32_e32 v14, v22
	v_permlane16_swap_b32_e32 v15, v23
	v_permlane16_swap_b32_e32 v16, v24
	v_permlane16_swap_b32_e32 v17, v25
	v_permlane16_swap_b32_e32 v18, v26
; __device__ __forceinline__ float lane_get(float v, int src_lane) { return __builtin_bit_cast(float, __builtin_amdgcn_ds_bpermute(src_lane << 2, __builtin_bit_cast(int, v))); }
; __device__ __forceinline__ void fgate_phase(const bfr* x, const float* wf, const float* bfg, float* cl, float* ctot, LAS float* scr, int bx, int G, int tid, int lane, int wave) {
;     ...
;             for (int o = 1; o < 64; o <<= 1) {
; #pragma unroll
;                 for (int q = 0; q < 18; ++q) r[q] += lane_get(r[q], lane ^ o); }
;             const float rsa = rsqrtf(r[16] * (1.f / D) + EPS), rsb = rsqrtf(r[17] * (1.f / D) + EPS);
;             if (lane < 16) { const int h = lane & 7; float dsel = r[0];
; #pragma unroll
;                 for (int q = 1; q < 16; ++q) dsel = (lane == q) ? r[q] : dsel;
;                 const float zz = dsel * (lane < 8 ? rsa : rsb) + bfg[h]; const float lf = fminf(zz, 0.f) - 0.6931471805599453f * __builtin_amdgcn_logf(1.0f + __builtin_amdgcn_exp2f(-LOG2E * fabsf(zz)));
;                 scr[(wave * 8 + j + (lane >> 3)) * 8 + h] = lf; } }
	v_permlane16_swap_b32_e32 v19, v27
	v_permlane16_swap_b32_e32 v20, v40
	v_permlane16_swap_b32_e32 v57, v58
	s_nop 1
	v_add_f32_e32 v13, v13, v21
	v_add_f32_e32 v14, v14, v22
	v_add_f32_e32 v15, v15, v23
	v_add_f32_e32 v16, v16, v24
	v_add_f32_e32 v17, v17, v25
	v_add_f32_e32 v18, v18, v26
	v_add_f32_e32 v19, v19, v27
	v_add_f32_e32 v20, v20, v40
	v_add_f32_e32 v57, v57, v58
	s_nop 1
	v_add_f32_dpp v13, v13, v13 quad_perm:[1,0,3,2] row_mask:0xf bank_mask:0xf
	v_add_f32_dpp v14, v14, v14 quad_perm:[1,0,3,2] row_mask:0xf bank_mask:0xf
	v_add_f32_dpp v15, v15, v15 quad_perm:[1,0,3,2] row_mask:0xf bank_mask:0xf
	v_add_f32_dpp v16, v16, v16 quad_perm:[1,0,3,2] row_mask:0xf bank_mask:0xf
	v_add_f32_dpp v17, v17, v17 quad_perm:[1,0,3,2] row_mask:0xf bank_mask:0xf
	v_add_f32_dpp v18, v18, v18 quad_perm:[1,0,3,2] row_mask:0xf bank_mask:0xf
	v_add_f32_dpp v19, v19, v19 quad_perm:[1,0,3,2] row_mask:0xf bank_mask:0xf
	v_add_f32_dpp v20, v20, v20 quad_perm:[1,0,3,2] row_mask:0xf bank_mask:0xf
	v_add_f32_dpp v57, v57, v57 quad_perm:[1,0,3,2] row_mask:0xf bank_mask:0xf
	s_nop 1
	v_add_f32_dpp v13, v13, v13 quad_perm:[2,3,0,1] row_mask:0xf bank_mask:0xf
	v_add_f32_dpp v14, v14, v14 quad_perm:[2,3,0,1] row_mask:0xf bank_mask:0xf
	v_add_f32_dpp v15, v15, v15 quad_perm:[2,3,0,1] row_mask:0xf bank_mask:0xf
	v_add_f32_dpp v16, v16, v16 quad_perm:[2,3,0,1] row_mask:0xf bank_mask:0xf
	v_add_f32_dpp v17, v17, v17 quad_perm:[2,3,0,1] row_mask:0xf bank_mask:0xf
	v_add_f32_dpp v18, v18, v18 quad_perm:[2,3,0,1] row_mask:0xf bank_mask:0xf
	v_add_f32_dpp v19, v19, v19 quad_perm:[2,3,0,1] row_mask:0xf bank_mask:0xf
	v_add_f32_dpp v20, v20, v20 quad_perm:[2,3,0,1] row_mask:0xf bank_mask:0xf
	v_add_f32_dpp v57, v57, v57 quad_perm:[2,3,0,1] row_mask:0xf bank_mask:0xf
	s_nop 1
	v_add_f32_dpp v13, v13, v13 row_half_mirror row_mask:0xf bank_mask:0xf
	v_add_f32_dpp v14, v14, v14 row_half_mirror row_mask:0xf bank_mask:0xf
	v_add_f32_dpp v15, v15, v15 row_half_mirror row_mask:0xf bank_mask:0xf
	v_add_f32_dpp v16, v16, v16 row_half_mirror row_mask:0xf bank_mask:0xf
	v_add_f32_dpp v17, v17, v17 row_half_mirror row_mask:0xf bank_mask:0xf
	v_add_f32_dpp v18, v18, v18 row_half_mirror row_mask:0xf bank_mask:0xf
	v_add_f32_dpp v19, v19, v19 row_half_mirror row_mask:0xf bank_mask:0xf
	v_add_f32_dpp v20, v20, v20 row_half_mirror row_mask:0xf bank_mask:0xf
	v_add_f32_dpp v57, v57, v57 row_half_mirror row_mask:0xf bank_mask:0xf
	s_nop 1
	v_add_f32_dpp v13, v13, v13 row_mirror row_mask:0xf bank_mask:0xf
	v_add_f32_dpp v14, v14, v14 row_mirror row_mask:0xf bank_mask:0xf
	v_add_f32_dpp v15, v15, v15 row_mirror row_mask:0xf bank_mask:0xf
	v_add_f32_dpp v16, v16, v16 row_mirror row_mask:0xf bank_mask:0xf
	v_add_f32_dpp v17, v17, v17 row_mirror row_mask:0xf bank_mask:0xf
	v_add_f32_dpp v18, v18, v18 row_mirror row_mask:0xf bank_mask:0xf
	v_add_f32_dpp v19, v19, v19 row_mirror row_mask:0xf bank_mask:0xf
	v_add_f32_dpp v20, v20, v20 row_mirror row_mask:0xf bank_mask:0xf
	v_add_f32_dpp v57, v57, v57 row_mirror row_mask:0xf bank_mask:0xf
	s_nop 1
	v_mov_b32_e32 v62, v13
	v_cndmask_b32_e64 v62, v62, v14, s[6:7]
	v_cndmask_b32_e64 v62, v62, v15, s[8:9]
	v_cndmask_b32_e64 v62, v62, v16, s[10:11]
	v_cndmask_b32_e64 v62, v62, v17, s[12:13]
	v_cndmask_b32_e64 v62, v62, v18, s[14:15]
	v_cndmask_b32_e64 v62, v62, v19, s[16:17]
	v_cndmask_b32_e64 v62, v62, v20, s[18:19]
	v_mul_f32_e32 v63, 0x3a800000, v57
	v_add_f32_e32 v63, 0x358637bd, v63
	v_rsq_f32_e32 v63, v63
	s_nop 0
	v_fma_f32 v62, v62, v63, v61
	v_mul_f32_e64 v63, |v62|, s65
	v_exp_f32_e32 v63, v63
	v_min_f32_e32 v62, 0, v62
	v_add_f32_e32 v63, 1.0, v63
	v_log_f32_e32 v63, v63
	s_nop 0
	v_fmac_f32_e32 v62, 0xbf317218, v63
	s_mov_b64 s[54:55], exec
	s_mov_b32 exec_lo, 0xff00ff
	s_mov_b32 exec_hi, 0xff00ff
	ds_write_b32 v65, v62 offset:128
	s_mov_b64 exec, s[54:55]
